# v33 + non-temporal stores for the full-line cross-phase outputs of the norm, conv, gated-delta precompute and combine row loops (streamed out before the barrier flush)
# baseline (speedup 1.0000x reference)
.LBB0_161:
	s_or_b64 exec, exec, s[8:9]
	v_pk_mul_f32 v[68:69], v[58:59], v[58:59]
	v_pk_mul_f32 v[70:71], v[56:57], v[56:57]
	v_mov_b32_e32 v67, v181
	v_pk_mov_b32 v[76:77], v[70:71], v[68:69] op_sel:[1,0]
	v_mov_b32_e32 v71, v69
	v_pk_add_f32 v[68:69], v[76:77], v[70:71]
	v_pk_mul_f32 v[70:71], v[52:53], v[52:53]
	v_pk_add_f32 v[68:69], v[68:69], v[68:69] op_sel_hi:[0,1]
	v_pk_mul_f32 v[76:77], v[54:55], v[54:55]
	v_mul_f32_e32 v68, v48, v48
	v_pk_mov_b32 v[78:79], v[76:77], v[70:71] op_sel:[1,0]
	v_mov_b32_e32 v77, v71
	v_pk_add_f32 v[70:71], v[78:79], v[76:77]
	v_pk_fma_f32 v[76:77], v[48:49], v[48:49], v[68:69] op_sel_hi:[1,1,0]
	v_mul_f32_e32 v68, v50, v50
	v_pk_add_f32 v[70:71], v[70:71], v[70:71] op_sel_hi:[0,1]
	v_pk_fma_f32 v[78:79], v[50:51], v[50:51], v[68:69] op_sel_hi:[1,1,0]
	v_mul_f32_e32 v76, v44, v44
	v_mul_f32_e32 v78, v45, v45
	v_mul_f32_e32 v68, v46, v46
	v_mul_f32_e32 v70, v47, v47
	v_pk_add_f32 v[76:77], v[76:77], v[78:79]
	v_pk_add_f32 v[68:69], v[68:69], v[70:71]
	v_lshlrev_b32_e32 v180, 3, v60
	v_pk_add_f32 v[68:69], v[76:77], v[68:69]
	v_lshl_add_u64 v[70:71], s[22:23], 0, v[30:31]
	v_add_f32_e32 v43, v68, v69
	s_nop 1
	v_add_f32_dpp v43, v43, v43 row_shr:1 row_mask:0xf bank_mask:0xf bound_ctrl:1
	s_nop 1
	v_add_f32_dpp v43, v43, v43 row_shr:2 row_mask:0xf bank_mask:0xf bound_ctrl:1
	s_nop 1
	v_add_f32_dpp v43, v43, v43 row_shr:4 row_mask:0xf bank_mask:0xf bound_ctrl:1
	s_nop 1
	v_add_f32_dpp v43, v43, v43 row_shr:8 row_mask:0xf bank_mask:0xf bound_ctrl:1
	s_nop 1
	v_mov_b32_dpp v67, v43 row_bcast:15 row_mask:0xa bank_mask:0xf
	v_add_f32_e32 v43, v43, v67
	v_mov_b32_e32 v67, v181
	s_nop 1
	v_mov_b32_dpp v67, v43 row_bcast:31 row_mask:0xc bank_mask:0xf
	v_add_f32_e32 v43, v43, v67
	s_nop 0
	v_readlane_b32 s0, v43, 63
	s_nop 1
	v_fma_f32 v43, s0, v247, v237
	v_rsq_f32_e32 v68, v43
	s_nop 0
	v_pk_mul_f32 v[56:57], v[68:69], v[56:57] op_sel_hi:[0,1]
	v_pk_mul_f32 v[58:59], v[68:69], v[58:59] op_sel_hi:[0,1]
	s_waitcnt lgkmcnt(0)
	v_pk_fma_f32 v[6:7], v[6:7], v[58:59], v[10:11]
	v_pk_fma_f32 v[4:5], v[4:5], v[56:57], v[8:9]
	v_pk_mul_f32 v[76:77], v[54:55], v[68:69] op_sel_hi:[1,0]
	v_cvt_pk_bf16_f32 v4, v4, v5
	v_cvt_pk_bf16_f32 v5, v6, v7
	v_lshl_add_u64 v[6:7], v[70:71], 0, v[180:181]
	global_store_dwordx2 v[6:7], v[4:5], off nt
	v_lshl_add_u32 v4, v42, 4, v73
	ds_read_b128 v[4:7], v4 offset:40960
	ds_read_b128 v[8:11], v66 offset:46080
	v_pk_mul_f32 v[78:79], v[52:53], v[68:69] op_sel_hi:[1,0]
	v_lshl_add_u32 v42, v40, 4, v73
	ds_read_b128 v[52:55], v42 offset:40960
	s_waitcnt lgkmcnt(1)
	v_pk_fma_f32 v[6:7], v[6:7], v[78:79], v[10:11]
	v_pk_fma_f32 v[4:5], v[4:5], v[76:77], v[8:9]
	v_cvt_pk_bf16_f32 v9, v6, v7
	v_cvt_pk_bf16_f32 v8, v4, v5
	ds_read_b128 v[4:7], v66 offset:47104
	v_lshl_add_u32 v42, v62, 4, v73
	v_lshl_add_u64 v[10:11], v[64:65], 3, v[70:71]
	ds_read_b128 v[56:59], v42 offset:40960
	global_store_dwordx2 v[10:11], v[8:9], off nt
	ds_read_b128 v[8:11], v66 offset:48128
	v_pk_mul_f32 v[42:43], v[48:49], v[68:69] op_sel_hi:[1,0]
	v_pk_mul_f32 v[48:49], v[50:51], v[68:69] op_sel_hi:[1,0]
	s_waitcnt lgkmcnt(2)
	v_pk_fma_f32 v[4:5], v[52:53], v[42:43], v[4:5]
	v_pk_fma_f32 v[6:7], v[54:55], v[48:49], v[6:7]
	v_cvt_pk_bf16_f32 v4, v4, v5
	v_cvt_pk_bf16_f32 v5, v6, v7
	v_lshl_add_u64 v[6:7], v[40:41], 3, v[70:71]
	global_store_dwordx2 v[6:7], v[4:5], off nt
	v_pk_mul_f32 v[4:5], v[44:45], v[68:69] op_sel_hi:[1,0]
	v_pk_mul_f32 v[6:7], v[46:47], v[68:69] op_sel_hi:[1,0]
	s_waitcnt lgkmcnt(0)
	v_pk_fma_f32 v[4:5], v[4:5], v[56:57], v[8:9]
	v_pk_fma_f32 v[6:7], v[6:7], v[58:59], v[10:11]
	v_cvt_pk_bf16_f32 v4, v4, v5
	v_cvt_pk_bf16_f32 v5, v6, v7
	v_lshl_add_u64 v[6:7], v[62:63], 3, v[70:71]
	v_mov_b32_e32 v43, v61
	global_store_dwordx2 v[6:7], v[4:5], off nt

.LBB0_169:
	s_or_b64 exec, exec, s[6:7]
	s_waitcnt vmcnt(3)
	v_and_b32_e32 v57, 0xffff0000, v13
	v_and_b32_e32 v56, 0xffff0000, v12
	v_lshlrev_b32_e32 v55, 16, v13
	v_lshlrev_b32_e32 v54, 16, v12
	v_pk_mul_f32 v[70:71], v[56:57], v[56:57]
	s_waitcnt vmcnt(2)
	v_and_b32_e32 v61, 0xffff0000, v15
	v_and_b32_e32 v60, 0xffff0000, v14
	v_pk_fma_f32 v[70:71], v[54:55], v[54:55], v[70:71]
	v_lshlrev_b32_e32 v59, 16, v15
	v_lshlrev_b32_e32 v58, 16, v14
	s_waitcnt vmcnt(1)
	v_lshlrev_b32_e32 v62, 16, v16
	v_and_b32_e32 v63, 0xffff0000, v16
	v_lshlrev_b32_e32 v64, 16, v17
	s_waitcnt vmcnt(0)
	v_lshlrev_b32_e32 v66, 16, v18
	v_pk_add_f32 v[70:71], v[70:71], v[70:71] op_sel_hi:[0,1]
	v_pk_mul_f32 v[74:75], v[60:61], v[60:61]
	v_and_b32_e32 v65, 0xffff0000, v17
	v_pk_fma_f32 v[74:75], v[58:59], v[58:59], v[74:75]
	v_mul_f32_e32 v67, v62, v62
	v_mul_f32_e32 v77, v63, v63
	v_mul_f32_e32 v70, v64, v64
	v_mov_b32_e32 v76, v66
	v_and_b32_e32 v82, 0xffff0000, v18
	v_lshlrev_b32_e32 v68, 16, v19
	v_and_b32_e32 v69, 0xffff0000, v19
	v_pk_add_f32 v[74:75], v[74:75], v[74:75] op_sel_hi:[0,1]
	v_pk_fma_f32 v[78:79], v[64:65], v[64:65], v[70:71] op_sel_hi:[1,1,0]
	v_pk_add_f32 v[76:77], v[66:67], v[76:77]
	v_mul_f32_e32 v78, v82, v82
	v_mul_f32_e32 v74, v68, v68
	v_mul_f32_e32 v70, v69, v69
	v_mul_f32_e32 v80, v66, v66
	v_mov_b32_e32 v81, v77
	v_pk_add_f32 v[76:77], v[80:81], v[78:79]
	v_pk_add_f32 v[70:71], v[74:75], v[70:71]
	v_mov_b32_e32 v49, v181
	v_pk_add_f32 v[70:71], v[76:77], v[70:71]
	v_mov_b32_e32 v74, v54
	v_add_f32_e32 v45, v70, v71
	v_mov_b32_e32 v75, v56
	v_mov_b32_e32 v56, v55
	v_add_f32_dpp v45, v45, v45 row_shr:1 row_mask:0xf bank_mask:0xf bound_ctrl:1
	v_lshlrev_b32_e32 v180, 3, v44
	v_mov_b32_e32 v67, v82
	v_add_f32_dpp v45, v45, v45 row_shr:2 row_mask:0xf bank_mask:0xf bound_ctrl:1
	s_nop 1
	v_add_f32_dpp v45, v45, v45 row_shr:4 row_mask:0xf bank_mask:0xf bound_ctrl:1
	s_nop 1
	v_add_f32_dpp v45, v45, v45 row_shr:8 row_mask:0xf bank_mask:0xf bound_ctrl:1
	s_nop 1
	v_mov_b32_dpp v49, v45 row_bcast:15 row_mask:0xa bank_mask:0xf
	v_add_f32_e32 v45, v45, v49
	v_mov_b32_e32 v49, v181
	s_nop 1
	v_mov_b32_dpp v49, v45 row_bcast:31 row_mask:0xc bank_mask:0xf
	v_add_f32_e32 v45, v45, v49
	s_nop 0
	v_readlane_b32 s0, v45, 63
	s_nop 1
	v_fma_f32 v45, s0, v247, v237
	v_rsq_f32_e32 v70, v45
	v_lshl_add_u64 v[44:45], s[22:23], 0, v[28:29]
	v_pk_mul_f32 v[74:75], v[70:71], v[74:75] op_sel_hi:[0,1]
	v_pk_mul_f32 v[54:55], v[70:71], v[56:57] op_sel_hi:[0,1]
	s_waitcnt lgkmcnt(0)
	v_pk_fma_f32 v[6:7], v[6:7], v[54:55], v[10:11]
	v_pk_fma_f32 v[4:5], v[4:5], v[74:75], v[8:9]
	s_nop 0
	v_cvt_pk_bf16_f32 v4, v4, v5
	v_cvt_pk_bf16_f32 v5, v6, v7
	v_lshl_add_u64 v[6:7], v[44:45], 0, v[180:181]
	global_store_dwordx2 v[6:7], v[4:5], off nt
	v_mov_b32_e32 v4, v58
	v_mov_b32_e32 v5, v60
	v_pk_mul_f32 v[74:75], v[70:71], v[4:5] op_sel_hi:[0,1]
	v_lshl_add_u32 v4, v48, 4, v73
	ds_read_b128 v[4:7], v4 offset:40960
	ds_read_b128 v[8:11], v41 offset:46080
	v_mov_b32_e32 v60, v59
	v_pk_mul_f32 v[76:77], v[70:71], v[60:61] op_sel_hi:[0,1]
	v_lshl_add_u32 v48, v46, 4, v73
	ds_read_b128 v[54:57], v48 offset:40960
	s_waitcnt lgkmcnt(1)
	v_pk_fma_f32 v[6:7], v[6:7], v[76:77], v[10:11]
	v_pk_fma_f32 v[4:5], v[4:5], v[74:75], v[8:9]
	v_cvt_pk_bf16_f32 v9, v6, v7
	v_cvt_pk_bf16_f32 v8, v4, v5
	ds_read_b128 v[4:7], v41 offset:47104
	v_lshl_add_u32 v48, v50, 4, v73
	v_lshl_add_u64 v[10:11], v[52:53], 3, v[44:45]
	ds_read_b128 v[58:61], v48 offset:40960
	global_store_dwordx2 v[10:11], v[8:9], off nt
	ds_read_b128 v[8:11], v41 offset:48128
	v_pk_mul_f32 v[48:49], v[70:71], v[62:63] op_sel_hi:[0,1]
	v_pk_mul_f32 v[52:53], v[70:71], v[64:65] op_sel_hi:[0,1]
	s_waitcnt lgkmcnt(2)
	v_pk_fma_f32 v[6:7], v[56:57], v[52:53], v[6:7]
	v_pk_fma_f32 v[4:5], v[54:55], v[48:49], v[4:5]
	v_add_u32_e32 v74, 3, v40
	v_cvt_pk_bf16_f32 v4, v4, v5
	v_cvt_pk_bf16_f32 v5, v6, v7
	v_lshl_add_u64 v[6:7], v[46:47], 3, v[44:45]
	global_store_dwordx2 v[6:7], v[4:5], off nt
	v_pk_mul_f32 v[4:5], v[70:71], v[66:67] op_sel_hi:[0,1]
	v_pk_mul_f32 v[6:7], v[70:71], v[68:69] op_sel_hi:[0,1]
	s_waitcnt lgkmcnt(0)
	v_pk_fma_f32 v[6:7], v[6:7], v[60:61], v[10:11]
	v_pk_fma_f32 v[4:5], v[4:5], v[58:59], v[8:9]
	v_cmp_lt_i32_e64 s[8:9], v74, v72
	v_cvt_pk_bf16_f32 v4, v4, v5
	v_cvt_pk_bf16_f32 v5, v6, v7
	v_lshl_add_u64 v[6:7], v[50:51], 3, v[44:45]
	v_cmp_ge_i32_e64 s[6:7], v74, v72
	global_store_dwordx2 v[6:7], v[4:5], off nt
	s_and_saveexec_b64 s[4:5], s[8:9]
	s_cbranch_execz .LBB0_171
	v_mov_b32_e32 v4, v186
	s_nop 0
	v_and_b32_e32 v6, 63, v4
	v_add_u32_e32 v4, 0xfffff803, v40
	v_ashrrev_i32_e32 v5, 31, v4
	v_lshlrev_b64 v[4:5], 12, v[4:5]
	v_lshl_add_u64 v[4:5], s[10:11], 0, v[4:5]
	v_lshlrev_b32_e32 v180, 3, v6
	v_lshl_add_u64 v[4:5], v[4:5], 0, v[180:181]
	global_load_dwordx2 v[12:13], v[4:5], off
	global_load_dwordx2 v[14:15], v[4:5], off offset:512
	global_load_dwordx2 v[16:17], v[4:5], off offset:1024
	global_load_dwordx2 v[18:19], v[4:5], off offset:1536

.LBB0_176:
	s_or_b64 exec, exec, s[8:9]
	v_pk_mul_f32 v[76:77], v[60:61], v[60:61]
	v_pk_mul_f32 v[78:79], v[58:59], v[58:59]
	v_mov_b32_e32 v57, v181
	v_pk_mov_b32 v[80:81], v[78:79], v[76:77] op_sel:[1,0]
	v_mov_b32_e32 v79, v77
	v_pk_add_f32 v[76:77], v[80:81], v[78:79]
	v_pk_mul_f32 v[78:79], v[52:53], v[52:53]
	v_pk_add_f32 v[76:77], v[76:77], v[76:77] op_sel_hi:[0,1]
	v_pk_mul_f32 v[80:81], v[54:55], v[54:55]
	v_mul_f32_e32 v76, v48, v48
	v_pk_mov_b32 v[82:83], v[80:81], v[78:79] op_sel:[1,0]
	v_mov_b32_e32 v81, v79
	v_pk_add_f32 v[78:79], v[82:83], v[80:81]
	v_pk_fma_f32 v[80:81], v[48:49], v[48:49], v[76:77] op_sel_hi:[1,1,0]
	v_mul_f32_e32 v76, v50, v50
	v_pk_add_f32 v[78:79], v[78:79], v[78:79] op_sel_hi:[0,1]
	v_pk_fma_f32 v[82:83], v[50:51], v[50:51], v[76:77] op_sel_hi:[1,1,0]
	v_mul_f32_e32 v80, v44, v44
	v_mul_f32_e32 v82, v45, v45
	v_mul_f32_e32 v76, v46, v46
	v_mul_f32_e32 v78, v47, v47
	v_pk_add_f32 v[80:81], v[80:81], v[82:83]
	v_pk_add_f32 v[76:77], v[76:77], v[78:79]
	v_lshlrev_b32_e32 v180, 3, v62
	v_pk_add_f32 v[76:77], v[80:81], v[76:77]
	s_nop 0
	v_add_f32_e32 v43, v76, v77
	s_nop 1
	v_add_f32_dpp v43, v43, v43 row_shr:1 row_mask:0xf bank_mask:0xf bound_ctrl:1
	s_nop 1
	v_add_f32_dpp v43, v43, v43 row_shr:2 row_mask:0xf bank_mask:0xf bound_ctrl:1
	s_nop 1
	v_add_f32_dpp v43, v43, v43 row_shr:4 row_mask:0xf bank_mask:0xf bound_ctrl:1
	s_nop 1
	v_add_f32_dpp v43, v43, v43 row_shr:8 row_mask:0xf bank_mask:0xf bound_ctrl:1
	s_nop 1
	v_mov_b32_dpp v57, v43 row_bcast:15 row_mask:0xa bank_mask:0xf
	v_add_f32_e32 v43, v43, v57
	v_mov_b32_e32 v57, v181
	s_nop 1
	v_mov_b32_dpp v57, v43 row_bcast:31 row_mask:0xc bank_mask:0xf
	v_add_f32_e32 v43, v43, v57
	v_ashrrev_i32_e32 v57, 31, v56
	v_readlane_b32 s0, v43, 63
	v_lshlrev_b64 v[56:57], 11, v[56:57]
	s_nop 0
	v_fma_f32 v43, s0, v247, v237
	v_rsq_f32_e32 v76, v43
	v_lshl_add_u32 v43, v64, 4, v73
	v_pk_mul_f32 v[58:59], v[76:77], v[58:59] op_sel_hi:[0,1]
	v_pk_mul_f32 v[60:61], v[76:77], v[60:61] op_sel_hi:[0,1]
	s_waitcnt lgkmcnt(0)
	v_pk_fma_f32 v[6:7], v[6:7], v[60:61], v[10:11]
	v_pk_fma_f32 v[4:5], v[4:5], v[58:59], v[8:9]
	v_lshl_add_u64 v[60:61], s[18:19], 0, v[56:57]
	v_cvt_pk_bf16_f32 v4, v4, v5
	v_cvt_pk_bf16_f32 v5, v6, v7
	v_lshl_add_u64 v[6:7], v[60:61], 0, v[180:181]
	global_store_dwordx2 v[6:7], v[4:5], off nt
	v_lshl_add_u32 v4, v66, 4, v73
	ds_read_b128 v[4:7], v4 offset:40960
	ds_read_b128 v[8:11], v63 offset:46080
	v_pk_mul_f32 v[78:79], v[54:55], v[76:77] op_sel_hi:[1,0]
	v_pk_mul_f32 v[80:81], v[52:53], v[76:77] op_sel_hi:[1,0]
	ds_read_b128 v[52:55], v43 offset:40960
	v_pk_mul_f32 v[48:49], v[48:49], v[76:77] op_sel_hi:[1,0]
	s_waitcnt lgkmcnt(1)
	v_pk_fma_f32 v[6:7], v[6:7], v[80:81], v[10:11]
	v_pk_fma_f32 v[4:5], v[4:5], v[78:79], v[8:9]
	v_cvt_pk_bf16_f32 v9, v6, v7
	v_cvt_pk_bf16_f32 v8, v4, v5
	ds_read_b128 v[4:7], v63 offset:47104
	v_lshl_add_u32 v43, v68, 4, v73
	v_lshl_add_u64 v[10:11], v[70:71], 3, v[60:61]
	ds_read_b128 v[56:59], v43 offset:40960
	global_store_dwordx2 v[10:11], v[8:9], off nt
	ds_read_b128 v[8:11], v63 offset:48128
	v_pk_mul_f32 v[50:51], v[50:51], v[76:77] op_sel_hi:[1,0]
	s_waitcnt lgkmcnt(2)
	v_pk_fma_f32 v[4:5], v[52:53], v[48:49], v[4:5]
	v_pk_fma_f32 v[6:7], v[54:55], v[50:51], v[6:7]
	v_cvt_pk_bf16_f32 v4, v4, v5
	v_cvt_pk_bf16_f32 v5, v6, v7
	v_lshl_add_u64 v[6:7], v[64:65], 3, v[60:61]
	global_store_dwordx2 v[6:7], v[4:5], off nt
	v_pk_mul_f32 v[4:5], v[44:45], v[76:77] op_sel_hi:[1,0]
	v_pk_mul_f32 v[6:7], v[46:47], v[76:77] op_sel_hi:[1,0]
	s_waitcnt lgkmcnt(0)
	v_pk_fma_f32 v[4:5], v[4:5], v[56:57], v[8:9]
	v_pk_fma_f32 v[6:7], v[6:7], v[58:59], v[10:11]
	v_cvt_pk_bf16_f32 v4, v4, v5
	v_cvt_pk_bf16_f32 v5, v6, v7
	v_lshl_add_u64 v[6:7], v[68:69], 3, v[60:61]
	v_mov_b32_e32 v43, v41
	global_store_dwordx2 v[6:7], v[4:5], off nt

.LBB0_196:
	s_or_b64 exec, exec, s[16:17]
	v_pk_mul_f32 v[62:63], v[52:53], v[52:53]
	v_pk_mul_f32 v[64:65], v[50:51], v[50:51]
	v_lshlrev_b32_e32 v180, 3, v54
	v_pk_mov_b32 v[68:69], v[64:65], v[62:63] op_sel:[1,0]
	v_mov_b32_e32 v65, v63
	v_pk_add_f32 v[62:63], v[68:69], v[64:65]
	v_pk_mul_f32 v[64:65], v[46:47], v[46:47]
	v_pk_add_f32 v[62:63], v[62:63], v[62:63] op_sel_hi:[0,1]
	v_pk_mul_f32 v[68:69], v[48:49], v[48:49]
	v_mul_f32_e32 v62, v42, v42
	v_pk_mov_b32 v[70:71], v[68:69], v[64:65] op_sel:[1,0]
	v_mov_b32_e32 v69, v65
	v_pk_add_f32 v[64:65], v[70:71], v[68:69]
	v_pk_fma_f32 v[68:69], v[42:43], v[42:43], v[62:63] op_sel_hi:[1,1,0]
	v_mul_f32_e32 v62, v44, v44
	v_pk_add_f32 v[64:65], v[64:65], v[64:65] op_sel_hi:[0,1]
	v_pk_fma_f32 v[70:71], v[44:45], v[44:45], v[62:63] op_sel_hi:[1,1,0]
	v_mul_f32_e32 v68, v38, v38
	v_mul_f32_e32 v70, v39, v39
	v_mul_f32_e32 v62, v40, v40
	v_mul_f32_e32 v64, v41, v41
	v_pk_add_f32 v[68:69], v[68:69], v[70:71]
	v_pk_add_f32 v[62:63], v[62:63], v[64:65]
	v_lshl_add_u64 v[64:65], s[84:85], 0, v[96:97]
	v_pk_add_f32 v[62:63], v[68:69], v[62:63]
	v_mov_b32_e32 v67, v55
	v_add_f32_e32 v62, v62, v63
	v_mov_b32_e32 v63, v181
	s_nop 0
	v_add_f32_dpp v62, v62, v62 row_shr:1 row_mask:0xf bank_mask:0xf bound_ctrl:1
	s_nop 1
	v_add_f32_dpp v62, v62, v62 row_shr:2 row_mask:0xf bank_mask:0xf bound_ctrl:1
	s_nop 1
	v_add_f32_dpp v62, v62, v62 row_shr:4 row_mask:0xf bank_mask:0xf bound_ctrl:1
	s_nop 1
	v_add_f32_dpp v62, v62, v62 row_shr:8 row_mask:0xf bank_mask:0xf bound_ctrl:1
	s_nop 1
	v_mov_b32_dpp v63, v62 row_bcast:15 row_mask:0xa bank_mask:0xf
	v_add_f32_e32 v62, v62, v63
	v_mov_b32_e32 v63, v181
	s_nop 1
	v_mov_b32_dpp v63, v62 row_bcast:31 row_mask:0xc bank_mask:0xf
	v_add_f32_e32 v62, v62, v63
	s_nop 0
	v_readlane_b32 s0, v62, 63
	s_nop 1
	v_fma_f32 v62, s0, v247, v237
	v_rsq_f32_e32 v62, v62
	s_nop 0
	v_pk_mul_f32 v[50:51], v[62:63], v[50:51] op_sel_hi:[0,1]
	v_pk_mul_f32 v[52:53], v[62:63], v[52:53] op_sel_hi:[0,1]
	s_waitcnt lgkmcnt(0)
	v_pk_fma_f32 v[6:7], v[6:7], v[52:53], v[10:11]
	v_pk_fma_f32 v[4:5], v[4:5], v[50:51], v[8:9]
	v_pk_mul_f32 v[68:69], v[48:49], v[62:63] op_sel_hi:[1,0]
	v_cvt_pk_bf16_f32 v4, v4, v5
	v_cvt_pk_bf16_f32 v5, v6, v7
	v_lshl_add_u64 v[6:7], v[64:65], 0, v[180:181]
	global_store_dwordx2 v[6:7], v[4:5], off nt
	v_lshl_add_u32 v4, v56, 4, v114
	ds_read_b128 v[4:7], v4 offset:40960
	ds_read_b128 v[8:11], v57 offset:46080
	v_pk_mul_f32 v[70:71], v[46:47], v[62:63] op_sel_hi:[1,0]
	v_lshl_add_u32 v46, v36, 4, v114
	ds_read_b128 v[46:49], v46 offset:40960
	v_lshl_add_u32 v50, v58, 4, v114
	s_waitcnt lgkmcnt(1)
	v_pk_fma_f32 v[6:7], v[6:7], v[70:71], v[10:11]
	v_pk_fma_f32 v[4:5], v[4:5], v[68:69], v[8:9]
	v_cvt_pk_bf16_f32 v9, v6, v7
	v_cvt_pk_bf16_f32 v8, v4, v5
	ds_read_b128 v[4:7], v57 offset:47104
	v_lshl_add_u64 v[10:11], v[60:61], 3, v[64:65]
	ds_read_b128 v[50:53], v50 offset:40960
	global_store_dwordx2 v[10:11], v[8:9], off nt
	ds_read_b128 v[8:11], v57 offset:48128
	v_pk_mul_f32 v[42:43], v[42:43], v[62:63] op_sel_hi:[1,0]
	v_pk_mul_f32 v[44:45], v[44:45], v[62:63] op_sel_hi:[1,0]
	s_waitcnt lgkmcnt(2)
	v_pk_fma_f32 v[4:5], v[46:47], v[42:43], v[4:5]
	v_pk_fma_f32 v[6:7], v[48:49], v[44:45], v[6:7]
	v_cvt_pk_bf16_f32 v4, v4, v5
	v_cvt_pk_bf16_f32 v5, v6, v7
	v_lshl_add_u64 v[6:7], v[36:37], 3, v[64:65]
	global_store_dwordx2 v[6:7], v[4:5], off nt
	v_pk_mul_f32 v[4:5], v[38:39], v[62:63] op_sel_hi:[1,0]
	v_pk_mul_f32 v[6:7], v[40:41], v[62:63] op_sel_hi:[1,0]
	s_waitcnt lgkmcnt(0)
	v_pk_fma_f32 v[4:5], v[4:5], v[50:51], v[8:9]
	v_pk_fma_f32 v[6:7], v[6:7], v[52:53], v[10:11]
	v_cvt_pk_bf16_f32 v4, v4, v5
	v_cvt_pk_bf16_f32 v5, v6, v7
	v_lshl_add_u64 v[6:7], v[58:59], 3, v[64:65]
	global_store_dwordx2 v[6:7], v[4:5], off nt

.LBB0_204:
	s_or_b64 exec, exec, s[14:15]
	s_waitcnt vmcnt(1)
	v_and_b32_e32 v51, 0xffff0000, v13
	v_and_b32_e32 v50, 0xffff0000, v12
	s_waitcnt vmcnt(2)
	v_and_b32_e32 v55, 0xffff0000, v15
	v_and_b32_e32 v54, 0xffff0000, v14
	v_lshlrev_b32_e32 v49, 16, v13
	v_lshlrev_b32_e32 v48, 16, v12
	v_lshlrev_b32_e32 v53, 16, v15
	v_lshlrev_b32_e32 v52, 16, v14
	s_waitcnt vmcnt(0)
	v_lshlrev_b32_e32 v58, 16, v16
	v_and_b32_e32 v59, 0xffff0000, v16
	v_lshlrev_b32_e32 v60, 16, v17
	s_waitcnt vmcnt(0)
	v_lshlrev_b32_e32 v62, 16, v18
	v_pk_mul_f32 v[68:69], v[50:51], v[50:51]
	v_pk_mul_f32 v[70:71], v[54:55], v[54:55]
	v_and_b32_e32 v61, 0xffff0000, v17
	v_pk_fma_f32 v[68:69], v[48:49], v[48:49], v[68:69]
	v_pk_fma_f32 v[70:71], v[52:53], v[52:53], v[70:71]
	v_mul_f32_e32 v63, v58, v58
	v_mul_f32_e32 v73, v59, v59
	v_mul_f32_e32 v56, v60, v60
	v_mov_b32_e32 v72, v62
	v_and_b32_e32 v66, 0xffff0000, v18
	v_lshlrev_b32_e32 v64, 16, v19
	v_and_b32_e32 v65, 0xffff0000, v19
	v_pk_add_f32 v[68:69], v[68:69], v[68:69] op_sel_hi:[0,1]
	v_pk_add_f32 v[70:71], v[70:71], v[70:71] op_sel_hi:[0,1]
	v_pk_fma_f32 v[74:75], v[60:61], v[60:61], v[56:57] op_sel_hi:[1,1,0]
	v_pk_add_f32 v[72:73], v[62:63], v[72:73]
	v_mul_f32_e32 v74, v66, v66
	v_mul_f32_e32 v70, v64, v64
	v_mul_f32_e32 v68, v65, v65
	v_mul_f32_e32 v76, v62, v62
	v_mov_b32_e32 v77, v73
	v_pk_add_f32 v[72:73], v[76:77], v[74:75]
	v_pk_add_f32 v[68:69], v[70:71], v[68:69]
	v_mov_b32_e32 v43, v181
	v_pk_add_f32 v[68:69], v[72:73], v[68:69]
	v_lshlrev_b32_e32 v180, 3, v38
	v_add_f32_e32 v39, v68, v69
	v_mov_b32_e32 v68, v48
	v_mov_b32_e32 v69, v50
	v_add_f32_dpp v39, v39, v39 row_shr:1 row_mask:0xf bank_mask:0xf bound_ctrl:1
	v_mov_b32_e32 v50, v49
	v_mov_b32_e32 v63, v66
	v_add_f32_dpp v39, v39, v39 row_shr:2 row_mask:0xf bank_mask:0xf bound_ctrl:1
	v_add_u32_e32 v66, 3, v57
	v_cmp_lt_i32_e64 s[16:17], v66, v115
	v_add_f32_dpp v39, v39, v39 row_shr:4 row_mask:0xf bank_mask:0xf bound_ctrl:1
	v_cmp_ge_i32_e64 s[14:15], v66, v115
	s_nop 0
	v_add_f32_dpp v39, v39, v39 row_shr:8 row_mask:0xf bank_mask:0xf bound_ctrl:1
	s_nop 1
	v_mov_b32_dpp v43, v39 row_bcast:15 row_mask:0xa bank_mask:0xf
	v_add_f32_e32 v39, v39, v43
	v_mov_b32_e32 v43, v181
	s_nop 1
	v_mov_b32_dpp v43, v39 row_bcast:31 row_mask:0xc bank_mask:0xf
	v_add_f32_e32 v39, v39, v43
	s_nop 0
	v_readlane_b32 s0, v39, 63
	s_nop 1
	v_fma_f32 v39, s0, v247, v237
	v_rsq_f32_e32 v56, v39
	v_lshl_add_u64 v[38:39], s[84:85], 0, v[94:95]
	v_pk_mul_f32 v[68:69], v[56:57], v[68:69] op_sel_hi:[0,1]
	v_pk_mul_f32 v[48:49], v[56:57], v[50:51] op_sel_hi:[0,1]
	s_waitcnt lgkmcnt(0)
	v_pk_fma_f32 v[6:7], v[6:7], v[48:49], v[10:11]
	v_pk_fma_f32 v[4:5], v[4:5], v[68:69], v[8:9]
	s_nop 0
	v_cvt_pk_bf16_f32 v4, v4, v5
	v_cvt_pk_bf16_f32 v5, v6, v7
	v_lshl_add_u64 v[6:7], v[38:39], 0, v[180:181]
	global_store_dwordx2 v[6:7], v[4:5], off nt
	v_mov_b32_e32 v4, v52
	v_mov_b32_e32 v5, v54
	v_pk_mul_f32 v[68:69], v[56:57], v[4:5] op_sel_hi:[0,1]
	v_lshl_add_u32 v4, v42, 4, v114
	ds_read_b128 v[4:7], v4 offset:40960
	ds_read_b128 v[8:11], v37 offset:46080
	v_mov_b32_e32 v54, v53
	v_pk_mul_f32 v[70:71], v[56:57], v[54:55] op_sel_hi:[0,1]
	v_lshl_add_u32 v42, v40, 4, v114
	ds_read_b128 v[48:51], v42 offset:40960
	s_waitcnt lgkmcnt(1)
	v_pk_fma_f32 v[6:7], v[6:7], v[70:71], v[10:11]
	v_pk_fma_f32 v[4:5], v[4:5], v[68:69], v[8:9]
	v_cvt_pk_bf16_f32 v9, v6, v7
	v_cvt_pk_bf16_f32 v8, v4, v5
	ds_read_b128 v[4:7], v37 offset:47104
	v_lshl_add_u32 v42, v44, 4, v114
	v_lshl_add_u64 v[10:11], v[46:47], 3, v[38:39]
	ds_read_b128 v[52:55], v42 offset:40960
	global_store_dwordx2 v[10:11], v[8:9], off nt
	ds_read_b128 v[8:11], v37 offset:48128
	v_pk_mul_f32 v[42:43], v[56:57], v[58:59] op_sel_hi:[0,1]
	v_pk_mul_f32 v[46:47], v[56:57], v[60:61] op_sel_hi:[0,1]
	s_waitcnt lgkmcnt(2)
	v_pk_fma_f32 v[6:7], v[50:51], v[46:47], v[6:7]
	v_pk_fma_f32 v[4:5], v[48:49], v[42:43], v[4:5]
	s_nop 0
	v_cvt_pk_bf16_f32 v4, v4, v5
	v_cvt_pk_bf16_f32 v5, v6, v7
	v_lshl_add_u64 v[6:7], v[40:41], 3, v[38:39]
	global_store_dwordx2 v[6:7], v[4:5], off nt
	v_pk_mul_f32 v[4:5], v[56:57], v[62:63] op_sel_hi:[0,1]
	v_pk_mul_f32 v[6:7], v[56:57], v[64:65] op_sel_hi:[0,1]
	s_waitcnt lgkmcnt(0)
	v_pk_fma_f32 v[6:7], v[6:7], v[54:55], v[10:11]
	v_pk_fma_f32 v[4:5], v[4:5], v[52:53], v[8:9]
	s_nop 0
	v_cvt_pk_bf16_f32 v4, v4, v5
	v_cvt_pk_bf16_f32 v5, v6, v7
	v_lshl_add_u64 v[6:7], v[44:45], 3, v[38:39]
	global_store_dwordx2 v[6:7], v[4:5], off nt
	s_and_saveexec_b64 s[4:5], s[16:17]
	s_cbranch_execz .LBB0_206
	v_mov_b32_e32 v4, v186
	s_nop 0
	v_and_b32_e32 v6, 63, v4
	v_add_u32_e32 v4, 0xfffff803, v57
	v_ashrrev_i32_e32 v5, 31, v4
	v_lshlrev_b64 v[4:5], 12, v[4:5]
	v_lshl_add_u64 v[4:5], s[38:39], 0, v[4:5]
	v_lshlrev_b32_e32 v180, 3, v6
	v_lshl_add_u64 v[4:5], v[4:5], 0, v[180:181]
	global_load_dwordx2 v[12:13], v[4:5], off
	global_load_dwordx2 v[14:15], v[4:5], off offset:512
	global_load_dwordx2 v[16:17], v[4:5], off offset:1024
	global_load_dwordx2 v[18:19], v[4:5], off offset:1536

.LBB0_211:
	s_or_b64 exec, exec, s[16:17]
	v_pk_mul_f32 v[68:69], v[54:55], v[54:55]
	v_pk_mul_f32 v[70:71], v[52:53], v[52:53]
	v_mov_b32_e32 v67, v181
	v_pk_mov_b32 v[72:73], v[70:71], v[68:69] op_sel:[1,0]
	v_mov_b32_e32 v71, v69
	v_pk_add_f32 v[68:69], v[72:73], v[70:71]
	v_pk_mul_f32 v[70:71], v[46:47], v[46:47]
	v_pk_add_f32 v[68:69], v[68:69], v[68:69] op_sel_hi:[0,1]
	v_pk_mul_f32 v[72:73], v[48:49], v[48:49]
	v_mul_f32_e32 v68, v42, v42
	v_pk_mov_b32 v[74:75], v[72:73], v[70:71] op_sel:[1,0]
	v_mov_b32_e32 v73, v71
	v_pk_add_f32 v[70:71], v[74:75], v[72:73]
	v_pk_fma_f32 v[72:73], v[42:43], v[42:43], v[68:69] op_sel_hi:[1,1,0]
	v_mul_f32_e32 v68, v44, v44
	v_pk_add_f32 v[70:71], v[70:71], v[70:71] op_sel_hi:[0,1]
	v_pk_fma_f32 v[74:75], v[44:45], v[44:45], v[68:69] op_sel_hi:[1,1,0]
	v_mul_f32_e32 v72, v38, v38
	v_mul_f32_e32 v74, v39, v39
	v_mul_f32_e32 v68, v40, v40
	v_mul_f32_e32 v70, v41, v41
	v_pk_add_f32 v[72:73], v[72:73], v[74:75]
	v_pk_add_f32 v[68:69], v[68:69], v[70:71]
	v_lshlrev_b32_e32 v180, 3, v56
	v_pk_add_f32 v[68:69], v[72:73], v[68:69]
	s_nop 0
	v_add_f32_e32 v51, v68, v69
	s_nop 1
	v_add_f32_dpp v51, v51, v51 row_shr:1 row_mask:0xf bank_mask:0xf bound_ctrl:1
	s_nop 1
	v_add_f32_dpp v51, v51, v51 row_shr:2 row_mask:0xf bank_mask:0xf bound_ctrl:1
	s_nop 1
	v_add_f32_dpp v51, v51, v51 row_shr:4 row_mask:0xf bank_mask:0xf bound_ctrl:1
	s_nop 1
	v_add_f32_dpp v51, v51, v51 row_shr:8 row_mask:0xf bank_mask:0xf bound_ctrl:1
	s_nop 1
	v_mov_b32_dpp v67, v51 row_bcast:15 row_mask:0xa bank_mask:0xf
	v_add_f32_e32 v51, v51, v67
	v_mov_b32_e32 v67, v181
	s_nop 1
	v_mov_b32_dpp v67, v51 row_bcast:31 row_mask:0xc bank_mask:0xf
	v_add_f32_e32 v51, v51, v67
	v_mov_b32_e32 v67, v37
	v_readlane_b32 s0, v51, 63
	s_nop 1
	v_fma_f32 v51, s0, v247, v237
	v_rsq_f32_e32 v68, v51
	v_ashrrev_i32_e32 v51, 31, v50
	v_lshlrev_b64 v[50:51], 11, v[50:51]
	v_pk_mul_f32 v[52:53], v[68:69], v[52:53] op_sel_hi:[0,1]
	v_pk_mul_f32 v[54:55], v[68:69], v[54:55] op_sel_hi:[0,1]
	s_waitcnt lgkmcnt(0)
	v_pk_fma_f32 v[6:7], v[6:7], v[54:55], v[10:11]
	v_pk_fma_f32 v[4:5], v[4:5], v[52:53], v[8:9]
	v_lshl_add_u64 v[54:55], s[20:21], 0, v[50:51]
	v_cvt_pk_bf16_f32 v4, v4, v5
	v_cvt_pk_bf16_f32 v5, v6, v7
	v_lshl_add_u64 v[6:7], v[54:55], 0, v[180:181]
	global_store_dwordx2 v[6:7], v[4:5], off nt
	v_lshl_add_u32 v4, v60, 4, v114
	ds_read_b128 v[4:7], v4 offset:40960
	ds_read_b128 v[8:11], v61 offset:46080
	v_pk_mul_f32 v[70:71], v[48:49], v[68:69] op_sel_hi:[1,0]
	v_pk_mul_f32 v[72:73], v[46:47], v[68:69] op_sel_hi:[1,0]
	v_lshl_add_u32 v46, v58, 4, v114
	ds_read_b128 v[46:49], v46 offset:40960
	s_waitcnt lgkmcnt(1)
	v_pk_fma_f32 v[6:7], v[6:7], v[72:73], v[10:11]
	v_pk_fma_f32 v[4:5], v[4:5], v[70:71], v[8:9]
	v_cvt_pk_bf16_f32 v9, v6, v7
	v_cvt_pk_bf16_f32 v8, v4, v5
	ds_read_b128 v[4:7], v61 offset:47104
	v_lshl_add_u32 v50, v62, 4, v114
	v_lshl_add_u64 v[10:11], v[64:65], 3, v[54:55]
	ds_read_b128 v[50:53], v50 offset:40960
	global_store_dwordx2 v[10:11], v[8:9], off nt
	ds_read_b128 v[8:11], v61 offset:48128
	v_pk_mul_f32 v[42:43], v[42:43], v[68:69] op_sel_hi:[1,0]
	v_pk_mul_f32 v[44:45], v[44:45], v[68:69] op_sel_hi:[1,0]
	s_waitcnt lgkmcnt(2)
	v_pk_fma_f32 v[4:5], v[46:47], v[42:43], v[4:5]
	v_pk_fma_f32 v[6:7], v[48:49], v[44:45], v[6:7]
	v_cvt_pk_bf16_f32 v4, v4, v5
	v_cvt_pk_bf16_f32 v5, v6, v7
	v_lshl_add_u64 v[6:7], v[58:59], 3, v[54:55]
	global_store_dwordx2 v[6:7], v[4:5], off nt
	v_pk_mul_f32 v[4:5], v[38:39], v[68:69] op_sel_hi:[1,0]
	v_pk_mul_f32 v[6:7], v[40:41], v[68:69] op_sel_hi:[1,0]
	s_waitcnt lgkmcnt(0)
	v_pk_fma_f32 v[4:5], v[4:5], v[50:51], v[8:9]
	v_pk_fma_f32 v[6:7], v[6:7], v[52:53], v[10:11]
	v_cvt_pk_bf16_f32 v4, v4, v5
	v_cvt_pk_bf16_f32 v5, v6, v7
	v_lshl_add_u64 v[6:7], v[62:63], 3, v[54:55]
	global_store_dwordx2 v[6:7], v[4:5], off nt

.LBB0_230:
	s_or_b64 exec, exec, s[4:5]
	v_mov_b32_e32 v52, v186
	s_mov_b32 s0, 0x1b485000
	v_and_b32_e32 v113, 63, v52
	v_or_b32_e32 v56, 64, v113
	v_lshlrev_b32_e32 v119, 4, v56
	v_or_b32_e32 v56, 0x80, v113
	v_lshlrev_b32_e32 v180, 4, v113
	v_lshlrev_b32_e32 v118, 4, v56
	v_or_b32_e32 v56, 0xc0, v113
	v_lshlrev_b32_e32 v117, 4, v56
	v_lshl_add_u64 v[56:57], v[110:111], 0, v[180:181]
	v_lshl_add_u64 v[136:137], s[78:79], 0, v[56:57]
	v_add_co_u32_e32 v138, vcc, s0, v136
	s_mov_b32 s0, 0x1bc85000
	s_nop 0
	v_addc_co_u32_e32 v139, vcc, 0, v137, vcc
	v_add_co_u32_e32 v140, vcc, s0, v136
	s_mov_b32 s0, 0x1c485000
	s_nop 0
	v_addc_co_u32_e32 v141, vcc, 0, v137, vcc
	v_add_co_u32_e32 v142, vcc, s0, v136
	s_mov_b32 s0, 0x1cc85000
	s_nop 0
	v_addc_co_u32_e32 v143, vcc, 0, v137, vcc
	global_load_dwordx4 v[56:59], v[138:139], off
	global_load_dwordx4 v[72:75], v[140:141], off
	global_load_dwordx4 v[76:79], v[142:143], off
	v_add_co_u32_e32 v144, vcc, s0, v136
	global_load_dwordx4 v[52:55], v180, s[24:25]
	global_load_dwordx4 v[60:63], v119, s[24:25]
	v_addc_co_u32_e32 v145, vcc, 0, v137, vcc
	global_load_dwordx4 v[64:67], v118, s[24:25]
	global_load_dwordx4 v[68:71], v117, s[24:25]
	global_load_dwordx4 v[80:83], v[144:145], off
	global_load_dwordx4 v[120:123], v[138:139], off offset:1024
	global_load_dwordx4 v[124:127], v[140:141], off offset:1024
	global_load_dwordx4 v[128:131], v[142:143], off offset:1024
	global_load_dwordx4 v[132:135], v[144:145], off offset:1024
	s_xor_b64 s[42:43], s[42:43], -1
	s_mov_b64 s[50:51], -1
	s_waitcnt vmcnt(10)
	v_pk_add_f32 v[58:59], v[58:59], v[74:75]
	v_pk_add_f32 v[56:57], v[56:57], v[72:73]
	s_waitcnt vmcnt(4)
	v_pk_add_f32 v[72:73], v[78:79], v[82:83]
	v_pk_add_f32 v[74:75], v[76:77], v[80:81]
	v_pk_add_f32 v[58:59], v[58:59], v[72:73]
	v_pk_add_f32 v[56:57], v[56:57], v[74:75]
	v_pk_fma_f32 v[58:59], v[54:55], v[58:59], v[6:7]
	v_pk_fma_f32 v[56:57], v[52:53], v[56:57], v[4:5]
	s_waitcnt vmcnt(2)
	v_pk_add_f32 v[52:53], v[122:123], v[126:127]
	v_pk_add_f32 v[54:55], v[120:121], v[124:125]
	s_waitcnt vmcnt(0)
	v_pk_add_f32 v[72:73], v[130:131], v[134:135]
	v_pk_add_f32 v[74:75], v[128:129], v[132:133]
	v_pk_add_f32 v[52:53], v[52:53], v[72:73]
	v_pk_add_f32 v[72:73], v[54:55], v[74:75]
	v_pk_fma_f32 v[54:55], v[62:63], v[52:53], v[10:11]
	v_pk_fma_f32 v[52:53], v[60:61], v[72:73], v[8:9]
	global_load_dwordx4 v[60:63], v[138:139], off offset:2048
	global_load_dwordx4 v[72:75], v[140:141], off offset:2048
	global_load_dwordx4 v[76:79], v[142:143], off offset:2048
	global_load_dwordx4 v[80:83], v[144:145], off offset:2048
	global_load_dwordx4 v[120:123], v[138:139], off offset:3072
	global_load_dwordx4 v[124:127], v[140:141], off offset:3072
	global_load_dwordx4 v[128:131], v[142:143], off offset:3072
	global_load_dwordx4 v[132:135], v[144:145], off offset:3072
	s_waitcnt vmcnt(6)
	v_pk_add_f32 v[62:63], v[62:63], v[74:75]
	v_pk_add_f32 v[60:61], v[60:61], v[72:73]
	s_waitcnt vmcnt(4)
	v_pk_add_f32 v[72:73], v[78:79], v[82:83]
	v_pk_add_f32 v[74:75], v[76:77], v[80:81]
	v_pk_add_f32 v[62:63], v[62:63], v[72:73]
	v_pk_add_f32 v[60:61], v[60:61], v[74:75]
	v_pk_fma_f32 v[66:67], v[66:67], v[62:63], v[14:15]
	v_pk_fma_f32 v[64:65], v[64:65], v[60:61], v[12:13]
	s_waitcnt vmcnt(2)
	v_pk_add_f32 v[60:61], v[122:123], v[126:127]
	v_pk_add_f32 v[62:63], v[120:121], v[124:125]
	s_waitcnt vmcnt(0)
	v_pk_add_f32 v[72:73], v[130:131], v[134:135]
	v_pk_add_f32 v[74:75], v[128:129], v[132:133]
	v_pk_add_f32 v[60:61], v[60:61], v[72:73]
	v_pk_add_f32 v[72:73], v[62:63], v[74:75]
	v_pk_fma_f32 v[62:63], v[70:71], v[60:61], v[18:19]
	v_pk_fma_f32 v[60:61], v[68:69], v[72:73], v[16:17]
	v_add_co_u32_e32 v68, vcc, 0x3465000, v136
	v_add_u32_e32 v120, v114, v180
	s_nop 0
	v_addc_co_u32_e32 v69, vcc, 0, v137, vcc
	s_and_b64 vcc, exec, s[42:43]
	global_store_dwordx4 v[68:69], v[56:59], off nt
	global_store_dwordx4 v[68:69], v[52:55], off offset:1024 nt
	global_store_dwordx4 v[68:69], v[64:67], off offset:2048 nt
	global_store_dwordx4 v[68:69], v[60:63], off offset:3072 nt
	s_cbranch_vccz .LBB0_232
	global_load_dwordx4 v[68:71], v180, s[34:35]
	global_load_dwordx4 v[72:75], v180, s[30:31]
	global_load_dwordx4 v[76:79], v180, s[28:29]
	s_mov_b64 s[50:51], 0
	s_waitcnt vmcnt(1)
	v_pk_add_f32 v[74:75], v[74:75], 1.0 op_sel_hi:[1,0]
	v_pk_add_f32 v[72:73], v[72:73], 1.0 op_sel_hi:[1,0]
	v_pk_mul_f32 v[70:71], v[70:71], v[74:75]
	v_pk_mul_f32 v[68:69], v[68:69], v[72:73]
	ds_write_b128 v120, v[68:71] offset:40960
	s_waitcnt vmcnt(0)
	ds_write_b128 v120, v[76:79] offset:45056
	global_load_dwordx4 v[72:75], v180, s[34:35] offset:1024
	global_load_dwordx4 v[80:83], v119, s[30:31]
	s_waitcnt vmcnt(0)
	v_pk_add_f32 v[82:83], v[82:83], 1.0 op_sel_hi:[1,0]
	v_pk_add_f32 v[80:81], v[80:81], 1.0 op_sel_hi:[1,0]
	v_pk_mul_f32 v[74:75], v[74:75], v[82:83]
	v_pk_mul_f32 v[72:73], v[72:73], v[80:81]
	global_load_dwordx4 v[80:83], v119, s[28:29]
	ds_write_b128 v120, v[72:75] offset:41984
	s_waitcnt vmcnt(0)
	ds_write_b128 v120, v[80:83] offset:46080
	global_load_dwordx4 v[122:125], v180, s[34:35] offset:2048
	global_load_dwordx4 v[126:129], v118, s[30:31]
	s_waitcnt vmcnt(0)
	v_pk_add_f32 v[128:129], v[128:129], 1.0 op_sel_hi:[1,0]
	v_pk_add_f32 v[126:127], v[126:127], 1.0 op_sel_hi:[1,0]
	v_pk_mul_f32 v[124:125], v[124:125], v[128:129]
	v_pk_mul_f32 v[122:123], v[122:123], v[126:127]
	ds_write_b128 v120, v[122:125] offset:43008
	global_load_dwordx4 v[122:125], v118, s[28:29]
	s_waitcnt vmcnt(0)
	ds_write_b128 v120, v[122:125] offset:47104
	global_load_dwordx4 v[122:125], v180, s[34:35] offset:3072
	global_load_dwordx4 v[126:129], v117, s[30:31]
	s_waitcnt vmcnt(0)
	v_pk_add_f32 v[118:119], v[128:129], 1.0 op_sel_hi:[1,0]
	v_pk_add_f32 v[126:127], v[126:127], 1.0 op_sel_hi:[1,0]
	v_pk_mul_f32 v[124:125], v[124:125], v[118:119]
	v_pk_mul_f32 v[122:123], v[122:123], v[126:127]
	ds_write_b128 v120, v[122:125] offset:44032
	global_load_dwordx4 v[122:125], v117, s[28:29]
	s_waitcnt vmcnt(0)
	ds_write_b128 v120, v[122:125] offset:48128

.LBB0_234:
	v_pk_mul_f32 v[118:119], v[58:59], v[58:59]
	v_pk_mul_f32 v[122:123], v[56:57], v[56:57]
	v_mul_f32_e32 v117, v60, v60
	v_pk_mov_b32 v[124:125], v[122:123], v[118:119] op_sel:[1,0]
	v_mov_b32_e32 v123, v119
	v_pk_add_f32 v[118:119], v[124:125], v[122:123]
	v_pk_mul_f32 v[122:123], v[54:55], v[54:55]
	v_pk_mul_f32 v[124:125], v[52:53], v[52:53]
	v_mul_f32_e32 v121, v61, v61
	v_pk_mov_b32 v[126:127], v[124:125], v[122:123] op_sel:[1,0]
	v_mov_b32_e32 v125, v123
	v_pk_add_f32 v[122:123], v[126:127], v[124:125]
	v_pk_add_f32 v[118:119], v[118:119], v[118:119] op_sel:[0,1] op_sel_hi:[1,0]
	v_pk_add_f32 v[122:123], v[122:123], v[122:123] op_sel:[0,1] op_sel_hi:[1,0]
	v_mov_b32_e32 v119, v117
	v_mov_b32_e32 v123, v121
	v_pk_add_f32 v[118:119], v[118:119], v[122:123]
	v_mul_f32_e32 v122, v65, v65
	v_mul_f32_e32 v124, v62, v62
	v_pk_fma_f32 v[122:123], v[64:65], v[64:65], v[122:123] op_sel_hi:[1,1,0]
	v_mul_f32_e32 v126, v63, v63
	v_mov_b32_e32 v123, v124
	v_mul_f32_e32 v124, v67, v67
	v_pk_fma_f32 v[124:125], v[66:67], v[66:67], v[124:125] op_sel_hi:[1,1,0]
	v_lshlrev_b32_e32 v180, 3, v113
	v_mov_b32_e32 v125, v126
	v_pk_add_f32 v[122:123], v[122:123], v[124:125]
	s_nop 0
	v_pk_add_f32 v[118:119], v[118:119], v[122:123]
	s_nop 0
	v_add_f32_e32 v117, v118, v119
	v_mov_b32_e32 v118, v181
	s_nop 0
	v_add_f32_dpp v117, v117, v117 row_shr:1 row_mask:0xf bank_mask:0xf bound_ctrl:1
	s_nop 1
	v_add_f32_dpp v117, v117, v117 row_shr:2 row_mask:0xf bank_mask:0xf bound_ctrl:1
	s_nop 1
	v_add_f32_dpp v117, v117, v117 row_shr:4 row_mask:0xf bank_mask:0xf bound_ctrl:1
	s_nop 1
	v_add_f32_dpp v117, v117, v117 row_shr:8 row_mask:0xf bank_mask:0xf bound_ctrl:1
	s_nop 1
	v_mov_b32_dpp v118, v117 row_bcast:15 row_mask:0xa bank_mask:0xf
	v_add_f32_e32 v117, v117, v118
	v_mov_b32_e32 v118, v181
	s_nop 1
	v_mov_b32_dpp v118, v117 row_bcast:31 row_mask:0xc bank_mask:0xf
	v_add_f32_e32 v117, v117, v118
	s_nop 0
	v_readlane_b32 s0, v117, 63
	s_nop 1
	v_fma_f32 v117, s0, v247, v237
	v_rsq_f32_e32 v118, v117
	s_mov_b32 s0, 0x3e85000
	v_pk_mul_f32 v[56:57], v[56:57], v[118:119] op_sel_hi:[1,0]
	v_pk_mul_f32 v[58:59], v[58:59], v[118:119] op_sel_hi:[1,0]
	s_waitcnt lgkmcnt(1)
	v_pk_fma_f32 v[56:57], v[68:69], v[56:57], v[76:77]
	v_pk_fma_f32 v[58:59], v[70:71], v[58:59], v[78:79]
	v_cvt_pk_bf16_f32 v56, v56, v57
	v_cvt_pk_bf16_f32 v57, v58, v59
	v_lshl_add_u64 v[58:59], v[108:109], 0, v[180:181]
	v_lshl_add_u64 v[58:59], s[78:79], 0, v[58:59]
	v_pk_mul_f32 v[52:53], v[52:53], v[118:119] op_sel_hi:[1,0]
	v_pk_mul_f32 v[54:55], v[54:55], v[118:119] op_sel_hi:[1,0]
	v_add_co_u32_e32 v76, vcc, s0, v58
	s_waitcnt lgkmcnt(0)
	v_pk_fma_f32 v[54:55], v[74:75], v[54:55], v[82:83]
	v_pk_fma_f32 v[52:53], v[72:73], v[52:53], v[80:81]
	v_addc_co_u32_e32 v77, vcc, 0, v59, vcc
	v_cvt_pk_bf16_f32 v52, v52, v53
	v_cvt_pk_bf16_f32 v53, v54, v55
	global_store_dwordx2 v[76:77], v[56:57], off nt
	global_store_dwordx2 v[76:77], v[52:53], off offset:512 nt
	ds_read_b128 v[52:55], v120 offset:43008
	ds_read_b128 v[56:59], v120 offset:47104
	v_pk_mul_f32 v[72:73], v[64:65], v[118:119] op_sel_hi:[1,0]
	v_pk_mul_f32 v[74:75], v[66:67], v[118:119] op_sel_hi:[1,0]
	ds_read_b128 v[64:67], v120 offset:44032
	ds_read_b128 v[68:71], v120 offset:48128
	s_waitcnt lgkmcnt(2)
	v_pk_fma_f32 v[54:55], v[54:55], v[74:75], v[58:59]
	v_pk_fma_f32 v[52:53], v[52:53], v[72:73], v[56:57]
	v_add_u32_e32 v72, -1, v112
	v_cvt_pk_bf16_f32 v52, v52, v53
	v_cvt_pk_bf16_f32 v53, v54, v55
	global_store_dwordx2 v[76:77], v[52:53], off offset:1024 nt
	v_pk_mul_f32 v[52:53], v[60:61], v[118:119] op_sel_hi:[1,0]
	v_pk_mul_f32 v[54:55], v[62:63], v[118:119] op_sel_hi:[1,0]
	s_waitcnt lgkmcnt(0)
	v_pk_fma_f32 v[52:53], v[52:53], v[64:65], v[68:69]
	v_pk_fma_f32 v[54:55], v[54:55], v[66:67], v[70:71]
	v_cvt_pk_bf16_f32 v52, v52, v53
	v_cvt_pk_bf16_f32 v53, v54, v55
	v_cmp_lt_i32_e32 vcc, v72, v116
	global_store_dwordx2 v[76:77], v[52:53], off offset:1536 nt
	s_and_saveexec_b64 s[4:5], vcc
	s_cbranch_execz .LBB0_236
	v_mov_b32_e32 v4, v186
	s_nop 0
	v_and_b32_e32 v4, 63, v4
	v_lshlrev_b32_e32 v180, 4, v4
	v_lshl_add_u64 v[4:5], v[110:111], 0, v[180:181]
	v_lshl_add_u64 v[4:5], s[16:17], 0, v[4:5]
	v_add_co_u32_e32 v16, vcc, 0x3000, v4
	s_nop 1
	v_addc_co_u32_e32 v17, vcc, 0, v5, vcc
	global_load_dwordx4 v[4:7], v[16:17], off
	global_load_dwordx4 v[8:11], v[16:17], off offset:1024
	global_load_dwordx4 v[12:15], v[16:17], off offset:2048
	s_nop 0
	global_load_dwordx4 v[16:19], v[16:17], off offset:3072
.LBB0_236:
	s_or_b64 exec, exec, s[4:5]
	v_add_u32_e32 v68, -3, v112
	v_cmp_lt_i32_e32 vcc, v68, v116
	s_and_saveexec_b64 s[42:43], vcc
	s_cbranch_execz .LBB0_239
	v_mov_b32_e32 v52, v186
	v_ashrrev_i32_e32 v69, 31, v68
	v_and_b32_e32 v73, 63, v52
	v_lshlrev_b32_e32 v180, 4, v73
	v_or_b32_e32 v64, 0xc00, v180
	v_lshlrev_b64 v[70:71], 12, v[68:69]
	global_load_dwordx4 v[52:55], v180, s[24:25]
	global_load_dwordx4 v[74:77], v64, s[24:25]
	v_lshl_add_u64 v[64:65], s[22:23], 0, v[70:71]
	v_lshl_add_u64 v[82:83], v[64:65], 0, v[180:181]
	s_mov_b32 s0, 0x800000
	v_add_co_u32_e32 v142, vcc, s0, v82
	s_mov_b32 s0, 0x1000000
	s_nop 0
	v_addc_co_u32_e32 v143, vcc, 0, v83, vcc
	v_add_co_u32_e32 v144, vcc, s0, v82
	s_mov_b32 s0, 0x1800000
	s_nop 0
	v_addc_co_u32_e32 v145, vcc, 0, v83, vcc
	global_load_dwordx4 v[64:67], v[82:83], off
	global_load_dwordx4 v[78:81], v[142:143], off
	global_load_dwordx4 v[118:121], v[144:145], off
	v_add_co_u32_e32 v146, vcc, s0, v82
	v_or_b32_e32 v56, 0x400, v180
	v_or_b32_e32 v60, 0x800, v180
	v_addc_co_u32_e32 v147, vcc, 0, v83, vcc
	global_load_dwordx4 v[56:59], v56, s[24:25]
	v_lshl_add_u64 v[70:71], s[26:27], 0, v[70:71]
	global_load_dwordx4 v[60:63], v60, s[24:25]
	s_nop 0
	global_load_dwordx4 v[122:125], v[146:147], off
	global_load_dwordx4 v[126:129], v[82:83], off offset:1024
	global_load_dwordx4 v[130:133], v[142:143], off offset:1024
	global_load_dwordx4 v[134:137], v[144:145], off offset:1024
	global_load_dwordx4 v[138:141], v[146:147], off offset:1024
	v_lshl_add_u64 v[70:71], v[70:71], 0, v[180:181]
	s_waitcnt vmcnt(8)
	v_pk_add_f32 v[66:67], v[66:67], v[80:81]
	v_pk_add_f32 v[64:65], v[64:65], v[78:79]
	s_waitcnt vmcnt(4)
	v_pk_add_f32 v[78:79], v[120:121], v[124:125]
	v_pk_add_f32 v[80:81], v[118:119], v[122:123]
	v_pk_add_f32 v[66:67], v[66:67], v[78:79]
	v_pk_add_f32 v[64:65], v[64:65], v[80:81]
	v_pk_fma_f32 v[66:67], v[54:55], v[66:67], v[22:23]
	v_pk_fma_f32 v[64:65], v[52:53], v[64:65], v[20:21]
	s_waitcnt vmcnt(2)
	v_pk_add_f32 v[52:53], v[128:129], v[132:133]
	v_pk_add_f32 v[54:55], v[126:127], v[130:131]
	s_waitcnt vmcnt(0)
	v_pk_add_f32 v[78:79], v[136:137], v[140:141]
	v_pk_add_f32 v[80:81], v[134:135], v[138:139]
	v_pk_add_f32 v[52:53], v[52:53], v[78:79]
	v_pk_add_f32 v[54:55], v[54:55], v[80:81]
	v_pk_fma_f32 v[58:59], v[58:59], v[52:53], v[26:27]
	v_pk_fma_f32 v[56:57], v[56:57], v[54:55], v[24:25]
	global_load_dwordx4 v[52:55], v[82:83], off offset:2048
	global_load_dwordx4 v[78:81], v[142:143], off offset:2048
	global_load_dwordx4 v[118:121], v[144:145], off offset:2048
	global_load_dwordx4 v[122:125], v[146:147], off offset:2048
	global_load_dwordx4 v[126:129], v[82:83], off offset:3072
	global_load_dwordx4 v[130:133], v[142:143], off offset:3072
	global_load_dwordx4 v[134:137], v[144:145], off offset:3072
	global_load_dwordx4 v[138:141], v[146:147], off offset:3072
	s_waitcnt vmcnt(6)
	v_pk_add_f32 v[54:55], v[54:55], v[80:81]
	v_pk_add_f32 v[52:53], v[52:53], v[78:79]
	s_waitcnt vmcnt(4)
	v_pk_add_f32 v[78:79], v[120:121], v[124:125]
	v_pk_add_f32 v[80:81], v[118:119], v[122:123]
	v_pk_add_f32 v[54:55], v[54:55], v[78:79]
	v_pk_add_f32 v[52:53], v[52:53], v[80:81]
	v_pk_fma_f32 v[62:63], v[62:63], v[54:55], v[30:31]
	v_pk_fma_f32 v[60:61], v[60:61], v[52:53], v[28:29]
	s_waitcnt vmcnt(2)
	v_pk_add_f32 v[52:53], v[128:129], v[132:133]
	v_pk_add_f32 v[54:55], v[126:127], v[130:131]
	s_waitcnt vmcnt(0)
	v_pk_add_f32 v[78:79], v[136:137], v[140:141]
	v_pk_add_f32 v[80:81], v[134:135], v[138:139]
	v_pk_add_f32 v[52:53], v[52:53], v[78:79]
	v_pk_add_f32 v[78:79], v[54:55], v[80:81]
	v_pk_fma_f32 v[54:55], v[76:77], v[52:53], v[34:35]
	v_pk_fma_f32 v[52:53], v[74:75], v[78:79], v[32:33]
	global_store_dwordx4 v[70:71], v[64:67], off nt
	global_store_dwordx4 v[70:71], v[56:59], off offset:1024 nt
	global_store_dwordx4 v[70:71], v[60:63], off offset:2048 nt
	global_store_dwordx4 v[70:71], v[52:55], off offset:3072 nt
	v_pk_mul_f32 v[70:71], v[66:67], v[66:67]
	v_pk_mul_f32 v[74:75], v[64:65], v[64:65]
	s_nop 0
	v_pk_mov_b32 v[76:77], v[74:75], v[70:71] op_sel:[1,0]
	v_mov_b32_e32 v75, v71
	v_pk_add_f32 v[70:71], v[76:77], v[74:75]
	v_pk_mul_f32 v[74:75], v[58:59], v[58:59]
	v_pk_mul_f32 v[76:77], v[56:57], v[56:57]
	v_pk_add_f32 v[70:71], v[70:71], v[70:71] op_sel:[0,1] op_sel_hi:[1,0]
	v_pk_mov_b32 v[78:79], v[76:77], v[74:75] op_sel:[1,0]
	v_mov_b32_e32 v77, v75
	v_pk_add_f32 v[74:75], v[78:79], v[76:77]
	v_mul_f32_e32 v76, v52, v52
	v_mul_f32_e32 v77, v53, v53
	v_pk_add_f32 v[74:75], v[74:75], v[74:75] op_sel:[0,1] op_sel_hi:[1,0]
	v_mov_b32_e32 v71, v76
	v_mov_b32_e32 v75, v77
	v_pk_add_f32 v[70:71], v[70:71], v[74:75]
	v_mul_f32_e32 v74, v61, v61
	v_mul_f32_e32 v76, v63, v63
	v_mul_f32_e32 v78, v54, v54
	v_mul_f32_e32 v79, v55, v55
	v_pk_fma_f32 v[74:75], v[60:61], v[60:61], v[74:75] op_sel_hi:[1,1,0]
	v_pk_fma_f32 v[76:77], v[62:63], v[62:63], v[76:77] op_sel_hi:[1,1,0]
	v_mov_b32_e32 v75, v78
	v_mov_b32_e32 v77, v79
	v_pk_add_f32 v[74:75], v[74:75], v[76:77]
	v_lshlrev_b64 v[76:77], 11, v[68:69]
	v_pk_add_f32 v[70:71], v[70:71], v[74:75]
	s_nop 0
	v_add_f32_e32 v70, v70, v71
	v_mov_b32_e32 v71, v181
	s_nop 0
	v_add_f32_dpp v70, v70, v70 row_shr:1 row_mask:0xf bank_mask:0xf bound_ctrl:1
	s_nop 1
	v_add_f32_dpp v70, v70, v70 row_shr:2 row_mask:0xf bank_mask:0xf bound_ctrl:1
	s_nop 1
	v_add_f32_dpp v70, v70, v70 row_shr:4 row_mask:0xf bank_mask:0xf bound_ctrl:1
	s_nop 1
	v_add_f32_dpp v70, v70, v70 row_shr:8 row_mask:0xf bank_mask:0xf bound_ctrl:1
	s_nop 1
	v_mov_b32_dpp v71, v70 row_bcast:15 row_mask:0xa bank_mask:0xf
	v_add_f32_e32 v70, v70, v71
	v_mov_b32_e32 v71, v181
	s_nop 1
	v_mov_b32_dpp v71, v70 row_bcast:31 row_mask:0xc bank_mask:0xf
	v_add_f32_e32 v70, v70, v71
	s_nop 0
	v_readlane_b32 s0, v70, 63
	s_nop 1
	v_fma_f32 v70, s0, v247, v237
	v_rsq_f32_e32 v74, v70
	s_nop 0
	v_pk_mul_f32 v[78:79], v[64:65], v[74:75] op_sel_hi:[1,0]
	v_pk_mul_f32 v[80:81], v[66:67], v[74:75] op_sel_hi:[1,0]
	v_add_u32_e32 v75, v114, v180
	ds_read_b128 v[64:67], v75 offset:40960
	ds_read_b128 v[68:71], v75 offset:45056
	v_lshlrev_b32_e32 v180, 3, v73
	s_waitcnt lgkmcnt(0)
	v_pk_fma_f32 v[66:67], v[66:67], v[80:81], v[70:71]
	v_pk_fma_f32 v[64:65], v[64:65], v[78:79], v[68:69]
	v_pk_mul_f32 v[70:71], v[56:57], v[74:75] op_sel_hi:[1,0]
	v_cvt_pk_bf16_f32 v64, v64, v65
	v_cvt_pk_bf16_f32 v65, v66, v67
	v_lshl_add_u64 v[66:67], s[20:21], 0, v[76:77]
	v_lshl_add_u64 v[68:69], v[66:67], 0, v[180:181]
	global_store_dwordx2 v[68:69], v[64:65], off nt
	v_pk_mul_f32 v[76:77], v[58:59], v[74:75] op_sel_hi:[1,0]
	ds_read_b128 v[56:59], v75 offset:41984
	ds_read_b128 v[64:67], v75 offset:46080
	s_waitcnt lgkmcnt(0)
	v_pk_fma_f32 v[58:59], v[58:59], v[76:77], v[66:67]
	v_pk_fma_f32 v[56:57], v[56:57], v[70:71], v[64:65]
	v_pk_mul_f32 v[64:65], v[60:61], v[74:75] op_sel_hi:[1,0]
	v_cvt_pk_bf16_f32 v56, v56, v57
	v_cvt_pk_bf16_f32 v57, v58, v59
	global_store_dwordx2 v[68:69], v[56:57], off offset:512 nt
	v_pk_mul_f32 v[66:67], v[62:63], v[74:75] op_sel_hi:[1,0]
	ds_read_b128 v[56:59], v75 offset:43008
	ds_read_b128 v[60:63], v75 offset:47104
	s_waitcnt lgkmcnt(0)
	v_pk_fma_f32 v[58:59], v[66:67], v[58:59], v[62:63]
	v_pk_fma_f32 v[56:57], v[64:65], v[56:57], v[60:61]
	v_pk_mul_f32 v[60:61], v[52:53], v[74:75] op_sel_hi:[1,0]
	v_cvt_pk_bf16_f32 v56, v56, v57
	v_cvt_pk_bf16_f32 v57, v58, v59
	global_store_dwordx2 v[68:69], v[56:57], off offset:1024 nt
	v_pk_mul_f32 v[62:63], v[54:55], v[74:75] op_sel_hi:[1,0]
	ds_read_b128 v[52:55], v75 offset:44032
	ds_read_b128 v[56:59], v75 offset:48128
	s_waitcnt lgkmcnt(0)
	v_pk_fma_f32 v[54:55], v[62:63], v[54:55], v[58:59]
	v_pk_fma_f32 v[52:53], v[60:61], v[52:53], v[56:57]
	s_nop 0
	v_cvt_pk_bf16_f32 v52, v52, v53
	v_cvt_pk_bf16_f32 v53, v54, v55
	global_store_dwordx2 v[68:69], v[52:53], off offset:1536 nt
	s_or_b64 exec, exec, s[42:43]
	v_cmp_lt_i32_e32 vcc, v112, v116
	s_and_saveexec_b64 s[4:5], vcc
	s_cbranch_execnz .LBB0_240

.LBB0_241:
	v_mov_b32_e32 v52, v186
	s_mov_b32 s0, 0x3465000
	v_and_b32_e32 v70, 63, v52
	v_lshlrev_b32_e32 v180, 4, v70
	v_or_b32_e32 v56, 0x400, v180
	v_or_b32_e32 v60, 0x800, v180
	global_load_dwordx4 v[56:59], v56, s[24:25]
	s_nop 0
	global_load_dwordx4 v[74:77], v60, s[24:25]
	v_or_b32_e32 v60, 0xc00, v180
	global_load_dwordx4 v[52:55], v180, s[24:25]
	global_load_dwordx4 v[78:81], v60, s[24:25]
	v_lshl_add_u64 v[60:61], v[104:105], 0, v[180:181]
	v_lshl_add_u64 v[68:69], s[78:79], 0, v[60:61]
	v_add_co_u32_e32 v82, vcc, 0x1b485000, v68
	s_nop 1
	v_addc_co_u32_e32 v83, vcc, 0, v69, vcc
	v_add_co_u32_e32 v142, vcc, 0x1bc85000, v68
	global_load_dwordx4 v[60:63], v[82:83], off
	s_nop 0
	v_addc_co_u32_e32 v143, vcc, 0, v69, vcc
	v_add_co_u32_e32 v144, vcc, 0x1c485000, v68
	global_load_dwordx4 v[64:67], v[142:143], off
	s_nop 0
	v_addc_co_u32_e32 v145, vcc, 0, v69, vcc
	global_load_dwordx4 v[118:121], v[144:145], off
	v_add_co_u32_e32 v146, vcc, 0x1cc85000, v68
	s_waitcnt vmcnt(1)
	v_pk_add_f32 v[62:63], v[62:63], v[66:67]
	v_addc_co_u32_e32 v147, vcc, 0, v69, vcc
	global_load_dwordx4 v[122:125], v[146:147], off
	global_load_dwordx4 v[126:129], v[82:83], off offset:1024
	global_load_dwordx4 v[130:133], v[142:143], off offset:1024
	global_load_dwordx4 v[134:137], v[144:145], off offset:1024
	global_load_dwordx4 v[138:141], v[146:147], off offset:1024
	v_pk_add_f32 v[60:61], v[60:61], v[64:65]
	v_add_co_u32_e32 v68, vcc, s0, v68
	s_waitcnt vmcnt(4)
	v_pk_add_f32 v[64:65], v[120:121], v[124:125]
	v_pk_add_f32 v[66:67], v[118:119], v[122:123]
	v_pk_add_f32 v[62:63], v[62:63], v[64:65]
	v_pk_add_f32 v[60:61], v[60:61], v[66:67]
	v_pk_fma_f32 v[66:67], v[54:55], v[62:63], v[38:39]
	v_pk_fma_f32 v[64:65], v[52:53], v[60:61], v[36:37]
	s_waitcnt vmcnt(2)
	v_pk_add_f32 v[52:53], v[128:129], v[132:133]
	v_pk_add_f32 v[54:55], v[126:127], v[130:131]
	s_waitcnt vmcnt(0)
	v_pk_add_f32 v[60:61], v[136:137], v[140:141]
	v_pk_add_f32 v[62:63], v[134:135], v[138:139]
	v_pk_add_f32 v[52:53], v[52:53], v[60:61]
	v_pk_add_f32 v[54:55], v[54:55], v[62:63]
	v_pk_fma_f32 v[62:63], v[58:59], v[52:53], v[50:51]
	v_pk_fma_f32 v[60:61], v[56:57], v[54:55], v[48:49]
	global_load_dwordx4 v[52:55], v[82:83], off offset:2048
	global_load_dwordx4 v[56:59], v[142:143], off offset:2048
	global_load_dwordx4 v[118:121], v[144:145], off offset:2048
	global_load_dwordx4 v[122:125], v[146:147], off offset:2048
	global_load_dwordx4 v[126:129], v[82:83], off offset:3072
	global_load_dwordx4 v[130:133], v[142:143], off offset:3072
	global_load_dwordx4 v[134:137], v[144:145], off offset:3072
	global_load_dwordx4 v[138:141], v[146:147], off offset:3072
	v_addc_co_u32_e32 v69, vcc, 0, v69, vcc
	s_waitcnt vmcnt(6)
	v_pk_add_f32 v[54:55], v[54:55], v[58:59]
	v_pk_add_f32 v[52:53], v[52:53], v[56:57]
	s_waitcnt vmcnt(4)
	v_pk_add_f32 v[56:57], v[120:121], v[124:125]
	v_pk_add_f32 v[58:59], v[118:119], v[122:123]
	v_pk_add_f32 v[54:55], v[54:55], v[56:57]
	v_pk_add_f32 v[52:53], v[52:53], v[58:59]
	v_pk_fma_f32 v[58:59], v[76:77], v[54:55], v[46:47]
	v_pk_fma_f32 v[56:57], v[74:75], v[52:53], v[44:45]
	s_waitcnt vmcnt(2)
	v_pk_add_f32 v[52:53], v[128:129], v[132:133]
	v_pk_add_f32 v[54:55], v[126:127], v[130:131]
	s_waitcnt vmcnt(0)
	v_pk_add_f32 v[74:75], v[136:137], v[140:141]
	v_pk_add_f32 v[76:77], v[134:135], v[138:139]
	v_pk_add_f32 v[52:53], v[52:53], v[74:75]
	v_pk_add_f32 v[74:75], v[54:55], v[76:77]
	v_pk_fma_f32 v[54:55], v[80:81], v[52:53], v[42:43]
	v_pk_fma_f32 v[52:53], v[78:79], v[74:75], v[40:41]
	global_store_dwordx4 v[68:69], v[64:67], off nt
	global_store_dwordx4 v[68:69], v[60:63], off offset:1024 nt
	global_store_dwordx4 v[68:69], v[56:59], off offset:2048 nt
	global_store_dwordx4 v[68:69], v[52:55], off offset:3072 nt
	v_pk_mul_f32 v[68:69], v[66:67], v[66:67]
	v_pk_mul_f32 v[74:75], v[64:65], v[64:65]
	v_mul_f32_e32 v71, v52, v52
	v_pk_mov_b32 v[76:77], v[74:75], v[68:69] op_sel:[1,0]
	v_mov_b32_e32 v75, v69
	v_pk_add_f32 v[68:69], v[76:77], v[74:75]
	v_pk_mul_f32 v[74:75], v[62:63], v[62:63]
	v_pk_mul_f32 v[76:77], v[60:61], v[60:61]
	v_mul_f32_e32 v73, v53, v53
	v_pk_mov_b32 v[78:79], v[76:77], v[74:75] op_sel:[1,0]
	v_mov_b32_e32 v77, v75
	v_pk_add_f32 v[74:75], v[78:79], v[76:77]
	v_pk_add_f32 v[68:69], v[68:69], v[68:69] op_sel:[0,1] op_sel_hi:[1,0]
	v_pk_add_f32 v[74:75], v[74:75], v[74:75] op_sel:[0,1] op_sel_hi:[1,0]
	v_mov_b32_e32 v69, v71
	v_mov_b32_e32 v75, v73
	v_pk_add_f32 v[68:69], v[68:69], v[74:75]
	v_mul_f32_e32 v74, v57, v57
	v_mul_f32_e32 v76, v54, v54
	v_pk_fma_f32 v[74:75], v[56:57], v[56:57], v[74:75] op_sel_hi:[1,1,0]
	v_mul_f32_e32 v78, v55, v55
	v_mov_b32_e32 v75, v76
	v_mul_f32_e32 v76, v59, v59
	v_pk_fma_f32 v[76:77], v[58:59], v[58:59], v[76:77] op_sel_hi:[1,1,0]
	s_nop 0
	v_mov_b32_e32 v77, v78
	v_pk_add_f32 v[74:75], v[74:75], v[76:77]
	s_nop 0
	v_pk_add_f32 v[68:69], v[68:69], v[74:75]
	s_nop 0
	v_add_f32_e32 v68, v68, v69
	v_mov_b32_e32 v69, v181
	s_nop 0
	v_add_f32_dpp v68, v68, v68 row_shr:1 row_mask:0xf bank_mask:0xf bound_ctrl:1
	s_nop 1
	v_add_f32_dpp v68, v68, v68 row_shr:2 row_mask:0xf bank_mask:0xf bound_ctrl:1
	s_nop 1
	v_add_f32_dpp v68, v68, v68 row_shr:4 row_mask:0xf bank_mask:0xf bound_ctrl:1
	s_nop 1
	v_add_f32_dpp v68, v68, v68 row_shr:8 row_mask:0xf bank_mask:0xf bound_ctrl:1
	s_nop 1
	v_mov_b32_dpp v69, v68 row_bcast:15 row_mask:0xa bank_mask:0xf
	v_add_f32_e32 v68, v68, v69
	v_mov_b32_e32 v69, v181
	s_nop 1
	v_mov_b32_dpp v69, v68 row_bcast:31 row_mask:0xc bank_mask:0xf
	v_add_f32_e32 v68, v68, v69
	s_nop 0
	v_readlane_b32 s0, v68, 63
	s_nop 1
	v_fma_f32 v68, s0, v247, v237
	v_rsq_f32_e32 v68, v68
	s_mov_b32 s0, 0x3e85000
	v_pk_mul_f32 v[78:79], v[64:65], v[68:69] op_sel_hi:[1,0]
	v_pk_mul_f32 v[80:81], v[66:67], v[68:69] op_sel_hi:[1,0]
	v_add_u32_e32 v69, v114, v180
	ds_read_b128 v[64:67], v69 offset:40960
	ds_read_b128 v[74:77], v69 offset:45056
	v_lshlrev_b32_e32 v180, 3, v70
	s_waitcnt lgkmcnt(0)
	v_pk_fma_f32 v[66:67], v[66:67], v[80:81], v[76:77]
	v_pk_fma_f32 v[64:65], v[64:65], v[78:79], v[74:75]
	v_pk_mul_f32 v[74:75], v[60:61], v[68:69] op_sel_hi:[1,0]
	v_cvt_pk_bf16_f32 v64, v64, v65
	v_cvt_pk_bf16_f32 v65, v66, v67
	v_lshl_add_u64 v[66:67], v[106:107], 0, v[180:181]
	v_lshl_add_u64 v[66:67], s[78:79], 0, v[66:67]
	v_add_co_u32_e32 v70, vcc, s0, v66
	v_pk_mul_f32 v[76:77], v[62:63], v[68:69] op_sel_hi:[1,0]
	s_nop 0
	v_addc_co_u32_e32 v71, vcc, 0, v67, vcc
	global_store_dwordx2 v[70:71], v[64:65], off nt
	ds_read_b128 v[60:63], v69 offset:41984
	ds_read_b128 v[64:67], v69 offset:46080
	s_waitcnt lgkmcnt(0)
	v_pk_fma_f32 v[62:63], v[62:63], v[76:77], v[66:67]
	v_pk_fma_f32 v[60:61], v[60:61], v[74:75], v[64:65]
	v_pk_mul_f32 v[64:65], v[56:57], v[68:69] op_sel_hi:[1,0]
	v_cvt_pk_bf16_f32 v60, v60, v61
	v_cvt_pk_bf16_f32 v61, v62, v63
	global_store_dwordx2 v[70:71], v[60:61], off offset:512 nt
	v_pk_mul_f32 v[66:67], v[58:59], v[68:69] op_sel_hi:[1,0]
	ds_read_b128 v[56:59], v69 offset:43008
	ds_read_b128 v[60:63], v69 offset:47104
	s_waitcnt lgkmcnt(0)
	v_pk_fma_f32 v[58:59], v[66:67], v[58:59], v[62:63]
	v_pk_fma_f32 v[56:57], v[64:65], v[56:57], v[60:61]
	v_pk_mul_f32 v[60:61], v[52:53], v[68:69] op_sel_hi:[1,0]
	v_cvt_pk_bf16_f32 v56, v56, v57
	v_cvt_pk_bf16_f32 v57, v58, v59
	global_store_dwordx2 v[70:71], v[56:57], off offset:1024 nt
	v_pk_mul_f32 v[62:63], v[54:55], v[68:69] op_sel_hi:[1,0]
	ds_read_b128 v[52:55], v69 offset:44032
	ds_read_b128 v[56:59], v69 offset:48128
	s_waitcnt lgkmcnt(0)
	v_pk_fma_f32 v[54:55], v[62:63], v[54:55], v[58:59]
	v_pk_fma_f32 v[52:53], v[60:61], v[52:53], v[56:57]
	s_nop 0
	v_cvt_pk_bf16_f32 v52, v52, v53
	v_cvt_pk_bf16_f32 v53, v54, v55
	global_store_dwordx2 v[70:71], v[52:53], off offset:1536 nt
	s_branch .LBB0_227

.LBB0_326:
	s_or_b64 exec, exec, s[8:9]
	v_lshlrev_b32_e32 v74, 16, v64
	v_and_b32_e32 v75, 0xffff0000, v64
	v_lshlrev_b32_e32 v76, 16, v66
	v_and_b32_e32 v77, 0xffff0000, v66
	v_lshlrev_b32_e32 v64, 16, v65
	v_and_b32_e32 v65, 0xffff0000, v65
	v_lshlrev_b32_e32 v66, 16, v67
	v_and_b32_e32 v67, 0xffff0000, v67
	v_pk_add_f32 v[74:75], v[76:77], v[74:75]
	v_pk_add_f32 v[64:65], v[66:67], v[64:65]
	v_mov_b32_e32 v76, v75
	v_mov_b32_e32 v77, v65
	v_mov_b32_e32 v66, v74
	v_mov_b32_e32 v67, v64
	v_pk_mul_f32 v[76:77], v[76:77], v[76:77]
	s_mov_b32 s0, 0x3e85000
	v_pk_fma_f32 v[66:67], v[66:67], v[66:67], v[76:77]
	s_nop 0
	v_add_f32_e32 v66, v66, v67
	s_nop 1
	v_add_f32_dpp v66, v66, v66 quad_perm:[1,0,3,2] row_mask:0xf bank_mask:0xf bound_ctrl:1
	s_nop 1
	v_add_f32_dpp v66, v66, v66 quad_perm:[2,3,0,1] row_mask:0xf bank_mask:0xf bound_ctrl:1
	s_nop 1
	v_add_f32_dpp v66, v66, v66 row_half_mirror row_mask:0xf bank_mask:0xf bound_ctrl:1
	s_nop 1
	v_add_f32_dpp v66, v66, v66 row_mirror row_mask:0xf bank_mask:0xf bound_ctrl:1
	v_fmamk_f32 v66, v66, 0x3c800000, v237
	v_rsq_f32_e32 v66, v66
	s_nop 0
	v_pk_mul_f32 v[74:75], v[74:75], v[66:67] op_sel_hi:[1,0]
	v_pk_mul_f32 v[64:65], v[64:65], v[66:67] op_sel_hi:[1,0]
	v_pk_mul_f32 v[66:67], v[4:5], v[74:75]
	v_lshlrev_b32_e32 v74, 16, v62
	v_and_b32_e32 v75, 0xffff0000, v62
	v_mul_f32_e32 v62, 0xbfb8aa3b, v74
	v_exp_f32_e32 v62, v62
	v_pk_mul_f32 v[64:65], v[6:7], v[64:65]
	v_add_f32_e32 v62, 1.0, v62
	v_rcp_f32_e32 v76, v62
	v_mul_f32_e32 v62, 0xbfb8aa3b, v75
	v_exp_f32_e32 v62, v62
	s_nop 0
	v_add_f32_e32 v62, 1.0, v62
	v_rcp_f32_e32 v77, v62
	v_lshlrev_b32_e32 v62, 16, v63
	v_and_b32_e32 v63, 0xffff0000, v63
	v_pk_mul_f32 v[74:75], v[76:77], v[74:75]
	s_nop 0
	v_pk_mul_f32 v[66:67], v[74:75], v[66:67]
	s_nop 0
	v_cvt_pk_bf16_f32 v66, v66, v67
	v_mul_f32_e32 v67, 0xbfb8aa3b, v62
	v_exp_f32_e32 v67, v67
	s_nop 0
	v_add_f32_e32 v67, 1.0, v67
	v_rcp_f32_e32 v74, v67
	v_mul_f32_e32 v67, 0xbfb8aa3b, v63
	v_exp_f32_e32 v67, v67
	s_nop 0
	v_add_f32_e32 v67, 1.0, v67
	v_rcp_f32_e32 v75, v67
	s_nop 0
	v_pk_mul_f32 v[62:63], v[74:75], v[62:63]
	s_nop 0
	v_pk_mul_f32 v[62:63], v[62:63], v[64:65]
	v_lshlrev_b32_e32 v64, 16, v60
	v_cvt_pk_bf16_f32 v67, v62, v63
	v_add_co_u32_e32 v62, vcc, s0, v70
	v_and_b32_e32 v65, 0xffff0000, v60
	s_nop 0
	v_addc_co_u32_e32 v63, vcc, 0, v71, vcc
	global_store_dwordx2 v[62:63], v[66:67], off nt
	v_lshlrev_b32_e32 v66, 16, v58
	v_and_b32_e32 v67, 0xffff0000, v58
	v_lshlrev_b32_e32 v60, 16, v61
	v_and_b32_e32 v61, 0xffff0000, v61
	v_lshlrev_b32_e32 v58, 16, v59
	v_and_b32_e32 v59, 0xffff0000, v59
	v_pk_add_f32 v[64:65], v[66:67], v[64:65]
	v_pk_add_f32 v[58:59], v[58:59], v[60:61]
	v_mov_b32_e32 v66, v65
	v_mov_b32_e32 v67, v59
	v_mov_b32_e32 v60, v64
	v_mov_b32_e32 v61, v58
	v_pk_mul_f32 v[66:67], v[66:67], v[66:67]
	s_mov_b64 s[0:1], 0x800
	v_pk_fma_f32 v[60:61], v[60:61], v[60:61], v[66:67]
	v_lshl_add_u64 v[20:21], v[20:21], 0, s[0:1]
	v_add_f32_e32 v60, v60, v61
	s_mov_b64 s[0:1], 0x1c00
	v_lshl_add_u64 v[24:25], v[24:25], 0, s[0:1]
	v_add_f32_dpp v60, v60, v60 quad_perm:[1,0,3,2] row_mask:0xf bank_mask:0xf bound_ctrl:1
	s_nop 1
	v_add_f32_dpp v60, v60, v60 quad_perm:[2,3,0,1] row_mask:0xf bank_mask:0xf bound_ctrl:1
	s_nop 1
	v_add_f32_dpp v60, v60, v60 row_half_mirror row_mask:0xf bank_mask:0xf bound_ctrl:1
	s_nop 1
	v_add_f32_dpp v60, v60, v60 row_mirror row_mask:0xf bank_mask:0xf bound_ctrl:1
	v_fmamk_f32 v60, v60, 0x3c800000, v237
	v_rsq_f32_e32 v60, v60
	s_nop 0
	v_pk_mul_f32 v[58:59], v[58:59], v[60:61] op_sel_hi:[1,0]
	v_pk_mul_f32 v[60:61], v[64:65], v[60:61] op_sel_hi:[1,0]
	v_lshlrev_b32_e32 v64, 16, v56
	v_and_b32_e32 v65, 0xffff0000, v56
	v_mul_f32_e32 v56, 0xbfb8aa3b, v64
	v_exp_f32_e32 v56, v56
	s_nop 0
	v_add_f32_e32 v56, 1.0, v56
	v_rcp_f32_e32 v66, v56
	v_mul_f32_e32 v56, 0xbfb8aa3b, v65
	v_exp_f32_e32 v56, v56
	s_nop 0
	v_add_f32_e32 v56, 1.0, v56
	v_rcp_f32_e32 v67, v56
	s_nop 0
	v_pk_mul_f32 v[64:65], v[66:67], v[64:65]
	s_nop 0
	v_pk_mul_f32 v[60:61], v[64:65], v[60:61]
	s_waitcnt vmcnt(8)
	v_mov_b64_e32 v[66:67], v[26:27]
	v_cvt_pk_bf16_f32 v56, v60, v61
	v_lshlrev_b32_e32 v60, 16, v57
	v_and_b32_e32 v61, 0xffff0000, v57
	v_mul_f32_e32 v57, 0xbfb8aa3b, v60
	v_exp_f32_e32 v57, v57
	s_nop 0
	v_add_f32_e32 v57, 1.0, v57
	v_rcp_f32_e32 v64, v57
	v_mul_f32_e32 v57, 0xbfb8aa3b, v61
	v_exp_f32_e32 v57, v57
	s_nop 0
	v_add_f32_e32 v57, 1.0, v57
	v_rcp_f32_e32 v65, v57
	s_nop 0
	v_pk_mul_f32 v[60:61], v[64:65], v[60:61]
	s_nop 0
	v_pk_mul_f32 v[58:59], v[60:61], v[58:59]
	v_mov_b64_e32 v[64:65], v[32:33]
	v_cvt_pk_bf16_f32 v57, v58, v59
	global_store_dwordx2 v[62:63], v[56:57], off offset:512 nt
	v_lshlrev_b32_e32 v56, 16, v54
	v_and_b32_e32 v57, 0xffff0000, v54
	v_lshlrev_b32_e32 v58, 16, v52
	v_and_b32_e32 v59, 0xffff0000, v52
	v_lshlrev_b32_e32 v54, 16, v55
	v_and_b32_e32 v55, 0xffff0000, v55
	v_lshlrev_b32_e32 v52, 16, v53
	v_and_b32_e32 v53, 0xffff0000, v53
	v_pk_add_f32 v[56:57], v[58:59], v[56:57]
	v_pk_add_f32 v[52:53], v[52:53], v[54:55]
	v_mov_b32_e32 v58, v57
	v_mov_b32_e32 v59, v53
	v_mov_b32_e32 v54, v56
	v_mov_b32_e32 v55, v52
	v_pk_mul_f32 v[58:59], v[58:59], v[58:59]
	v_mov_b64_e32 v[60:61], v[38:39]
	v_pk_fma_f32 v[54:55], v[54:55], v[54:55], v[58:59]
	s_nop 0
	v_add_f32_e32 v54, v54, v55
	s_nop 1
	v_add_f32_dpp v54, v54, v54 quad_perm:[1,0,3,2] row_mask:0xf bank_mask:0xf bound_ctrl:1
	s_nop 1
	v_add_f32_dpp v54, v54, v54 quad_perm:[2,3,0,1] row_mask:0xf bank_mask:0xf bound_ctrl:1
	s_nop 1
	v_add_f32_dpp v54, v54, v54 row_half_mirror row_mask:0xf bank_mask:0xf bound_ctrl:1
	s_nop 1
	v_add_f32_dpp v54, v54, v54 row_mirror row_mask:0xf bank_mask:0xf bound_ctrl:1
	v_fmamk_f32 v54, v54, 0x3c800000, v237
	v_rsq_f32_e32 v54, v54
	s_nop 0
	v_pk_mul_f32 v[56:57], v[56:57], v[54:55] op_sel_hi:[1,0]
	v_pk_mul_f32 v[52:53], v[52:53], v[54:55] op_sel_hi:[1,0]
	v_pk_mul_f32 v[54:55], v[8:9], v[56:57]
	v_lshlrev_b32_e32 v56, 16, v50
	v_and_b32_e32 v57, 0xffff0000, v50
	v_mul_f32_e32 v50, 0xbfb8aa3b, v56
	v_exp_f32_e32 v50, v50
	v_pk_mul_f32 v[52:53], v[10:11], v[52:53]
	v_add_f32_e32 v50, 1.0, v50
	v_rcp_f32_e32 v58, v50
	v_mul_f32_e32 v50, 0xbfb8aa3b, v57
	v_exp_f32_e32 v50, v50
	s_nop 0
	v_add_f32_e32 v50, 1.0, v50
	v_rcp_f32_e32 v59, v50
	s_nop 0
	v_pk_mul_f32 v[56:57], v[58:59], v[56:57]
	s_nop 0
	v_pk_mul_f32 v[54:55], v[56:57], v[54:55]
	s_waitcnt vmcnt(8)
	v_mov_b64_e32 v[58:59], v[40:41]
	v_cvt_pk_bf16_f32 v50, v54, v55
	v_lshlrev_b32_e32 v54, 16, v51
	v_and_b32_e32 v55, 0xffff0000, v51
	v_mul_f32_e32 v51, 0xbfb8aa3b, v54
	v_exp_f32_e32 v51, v51
	s_nop 0
	v_add_f32_e32 v51, 1.0, v51
	v_rcp_f32_e32 v56, v51
	v_mul_f32_e32 v51, 0xbfb8aa3b, v55
	v_exp_f32_e32 v51, v51
	s_nop 0
	v_add_f32_e32 v51, 1.0, v51
	v_rcp_f32_e32 v57, v51
	s_nop 0
	v_pk_mul_f32 v[54:55], v[56:57], v[54:55]
	s_nop 0
	v_pk_mul_f32 v[52:53], v[54:55], v[52:53]
	s_waitcnt vmcnt(4)
	v_mov_b64_e32 v[56:57], v[30:31]
	v_cvt_pk_bf16_f32 v51, v52, v53
	global_store_dwordx2 v[62:63], v[50:51], off offset:1024 nt
	v_lshlrev_b32_e32 v50, 16, v18
	v_and_b32_e32 v51, 0xffff0000, v18
	v_lshlrev_b32_e32 v52, 16, v16
	v_and_b32_e32 v53, 0xffff0000, v16
	v_pk_add_f32 v[50:51], v[52:53], v[50:51]
	v_lshlrev_b32_e32 v52, 16, v22
	v_and_b32_e32 v53, 0xffff0000, v22
	v_pk_fma_f32 v[50:51], v[12:13], v[52:53], v[50:51]
	v_lshlrev_b32_e32 v18, 16, v19
	v_mul_f32_e32 v16, 0x3d372713, v50
	v_mul_f32_e32 v16, v50, v16
	v_fma_f32 v16, v50, v16, v50
	v_mul_f32_e32 v16, 0x3f4c422a, v16
	v_mul_f32_e32 v16, 0xc038aa3b, v16
	v_exp_f32_e32 v16, v16
	v_and_b32_e32 v19, 0xffff0000, v19
	v_lshlrev_b32_e32 v22, 16, v23
	v_and_b32_e32 v23, 0xffff0000, v23
	v_add_f32_e32 v16, 1.0, v16
	v_rcp_f32_e32 v52, v16
	v_mul_f32_e32 v16, 0x3d372713, v51
	v_mul_f32_e32 v16, v51, v16
	v_fma_f32 v16, v51, v16, v51
	v_mul_f32_e32 v16, 0x3f4c422a, v16
	v_mul_f32_e32 v16, 0xc038aa3b, v16
	v_exp_f32_e32 v16, v16
	v_mov_b64_e32 v[54:55], v[44:45]
	v_add_f32_e32 v16, 1.0, v16
	v_rcp_f32_e32 v53, v16
	s_nop 0
	v_pk_mul_f32 v[50:51], v[50:51], v[52:53]
	s_nop 0
	v_cvt_pk_bf16_f32 v16, v50, v51
	v_lshlrev_b32_e32 v50, 16, v17
	v_and_b32_e32 v51, 0xffff0000, v17
	v_pk_add_f32 v[18:19], v[50:51], v[18:19]
	s_waitcnt vmcnt(4)
	v_mov_b64_e32 v[50:51], v[34:35]
	v_pk_fma_f32 v[18:19], v[14:15], v[22:23], v[18:19]
	v_mov_b64_e32 v[52:53], v[42:43]
	v_mul_f32_e32 v17, 0x3d372713, v18
	v_mul_f32_e32 v17, v18, v17
	v_fma_f32 v17, v18, v17, v18
	v_mul_f32_e32 v17, 0x3f4c422a, v17
	v_mul_f32_e32 v17, 0xc038aa3b, v17
	v_exp_f32_e32 v17, v17
	s_nop 0
	v_add_f32_e32 v17, 1.0, v17
	v_rcp_f32_e32 v22, v17
	v_mul_f32_e32 v17, 0x3d372713, v19
	v_mul_f32_e32 v17, v19, v17
	v_fma_f32 v17, v19, v17, v19
	v_mul_f32_e32 v17, 0x3f4c422a, v17
	v_mul_f32_e32 v17, 0xc038aa3b, v17
	v_exp_f32_e32 v17, v17
	s_nop 0
	v_add_f32_e32 v17, 1.0, v17
	v_rcp_f32_e32 v23, v17
	s_nop 0
	v_pk_mul_f32 v[18:19], v[18:19], v[22:23]
	s_nop 0
	v_cvt_pk_bf16_f32 v17, v18, v19
	global_store_dwordx2 v[62:63], v[16:17], off offset:1536 nt
	v_mov_b64_e32 v[62:63], v[28:29]
	s_waitcnt vmcnt(4)
	v_mov_b64_e32 v[22:23], v[36:37]
	v_mov_b64_e32 v[16:17], v[46:47]
	v_mov_b64_e32 v[18:19], v[48:49]
	s_andn2_b64 exec, exec, s[12:13]
	s_cbranch_execz .LBB0_329

.LBB0_574:
	s_or_b64 exec, exec, s[8:9]
	s_waitcnt lgkmcnt(0)
	v_add_u32_e32 v40, v45, v46
	ds_read_b128 v[36:39], v40 offset:11776
	ds_read_b128 v[44:47], v40 offset:9216
	ds_read_b128 v[48:51], v40 offset:13056
	ds_read_b128 v[52:55], v40 offset:10496
	s_waitcnt lgkmcnt(0)
	s_waitcnt lgkmcnt(2)
	v_mfma_f32_16x16x32_bf16 v[56:59], v[36:39], v[44:47], 0
	s_lshl_b32 s0, s26, 6
	s_and_b32 s0, s0, 0x1c0
	s_addk_i32 s0, 0x900
	s_waitcnt lgkmcnt(0)
	v_mfma_f32_16x16x32_bf16 v[36:39], v[36:39], v[52:55], 0
	s_nop 2
	v_xor_b32_e32 v41, 0x80000000, v56
	v_xor_b32_e32 v40, 0x80000000, v57
	v_cvt_pk_bf16_f32 v40, v41, v40
	v_xor_b32_e32 v41, 0x80000000, v58
	v_xor_b32_e32 v42, 0x80000000, v59
	v_xor_b32_e32 v37, 0x80000000, v37
	v_xor_b32_e32 v36, 0x80000000, v36
	v_cvt_pk_bf16_f32 v56, v36, v37
	v_xor_b32_e32 v36, 0x80000000, v38
	v_xor_b32_e32 v37, 0x80000000, v39
	v_cvt_pk_bf16_f32 v57, v36, v37
	v_mfma_f32_16x16x32_bf16 v[36:39], v[48:51], v[44:47], 0
	v_cvt_pk_bf16_f32 v41, v41, v42
	v_add_u32_e32 v42, v89, v43
	v_add_u32_e32 v43, v88, v43
	s_nop 4
	v_xor_b32_e32 v37, 0x80000000, v37
	v_xor_b32_e32 v36, 0x80000000, v36
	v_cvt_pk_bf16_f32 v36, v36, v37
	v_xor_b32_e32 v37, 0x80000000, v38
	v_xor_b32_e32 v38, 0x80000000, v39
	v_cvt_pk_bf16_f32 v37, v37, v38
	v_add_u32_e32 v38, 0x1000, v42
	ds_write2_b64 v38, v[40:41], v[36:37] offset0:64 offset1:68
	v_mfma_f32_16x16x32_bf16 v[36:39], v[48:51], v[52:55], 0
	v_add_u32_e32 v41, s27, v83
	s_nop 6
	v_xor_b32_e32 v37, 0x80000000, v37
	v_xor_b32_e32 v36, 0x80000000, v36
	v_cvt_pk_bf16_f32 v36, v36, v37
	v_xor_b32_e32 v37, 0x80000000, v38
	v_xor_b32_e32 v38, 0x80000000, v39
	v_cvt_pk_bf16_f32 v37, v37, v38
	v_add_u32_e32 v38, 0x1000, v43
	ds_write2_b64 v38, v[56:57], v[36:37] offset0:64 offset1:68
	v_and_b32_e32 v36, 7, v78
	v_lshlrev_b32_e32 v44, 4, v36
	s_waitcnt lgkmcnt(0)
	v_lshl_or_b32 v40, v36, 3, s0
	v_add_u32_e32 v36, v87, v44
	ds_read_b128 v[36:39], v36
	s_movk_i32 s0, 0xe00
	v_mad_u64_u32 v[40:41], s[0:1], v41, s0, v[40:41]
	v_mov_b32_e32 v41, v181
	v_lshl_add_u64 v[42:43], v[40:41], 1, s[16:17]
	s_waitcnt lgkmcnt(0)
	global_store_dwordx4 v[42:43], v[36:39], off nt
	v_add_u32_e32 v180, 0x7000, v40
	v_lshl_add_u64 v[42:43], v[180:181], 1, s[16:17]
	v_add_u32_e32 v36, v86, v44
	ds_read_b128 v[36:39], v36
	v_add_u32_e32 v180, 0xe000, v40
	s_waitcnt lgkmcnt(0)
	global_store_dwordx4 v[42:43], v[36:39], off nt
	s_nop 1
	v_add_u32_e32 v36, v85, v44
	ds_read_b128 v[36:39], v36
	v_lshl_add_u64 v[42:43], v[180:181], 1, s[16:17]
	v_add_u32_e32 v180, 0x15000, v40
	s_waitcnt lgkmcnt(0)
	global_store_dwordx4 v[42:43], v[36:39], off nt
	s_nop 1
	v_add_u32_e32 v36, v84, v44
	ds_read_b128 v[36:39], v36
	v_lshl_add_u64 v[42:43], v[180:181], 1, s[16:17]
	v_add_u32_e32 v180, 0x1c000, v40
	s_waitcnt lgkmcnt(0)
	global_store_dwordx4 v[42:43], v[36:39], off nt
	s_nop 1
	v_add_u32_e32 v36, v82, v44
	ds_read_b128 v[36:39], v36
	v_lshl_add_u64 v[42:43], v[180:181], 1, s[16:17]
	v_add_u32_e32 v180, 0x23000, v40
	s_waitcnt lgkmcnt(0)
	global_store_dwordx4 v[42:43], v[36:39], off nt
	s_nop 1
	v_add_u32_e32 v36, v81, v44
	ds_read_b128 v[36:39], v36
	v_lshl_add_u64 v[42:43], v[180:181], 1, s[16:17]
	v_add_u32_e32 v180, 0x2a000, v40
	s_waitcnt lgkmcnt(0)
	global_store_dwordx4 v[42:43], v[36:39], off nt
	s_nop 1
	v_add_u32_e32 v36, v80, v44
	ds_read_b128 v[36:39], v36
	v_lshl_add_u64 v[42:43], v[180:181], 1, s[16:17]
	v_add_u32_e32 v180, 0x31000, v40
	v_lshl_add_u64 v[40:41], v[180:181], 1, s[16:17]
	s_waitcnt lgkmcnt(0)
	global_store_dwordx4 v[42:43], v[36:39], off nt
	s_nop 1
	v_add_u32_e32 v36, v79, v44
	ds_read_b128 v[36:39], v36
	s_waitcnt lgkmcnt(0)
	global_store_dwordx4 v[40:41], v[36:39], off nt
	s_waitcnt lgkmcnt(0)

.LBB0_598:
	s_or_b64 exec, exec, s[8:9]
	s_waitcnt lgkmcnt(0)
	v_add_u32_e32 v72, v77, v78
	ds_read_b128 v[68:71], v72 offset:11776
	ds_read_b128 v[76:79], v72 offset:9216
	ds_read_b128 v[80:83], v72 offset:13056
	ds_read_b128 v[84:87], v72 offset:10496
	s_waitcnt lgkmcnt(0)
	s_waitcnt lgkmcnt(2)
	v_mfma_f32_16x16x32_bf16 v[88:91], v[68:71], v[76:79], 0
	s_lshl_b32 s0, s38, 6
	s_and_b32 s0, s0, 0x1c0
	s_addk_i32 s0, 0x900
	s_waitcnt lgkmcnt(0)
	v_mfma_f32_16x16x32_bf16 v[68:71], v[68:71], v[84:87], 0
	s_nop 2
	v_xor_b32_e32 v73, 0x80000000, v88
	v_xor_b32_e32 v72, 0x80000000, v89
	v_cvt_pk_bf16_f32 v72, v73, v72
	v_xor_b32_e32 v73, 0x80000000, v90
	v_xor_b32_e32 v74, 0x80000000, v91
	v_xor_b32_e32 v69, 0x80000000, v69
	v_xor_b32_e32 v68, 0x80000000, v68
	v_cvt_pk_bf16_f32 v88, v68, v69
	v_xor_b32_e32 v68, 0x80000000, v70
	v_xor_b32_e32 v69, 0x80000000, v71
	v_cvt_pk_bf16_f32 v89, v68, v69
	v_mfma_f32_16x16x32_bf16 v[68:71], v[80:83], v[76:79], 0
	v_cvt_pk_bf16_f32 v73, v73, v74
	v_add_u32_e32 v74, v133, v75
	v_add_u32_e32 v75, v130, v75
	s_andn2_b64 vcc, exec, s[22:23]
	s_nop 3
	v_xor_b32_e32 v69, 0x80000000, v69
	v_xor_b32_e32 v68, 0x80000000, v68
	v_cvt_pk_bf16_f32 v68, v68, v69
	v_xor_b32_e32 v69, 0x80000000, v70
	v_xor_b32_e32 v70, 0x80000000, v71
	v_cvt_pk_bf16_f32 v69, v69, v70
	v_add_u32_e32 v70, 0x1000, v74
	ds_write2_b64 v70, v[72:73], v[68:69] offset0:64 offset1:68
	v_mfma_f32_16x16x32_bf16 v[68:71], v[80:83], v[84:87], 0
	v_add_u32_e32 v73, s39, v123
	s_nop 6
	v_xor_b32_e32 v69, 0x80000000, v69
	v_xor_b32_e32 v68, 0x80000000, v68
	v_cvt_pk_bf16_f32 v68, v68, v69
	v_xor_b32_e32 v69, 0x80000000, v70
	v_xor_b32_e32 v70, 0x80000000, v71
	v_cvt_pk_bf16_f32 v69, v69, v70
	v_add_u32_e32 v70, 0x1000, v75
	ds_write2_b64 v70, v[88:89], v[68:69] offset0:64 offset1:68
	v_and_b32_e32 v68, 7, v120
	v_lshlrev_b32_e32 v76, 4, v68
	s_waitcnt lgkmcnt(0)
	v_lshl_or_b32 v72, v68, 3, s0
	v_add_u32_e32 v68, v129, v76
	ds_read_b128 v[68:71], v68
	s_movk_i32 s0, 0xe00
	v_mad_u64_u32 v[72:73], s[0:1], v73, s0, v[72:73]
	v_mov_b32_e32 v73, v181
	v_lshl_add_u64 v[74:75], v[72:73], 1, s[16:17]
	s_waitcnt lgkmcnt(0)
	global_store_dwordx4 v[74:75], v[68:71], off nt
	v_add_u32_e32 v180, 0x7000, v72
	v_lshl_add_u64 v[74:75], v[180:181], 1, s[16:17]
	v_add_u32_e32 v68, v128, v76
	ds_read_b128 v[68:71], v68
	v_add_u32_e32 v180, 0xe000, v72
	s_waitcnt lgkmcnt(0)
	global_store_dwordx4 v[74:75], v[68:71], off nt
	s_nop 1
	v_add_u32_e32 v68, v127, v76
	ds_read_b128 v[68:71], v68
	v_lshl_add_u64 v[74:75], v[180:181], 1, s[16:17]
	v_add_u32_e32 v180, 0x15000, v72
	s_waitcnt lgkmcnt(0)
	global_store_dwordx4 v[74:75], v[68:71], off nt
	s_nop 1
	v_add_u32_e32 v68, v126, v76
	ds_read_b128 v[68:71], v68
	v_lshl_add_u64 v[74:75], v[180:181], 1, s[16:17]
	v_add_u32_e32 v180, 0x1c000, v72
	s_waitcnt lgkmcnt(0)
	global_store_dwordx4 v[74:75], v[68:71], off nt
	s_nop 1
	v_add_u32_e32 v68, v125, v76
	ds_read_b128 v[68:71], v68
	v_lshl_add_u64 v[74:75], v[180:181], 1, s[16:17]
	v_add_u32_e32 v180, 0x23000, v72
	s_waitcnt lgkmcnt(0)
	global_store_dwordx4 v[74:75], v[68:71], off nt
	s_nop 1
	v_add_u32_e32 v68, v124, v76
	ds_read_b128 v[68:71], v68
	v_lshl_add_u64 v[74:75], v[180:181], 1, s[16:17]
	v_add_u32_e32 v180, 0x2a000, v72
	s_waitcnt lgkmcnt(0)
	global_store_dwordx4 v[74:75], v[68:71], off nt
	s_nop 1
	v_add_u32_e32 v68, v122, v76
	ds_read_b128 v[68:71], v68
	v_lshl_add_u64 v[74:75], v[180:181], 1, s[16:17]
	v_add_u32_e32 v180, 0x31000, v72
	v_lshl_add_u64 v[72:73], v[180:181], 1, s[16:17]
	s_waitcnt lgkmcnt(0)
	global_store_dwordx4 v[74:75], v[68:71], off nt
	s_nop 1
	v_add_u32_e32 v68, v121, v76
	ds_read_b128 v[68:71], v68
	s_waitcnt lgkmcnt(0)
	global_store_dwordx4 v[72:73], v[68:71], off nt
	s_waitcnt lgkmcnt(0)
	s_cbranch_vccnz .LBB0_575
	s_cmp_lt_i32 s36, s31
	s_cselect_b32 s0, s36, s37
	s_min_i32 s1, s0, s29
	s_cmp_lt_i32 s0, s29
	s_mul_i32 s1, s1, s28
	s_cselect_b32 s0, s34, s30
	s_add_i32 s1, s0, s1
	s_ashr_i32 s1, s1, 3
	s_mul_hi_i32 s2, s1, 0x78787879
	s_lshr_b32 s4, s2, 31
	s_ashr_i32 s2, s2, 5
	s_add_i32 s2, s2, s4
	s_mul_i32 s4, s2, 0x44
	s_sub_i32 s1, s1, s4
	s_lshl_b32 s6, s1, 6
	v_mov_b32_e32 v68, v186
	s_cmp_gt_i32 s1, 3
	s_mov_b64 s[4:5], -1
	s_cbranch_scc0 .LBB0_601
	s_lshl_b32 s1, s2, 12
	s_add_i32 s1, s6, s1
	s_addk_i32 s1, 0x700
	s_mov_b64 s[4:5], 0

.LBB0_625:
	s_or_b64 exec, exec, s[8:9]
	v_lshlrev_b32_e32 v148, 16, v177
	v_and_b32_e32 v149, 0xffff0000, v177
	v_pk_fma_f32 v[148:149], v[22:23], v[148:149], v[178:179]
	v_mov_b64_e32 v[230:231], v[130:131]
	v_mul_f32_e32 v150, 0xbfb8aa3b, v149
	v_exp_f32_e32 v150, v150
	v_mov_b64_e32 v[232:233], v[136:137]
	v_mov_b64_e32 v[234:235], v[134:135]
	v_mov_b64_e32 v[194:195], v[142:143]
	v_add_f32_e32 v150, 1.0, v150
	v_rcp_f32_e32 v151, v150
	v_mul_f32_e32 v150, 0xbfb8aa3b, v148
	v_exp_f32_e32 v150, v150
	v_mov_b64_e32 v[218:219], v[132:133]
	v_mov_b64_e32 v[224:225], v[144:145]
	v_mov_b64_e32 v[190:191], v[120:121]
	v_add_f32_e32 v150, 1.0, v150
	v_rcp_f32_e32 v150, v150
	v_mov_b64_e32 v[192:193], v[112:113]
	v_mov_b64_e32 v[178:179], v[114:115]
	v_mov_b64_e32 v[112:113], v[146:147]
	v_pk_mul_f32 v[148:149], v[148:149], v[150:151]
	v_lshlrev_b32_e32 v150, 16, v176
	v_and_b32_e32 v151, 0xffff0000, v176
	v_pk_fma_f32 v[150:151], v[20:21], v[150:151], v[174:175]
	v_mov_b64_e32 v[174:175], v[124:125]
	v_mul_f32_e32 v154, 0xbfb8aa3b, v151
	v_exp_f32_e32 v154, v154
	v_mov_b64_e32 v[176:177], v[118:119]
	v_mov_b64_e32 v[114:115], v[140:141]
	v_add_f32_e32 v154, 1.0, v154
	v_rcp_f32_e32 v155, v154
	v_mul_f32_e32 v154, 0xbfb8aa3b, v150
	v_exp_f32_e32 v154, v154
	s_nop 0
	v_add_f32_e32 v154, 1.0, v154
	v_rcp_f32_e32 v154, v154
	s_nop 0
	v_pk_mul_f32 v[150:151], v[150:151], v[154:155]
	s_nop 0
	v_cvt_pk_bf16_f32 v150, v150, v151
	v_cvt_pk_bf16_f32 v151, v148, v149
	global_store_dwordx2 v[188:189], v[150:151], off offset:1024 nt
	v_mov_b64_e32 v[148:149], v[128:129]
	v_mov_b64_e32 v[188:189], v[126:127]
	v_mov_b64_e32 v[150:151], v[122:123]
	v_mov_b64_e32 v[154:155], v[116:117]
	v_mov_b64_e32 v[116:117], v[138:139]

.LBB0_633:
	s_or_b64 exec, exec, s[8:9]
	v_lshlrev_b32_e32 v212, 16, v205
	v_and_b32_e32 v213, 0xffff0000, v205
	v_pk_fma_f32 v[202:203], v[10:11], v[212:213], v[202:203]
	v_lshlrev_b32_e32 v214, 16, v180
	v_mul_f32_e32 v205, 0xbfb8aa3b, v203
	v_exp_f32_e32 v205, v205
	v_mul_f32_e32 v212, 0xbfb8aa3b, v202
	v_exp_f32_e32 v212, v212
	v_and_b32_e32 v215, 0xffff0000, v180
	v_pk_fma_f32 v[200:201], v[8:9], v[214:215], v[200:201]
	v_add_f32_e32 v205, 1.0, v205
	v_mul_f32_e32 v180, 0xbfb8aa3b, v201
	v_rcp_f32_e32 v213, v205
	v_add_f32_e32 v205, 1.0, v212
	v_exp_f32_e32 v180, v180
	v_mul_f32_e32 v212, 0xbfb8aa3b, v200
	v_exp_f32_e32 v214, v212
	v_rcp_f32_e32 v212, v205
	v_add_f32_e32 v180, 1.0, v180
	v_rcp_f32_e32 v215, v180
	v_add_f32_e32 v180, 1.0, v214
	v_rcp_f32_e32 v214, v180
	v_pk_mul_f32 v[202:203], v[202:203], v[212:213]
	v_pk_mul_f32 v[200:201], v[200:201], v[214:215]
	v_mov_b32_e32 v212, v202
	v_mov_b32_e32 v213, v200
	v_pk_mul_f32 v[212:213], v[212:213], v[212:213]
	v_mov_b32_e32 v214, v203
	v_mov_b32_e32 v215, v201
	v_pk_fma_f32 v[212:213], v[214:215], v[214:215], v[212:213]
	s_nop 0
	v_add_f32_e32 v180, v212, v213
	s_nop 1
	v_add_f32_dpp v180, v180, v180 quad_perm:[1,0,3,2] row_mask:0xf bank_mask:0xf bound_ctrl:1
	s_nop 1
	v_add_f32_dpp v180, v180, v180 quad_perm:[2,3,0,1] row_mask:0xf bank_mask:0xf bound_ctrl:1
	s_nop 1
	v_add_f32_dpp v180, v180, v180 row_half_mirror row_mask:0xf bank_mask:0xf bound_ctrl:1
	s_nop 1
	v_add_f32_dpp v180, v180, v180 row_mirror row_mask:0xf bank_mask:0xf bound_ctrl:1
	v_add_f32_e32 v180, 0x358637bd, v180
	v_rsq_f32_e32 v180, v180
	s_nop 0
	v_mul_f32_e32 v180, 0x3e000000, v180
	v_pk_mul_f32 v[202:203], v[202:203], v[180:181] op_sel_hi:[1,0]
	v_pk_mul_f32 v[200:201], v[200:201], v[180:181] op_sel_hi:[1,0]
	v_and_b32_e32 v180, 63, v204
	v_lshlrev_b32_e32 v180, 3, v180
	v_cvt_pk_bf16_f32 v212, v200, v201
	v_cvt_pk_bf16_f32 v213, v202, v203
	v_lshl_add_u64 v[200:201], v[152:153], 0, v[180:181]
	global_store_dwordx2 v[200:201], v[212:213], off offset:-1024 nt
	s_and_saveexec_b64 s[0:1], s[26:27]
	s_xor_b64 s[28:29], exec, s[0:1]
	s_cbranch_execz .LBB0_635
	v_cmp_le_u32_e64 s[10:11], v207, v206
	s_and_b64 s[0:1], vcc, s[10:11]
	v_cmp_le_u32_e64 s[12:13], v210, v209
	s_and_b64 s[8:9], s[0:1], s[12:13]
	v_cndmask_b32_e64 v180, 0, v222, s[8:9]
	v_cmp_eq_u32_e64 s[14:15], 0, v207
	v_cmp_lt_u32_e64 s[16:17], v210, v209
	v_cndmask_b32_e64 v202, 0, v223, s[8:9]
	v_cndmask_b32_e64 v180, v180, 0, s[14:15]
	s_and_b64 s[8:9], s[10:11], s[16:17]
	v_cndmask_b32_e64 v205, v202, 0, s[14:15]
	v_lshlrev_b32_e32 v202, 16, v180
	v_and_b32_e32 v203, 0xffff0000, v180
	v_cndmask_b32_e64 v180, 0, v178, s[8:9]
	v_cndmask_b32_e64 v212, 0, v179, s[8:9]
	v_cmp_le_u32_e64 s[8:9], v211, v209
	s_and_b64 s[10:11], s[10:11], s[8:9]
	v_cndmask_b32_e64 v214, v212, 0, s[14:15]
	v_cndmask_b32_e64 v212, 0, v114, s[10:11]
	v_cndmask_b32_e64 v213, 0, v115, s[10:11]
	v_cmp_lt_u32_e64 s[10:11], v207, v206
	s_and_b64 s[0:1], vcc, s[10:11]
	v_cndmask_b32_e64 v180, v180, 0, s[14:15]
	v_cndmask_b32_e64 v215, v213, 0, s[14:15]
	v_cndmask_b32_e64 v216, v212, 0, s[14:15]
	s_and_b64 s[14:15], s[0:1], s[12:13]
	v_cndmask_b32_e64 v217, 0, v221, s[14:15]
	v_cndmask_b32_e64 v220, 0, v220, s[14:15]
	s_and_b64 s[14:15], s[10:11], s[16:17]
	s_and_b64 s[10:11], s[10:11], s[8:9]
	v_pk_fma_f32 v[202:203], v[100:101], v[202:203], 0 op_sel_hi:[1,1,0]
	v_lshlrev_b32_e32 v212, 16, v180
	v_and_b32_e32 v213, 0xffff0000, v180
	v_cndmask_b32_e64 v223, 0, v119, s[10:11]
	v_cndmask_b32_e64 v224, 0, v118, s[10:11]
	v_cmp_le_u32_e64 s[10:11], v208, v206
	v_pk_fma_f32 v[202:203], v[88:89], v[212:213], v[202:203]
	v_lshlrev_b32_e32 v212, 16, v216
	v_and_b32_e32 v213, 0xffff0000, v216
	v_cndmask_b32_e64 v222, 0, v176, s[14:15]
	s_and_b64 s[0:1], vcc, s[10:11]
	v_pk_fma_f32 v[202:203], v[104:105], v[212:213], v[202:203]
	v_lshlrev_b32_e32 v212, 16, v220
	v_and_b32_e32 v213, 0xffff0000, v220
	s_and_b64 s[12:13], s[0:1], s[12:13]
	v_pk_fma_f32 v[202:203], v[60:61], v[212:213], v[202:203]
	v_lshlrev_b32_e32 v212, 16, v222
	v_and_b32_e32 v213, 0xffff0000, v222
	v_cndmask_b32_e64 v219, 0, v219, s[12:13]
	v_cndmask_b32_e64 v218, 0, v218, s[12:13]
	s_and_b64 s[12:13], s[10:11], s[16:17]
	v_pk_fma_f32 v[202:203], v[48:49], v[212:213], v[202:203]
	v_lshlrev_b32_e32 v212, 16, v224
	v_and_b32_e32 v213, 0xffff0000, v224
	v_cndmask_b32_e64 v226, 0, v174, s[12:13]
	v_pk_fma_f32 v[202:203], v[40:41], v[212:213], v[202:203]
	v_lshlrev_b32_e32 v212, 16, v218
	v_and_b32_e32 v213, 0xffff0000, v218
	v_lshlrev_b32_e32 v204, 16, v205
	v_and_b32_e32 v205, 0xffff0000, v205
	v_pk_fma_f32 v[202:203], v[52:53], v[212:213], v[202:203]
	v_lshlrev_b32_e32 v212, 16, v226
	v_and_b32_e32 v213, 0xffff0000, v226
	v_pk_fma_f32 v[202:203], v[12:13], v[212:213], v[202:203]
	v_pk_fma_f32 v[204:205], v[102:103], v[204:205], 0 op_sel_hi:[1,1,0]
	v_lshlrev_b32_e32 v212, 16, v214
	v_and_b32_e32 v213, 0xffff0000, v214
	v_pk_fma_f32 v[204:205], v[90:91], v[212:213], v[204:205]
	v_lshlrev_b32_e32 v212, 16, v215
	v_and_b32_e32 v213, 0xffff0000, v215
	v_cndmask_b32_e64 v221, 0, v177, s[14:15]
	v_pk_fma_f32 v[204:205], v[106:107], v[212:213], v[204:205]
	v_lshlrev_b32_e32 v212, 16, v217
	v_and_b32_e32 v213, 0xffff0000, v217
	v_pk_fma_f32 v[204:205], v[62:63], v[212:213], v[204:205]
	v_lshlrev_b32_e32 v212, 16, v221
	v_and_b32_e32 v213, 0xffff0000, v221
	v_pk_fma_f32 v[204:205], v[50:51], v[212:213], v[204:205]
	v_lshlrev_b32_e32 v212, 16, v223
	v_and_b32_e32 v213, 0xffff0000, v223
	v_cndmask_b32_e64 v225, 0, v175, s[12:13]
	v_pk_fma_f32 v[204:205], v[42:43], v[212:213], v[204:205]
	v_lshlrev_b32_e32 v212, 16, v219
	v_and_b32_e32 v213, 0xffff0000, v219
	v_pk_fma_f32 v[204:205], v[54:55], v[212:213], v[204:205]
	v_lshlrev_b32_e32 v212, 16, v225
	v_and_b32_e32 v213, 0xffff0000, v225
	s_and_b64 s[8:9], s[10:11], s[8:9]
	v_pk_fma_f32 v[204:205], v[14:15], v[212:213], v[204:205]
	v_cndmask_b32_e64 v180, 0, v124, s[8:9]
	v_cndmask_b32_e64 v212, 0, v125, s[8:9]

.LBB0_637:
	s_or_b64 exec, exec, s[8:9]
	v_lshlrev_b32_e32 v214, 16, v212
	v_and_b32_e32 v215, 0xffff0000, v212
	v_pk_fma_f32 v[204:205], v[6:7], v[214:215], v[204:205]
	v_and_b32_e32 v215, 0xffff0000, v180
	v_mul_f32_e32 v212, 0xbfb8aa3b, v205
	v_exp_f32_e32 v212, v212
	v_mul_f32_e32 v213, 0xbfb8aa3b, v204
	v_exp_f32_e32 v214, v213
	v_add_f32_e32 v212, 1.0, v212
	v_rcp_f32_e32 v213, v212
	v_add_f32_e32 v212, 1.0, v214
	v_lshlrev_b32_e32 v214, 16, v180
	v_pk_fma_f32 v[202:203], v[4:5], v[214:215], v[202:203]
	v_rcp_f32_e32 v212, v212
	v_mul_f32_e32 v180, 0xbfb8aa3b, v203
	v_exp_f32_e32 v180, v180
	v_mul_f32_e32 v214, 0xbfb8aa3b, v202
	v_exp_f32_e32 v214, v214
	v_pk_mul_f32 v[204:205], v[204:205], v[212:213]
	v_add_f32_e32 v180, 1.0, v180
	v_rcp_f32_e32 v215, v180
	v_add_f32_e32 v180, 1.0, v214
	v_rcp_f32_e32 v214, v180
	v_mov_b32_e32 v212, v204
	v_pk_mul_f32 v[202:203], v[202:203], v[214:215]
	s_nop 0
	v_mov_b32_e32 v213, v202
	v_pk_mul_f32 v[212:213], v[212:213], v[212:213]
	v_mov_b32_e32 v214, v205
	v_mov_b32_e32 v215, v203
	v_pk_fma_f32 v[212:213], v[214:215], v[214:215], v[212:213]
	s_nop 0
	v_add_f32_e32 v180, v212, v213
	s_nop 1
	v_add_f32_dpp v180, v180, v180 quad_perm:[1,0,3,2] row_mask:0xf bank_mask:0xf bound_ctrl:1
	s_nop 1
	v_add_f32_dpp v180, v180, v180 quad_perm:[2,3,0,1] row_mask:0xf bank_mask:0xf bound_ctrl:1
	s_nop 1
	v_add_f32_dpp v180, v180, v180 row_half_mirror row_mask:0xf bank_mask:0xf bound_ctrl:1
	s_nop 1
	v_add_f32_dpp v180, v180, v180 row_mirror row_mask:0xf bank_mask:0xf bound_ctrl:1
	v_add_f32_e32 v180, 0x358637bd, v180
	v_rsq_f32_e32 v180, v180
	s_nop 0
	v_pk_mul_f32 v[204:205], v[204:205], v[180:181] op_sel_hi:[1,0]
	v_pk_mul_f32 v[202:203], v[202:203], v[180:181] op_sel_hi:[1,0]
	s_nop 0
	v_cvt_pk_bf16_f32 v202, v202, v203
	v_cvt_pk_bf16_f32 v203, v204, v205
	global_store_dwordx2 v[200:201], v[202:203], off offset:-512 nt
	s_and_saveexec_b64 s[0:1], s[26:27]
	s_xor_b64 s[26:27], exec, s[0:1]
	s_cbranch_execz .LBB0_639
	v_cmp_le_u32_e64 s[10:11], v207, v206
	s_and_b64 s[0:1], vcc, s[10:11]
	v_cmp_le_u32_e64 s[12:13], v210, v209
	s_and_b64 s[8:9], s[0:1], s[12:13]
	v_cndmask_b32_e64 v180, 0, v198, s[8:9]
	v_cndmask_b32_e64 v198, 0, v199, s[8:9]
	v_cmp_eq_u32_e64 s[14:15], 0, v207
	v_cmp_lt_u32_e64 s[16:17], v210, v209
	s_and_b64 s[8:9], s[10:11], s[16:17]
	v_cndmask_b32_e64 v202, v198, 0, s[14:15]
	v_cndmask_b32_e64 v180, v180, 0, s[14:15]
	v_lshlrev_b32_e32 v198, 16, v180
	v_and_b32_e32 v199, 0xffff0000, v180
	v_lshlrev_b32_e32 v204, 16, v202
	v_and_b32_e32 v205, 0xffff0000, v202
	v_cndmask_b32_e64 v180, 0, v154, s[8:9]
	v_cndmask_b32_e64 v202, 0, v155, s[8:9]
	v_cmp_le_u32_e64 s[8:9], v211, v209
	s_and_b64 s[10:11], s[10:11], s[8:9]
	v_cndmask_b32_e64 v210, v202, 0, s[14:15]
	v_cndmask_b32_e64 v202, 0, v116, s[10:11]
	v_cndmask_b32_e64 v203, 0, v117, s[10:11]
	v_cmp_lt_u32_e64 s[10:11], v207, v206
	s_and_b64 s[0:1], vcc, s[10:11]
	v_cndmask_b32_e64 v180, v180, 0, s[14:15]
	v_cndmask_b32_e64 v209, v203, 0, s[14:15]
	v_cndmask_b32_e64 v202, v202, 0, s[14:15]
	s_and_b64 s[14:15], s[0:1], s[12:13]
	v_cndmask_b32_e64 v207, 0, v197, s[14:15]
	v_cndmask_b32_e64 v203, 0, v196, s[14:15]
	s_and_b64 s[14:15], s[10:11], s[16:17]
	s_and_b64 s[10:11], s[10:11], s[8:9]
	v_cndmask_b32_e64 v213, 0, v123, s[10:11]
	v_cndmask_b32_e64 v214, 0, v122, s[10:11]
	v_cmp_le_u32_e64 s[10:11], v208, v206
	s_and_b64 s[0:1], vcc, s[10:11]
	s_and_b64 vcc, s[0:1], s[12:13]
	v_cndmask_b32_e32 v206, 0, v195, vcc
	v_cndmask_b32_e32 v208, 0, v194, vcc
	v_pk_fma_f32 v[194:195], v[96:97], v[198:199], 0 op_sel_hi:[1,1,0]
	v_lshlrev_b32_e32 v196, 16, v180
	v_and_b32_e32 v197, 0xffff0000, v180
	v_pk_fma_f32 v[194:195], v[80:81], v[196:197], v[194:195]
	v_lshlrev_b32_e32 v196, 16, v202
	v_and_b32_e32 v197, 0xffff0000, v202
	v_cndmask_b32_e64 v212, 0, v150, s[14:15]
	v_pk_fma_f32 v[194:195], v[72:73], v[196:197], v[194:195]
	v_lshlrev_b32_e32 v196, 16, v203
	v_and_b32_e32 v197, 0xffff0000, v203
	v_pk_fma_f32 v[194:195], v[84:85], v[196:197], v[194:195]
	v_lshlrev_b32_e32 v196, 16, v212
	v_and_b32_e32 v197, 0xffff0000, v212
	s_and_b64 vcc, s[10:11], s[16:17]
	v_pk_fma_f32 v[194:195], v[44:45], v[196:197], v[194:195]
	v_lshlrev_b32_e32 v196, 16, v214
	v_and_b32_e32 v197, 0xffff0000, v214
	v_cndmask_b32_e32 v216, 0, v148, vcc
	v_pk_fma_f32 v[194:195], v[32:33], v[196:197], v[194:195]
	v_lshlrev_b32_e32 v196, 16, v208
	v_and_b32_e32 v197, 0xffff0000, v208
	v_pk_fma_f32 v[194:195], v[24:25], v[196:197], v[194:195]
	v_lshlrev_b32_e32 v196, 16, v216
	v_and_b32_e32 v197, 0xffff0000, v216
	v_pk_fma_f32 v[202:203], v[36:37], v[196:197], v[194:195]
	v_pk_fma_f32 v[194:195], v[98:99], v[204:205], 0 op_sel_hi:[1,1,0]
	v_lshlrev_b32_e32 v196, 16, v210
	v_and_b32_e32 v197, 0xffff0000, v210
	v_pk_fma_f32 v[194:195], v[82:83], v[196:197], v[194:195]
	v_lshlrev_b32_e32 v196, 16, v209
	v_and_b32_e32 v197, 0xffff0000, v209
	v_cndmask_b32_e64 v211, 0, v151, s[14:15]
	v_pk_fma_f32 v[194:195], v[74:75], v[196:197], v[194:195]
	v_lshlrev_b32_e32 v196, 16, v207
	v_and_b32_e32 v197, 0xffff0000, v207
	v_pk_fma_f32 v[194:195], v[86:87], v[196:197], v[194:195]
	v_lshlrev_b32_e32 v196, 16, v211
	v_and_b32_e32 v197, 0xffff0000, v211
	v_pk_fma_f32 v[194:195], v[46:47], v[196:197], v[194:195]
	v_lshlrev_b32_e32 v196, 16, v213
	v_and_b32_e32 v197, 0xffff0000, v213
	v_cndmask_b32_e32 v215, 0, v149, vcc
	v_pk_fma_f32 v[194:195], v[34:35], v[196:197], v[194:195]
	v_lshlrev_b32_e32 v196, 16, v206
	v_and_b32_e32 v197, 0xffff0000, v206
	v_pk_fma_f32 v[194:195], v[26:27], v[196:197], v[194:195]
	v_lshlrev_b32_e32 v196, 16, v215
	v_and_b32_e32 v197, 0xffff0000, v215
	s_and_b64 vcc, s[10:11], s[8:9]
	v_pk_fma_f32 v[204:205], v[38:39], v[196:197], v[194:195]
	v_cndmask_b32_e32 v180, 0, v128, vcc
	v_cndmask_b32_e32 v212, 0, v129, vcc

.LBB0_641:
	s_or_b64 exec, exec, s[8:9]
	v_lshlrev_b32_e32 v194, 16, v212
	v_and_b32_e32 v195, 0xffff0000, v212
	v_pk_fma_f32 v[194:195], v[22:23], v[194:195], v[204:205]
	v_and_b32_e32 v199, 0xffff0000, v180
	v_mul_f32_e32 v196, 0xbfb8aa3b, v195
	v_exp_f32_e32 v196, v196
	v_mul_f32_e32 v197, 0xbfb8aa3b, v194
	v_exp_f32_e32 v198, v197
	v_add_u32_e32 v223, 1, v187
	v_add_f32_e32 v196, 1.0, v196
	v_rcp_f32_e32 v197, v196
	v_add_f32_e32 v196, 1.0, v198
	v_lshlrev_b32_e32 v198, 16, v180
	v_pk_fma_f32 v[198:199], v[20:21], v[198:199], v[202:203]
	v_rcp_f32_e32 v196, v196
	v_mul_f32_e32 v180, 0xbfb8aa3b, v199
	v_exp_f32_e32 v180, v180
	v_mul_f32_e32 v202, 0xbfb8aa3b, v198
	v_exp_f32_e32 v202, v202
	v_pk_mul_f32 v[194:195], v[194:195], v[196:197]
	v_add_f32_e32 v180, 1.0, v180
	v_rcp_f32_e32 v203, v180
	v_add_f32_e32 v180, 1.0, v202
	v_rcp_f32_e32 v202, v180
	v_cmp_lt_i32_e32 vcc, v223, v185
	s_waitcnt vmcnt(10)
	v_mov_b64_e32 v[214:215], v[130:131]
	s_waitcnt vmcnt(7)
	v_mov_b64_e32 v[210:211], v[136:137]
	v_pk_mul_f32 v[196:197], v[198:199], v[202:203]
	v_mov_b64_e32 v[216:217], v[134:135]
	v_cvt_pk_bf16_f32 v196, v196, v197
	v_cvt_pk_bf16_f32 v197, v194, v195
	global_store_dwordx2 v[200:201], v[196:197], off nt
	s_waitcnt vmcnt(7)
	v_mov_b64_e32 v[212:213], v[142:143]
	v_mov_b64_e32 v[206:207], v[132:133]
	s_waitcnt vmcnt(6)
	v_mov_b64_e32 v[208:209], v[144:145]
	s_waitcnt vmcnt(3)
	v_mov_b64_e32 v[200:201], v[146:147]
	v_mov_b64_e32 v[202:203], v[140:141]
	v_mov_b64_e32 v[204:205], v[138:139]
	v_mov_b64_e32 v[230:231], v[128:129]
	v_mov_b64_e32 v[232:233], v[124:125]
	v_mov_b64_e32 v[234:235], v[126:127]
	v_mov_b64_e32 v[194:195], v[122:123]
	v_mov_b64_e32 v[218:219], v[118:119]
	v_mov_b64_e32 v[224:225], v[120:121]
	s_and_saveexec_b64 s[26:27], vcc
	s_cbranch_execz .LBB0_626
	v_add_u32_e32 v180, 3, v187
	v_mov_b32_e32 v224, v186
	v_cmp_lt_i32_e32 vcc, v180, v185
	v_mov_b64_e32 v[204:205], v[138:139]
	v_mov_b64_e32 v[202:203], v[140:141]
	v_mov_b64_e32 v[200:201], v[146:147]
	v_mov_b64_e32 v[208:209], v[144:145]
	v_mov_b64_e32 v[206:207], v[132:133]
	v_mov_b64_e32 v[212:213], v[142:143]
	v_mov_b64_e32 v[216:217], v[134:135]
	v_mov_b64_e32 v[210:211], v[136:137]
	v_mov_b64_e32 v[214:215], v[130:131]
	s_and_saveexec_b64 s[8:9], vcc
	s_cbranch_execz .LBB0_644
	v_subrev_u32_e32 v180, 60, v187
	v_med3_i32 v180, v180, 0, v253
	v_max_i32_e32 v198, -3, v223
	v_mov_b32_e32 v196, v186
	v_mul_u32_u24_e32 v180, 0xe00, v180
	v_add_u32_e32 v198, 3, v198
	v_lshl_add_u64 v[194:195], v[180:181], 1, s[20:21]
	v_lshlrev_b32_e32 v180, 3, v196
	v_min_u32_e32 v198, 0x87ff, v198
	v_and_b32_e32 v180, 0x1f8, v180
	v_mul_u32_u24_e32 v198, 0xe00, v198
	v_lshl_add_u64 v[194:195], v[194:195], 0, v[180:181]
	s_mov_b64 s[0:1], 0x1200
	v_lshlrev_b32_e32 v198, 1, v198
	v_mov_b32_e32 v199, v181
	v_lshl_add_u64 v[196:197], v[194:195], 0, s[0:1]
	v_add_co_u32_e32 v194, vcc, 0x1000, v194
	v_lshl_add_u64 v[198:199], s[20:21], 0, v[198:199]
	s_nop 0
	v_addc_co_u32_e32 v195, vcc, 0, v195, vcc
	v_lshl_add_u64 v[198:199], v[198:199], 0, v[180:181]
	v_lshl_add_u64 v[212:213], v[198:199], 0, s[0:1]
	global_load_dwordx2 v[200:201], v[194:195], off offset:512
	global_load_dwordx2 v[202:203], v[196:197], off offset:512
	global_load_dwordx2 v[206:207], v[212:213], off offset:512
	global_load_dwordx2 v[204:205], v[196:197], off offset:1024
	v_max_i32_e32 v196, 0xffffffbc, v187
	v_add_u32_e32 v196, 0x44, v196
	v_min_u32_e32 v196, 0x87ff, v196
	v_mul_u32_u24_e32 v196, 0xe00, v196
	v_lshlrev_b32_e32 v196, 1, v196
	v_mov_b32_e32 v197, v181
	v_add_co_u32_e32 v194, vcc, s83, v198
	v_lshl_add_u64 v[196:197], s[20:21], 0, v[196:197]
	s_nop 0
	v_addc_co_u32_e32 v195, vcc, 0, v199, vcc
	v_lshl_add_u64 v[196:197], v[196:197], 0, v[180:181]
	v_lshl_add_u64 v[198:199], v[196:197], 0, s[0:1]
	global_load_dwordx2 v[208:209], v[194:195], off offset:512
	global_load_dwordx2 v[210:211], v[198:199], off offset:512
	global_load_dwordx2 v[214:215], v[198:199], off offset:1024
	s_nop 0
	global_load_dwordx2 v[212:213], v[212:213], off offset:1024
	v_add_co_u32_e32 v194, vcc, 0x1000, v196
	s_nop 1
	v_addc_co_u32_e32 v195, vcc, 0, v197, vcc
	global_load_dwordx2 v[216:217], v[194:195], off offset:512

.LBB0_648:
	s_or_b64 exec, exec, s[8:9]
	v_lshlrev_b32_e32 v188, 16, v197
	v_and_b32_e32 v189, 0xffff0000, v197
	v_pk_fma_f32 v[188:189], v[10:11], v[188:189], v[198:199]
	v_lshlrev_b32_e32 v192, 16, v196
	v_mul_f32_e32 v180, 0xbfb8aa3b, v189
	v_exp_f32_e32 v180, v180
	v_mul_f32_e32 v190, 0xbfb8aa3b, v188
	v_exp_f32_e32 v190, v190
	v_and_b32_e32 v193, 0xffff0000, v196
	v_add_f32_e32 v180, 1.0, v180
	v_pk_fma_f32 v[192:193], v[8:9], v[192:193], v[194:195]
	v_rcp_f32_e32 v191, v180
	v_add_f32_e32 v180, 1.0, v190
	v_mul_f32_e32 v190, 0xbfb8aa3b, v193
	v_exp_f32_e32 v194, v190
	v_mul_f32_e32 v190, 0xbfb8aa3b, v192
	v_exp_f32_e32 v196, v190
	v_rcp_f32_e32 v190, v180
	v_add_f32_e32 v180, 1.0, v194
	v_rcp_f32_e32 v195, v180
	v_add_f32_e32 v180, 1.0, v196
	v_rcp_f32_e32 v194, v180
	v_pk_mul_f32 v[188:189], v[188:189], v[190:191]
	s_movk_i32 s0, 0x600
	v_pk_mul_f32 v[190:191], v[192:193], v[194:195]
	v_mov_b32_e32 v192, v188
	v_mov_b32_e32 v193, v190
	v_pk_mul_f32 v[192:193], v[192:193], v[192:193]
	v_mov_b32_e32 v194, v189
	v_mov_b32_e32 v195, v191
	v_pk_fma_f32 v[192:193], v[194:195], v[194:195], v[192:193]
	s_nop 0
	v_add_f32_e32 v180, v192, v193
	s_nop 1
	v_add_f32_dpp v180, v180, v180 quad_perm:[1,0,3,2] row_mask:0xf bank_mask:0xf bound_ctrl:1
	s_nop 1
	v_add_f32_dpp v180, v180, v180 quad_perm:[2,3,0,1] row_mask:0xf bank_mask:0xf bound_ctrl:1
	s_nop 1
	v_add_f32_dpp v180, v180, v180 row_half_mirror row_mask:0xf bank_mask:0xf bound_ctrl:1
	s_nop 1
	v_add_f32_dpp v180, v180, v180 row_mirror row_mask:0xf bank_mask:0xf bound_ctrl:1
	v_add_f32_e32 v180, 0x358637bd, v180
	v_rsq_f32_e32 v180, v180
	s_nop 0
	v_mul_f32_e32 v180, 0x3e000000, v180
	v_pk_mul_f32 v[188:189], v[188:189], v[180:181] op_sel_hi:[1,0]
	v_pk_mul_f32 v[190:191], v[190:191], v[180:181] op_sel_hi:[1,0]
	v_lshlrev_b32_e32 v180, 3, v224
	v_cvt_pk_bf16_f32 v190, v190, v191
	v_cvt_pk_bf16_f32 v191, v188, v189
	v_mov_b64_e32 v[188:189], s[22:23]
	v_mad_i64_i32 v[188:189], s[0:1], v223, s0, v[188:189]
	v_and_b32_e32 v180, 0x1f8, v180
	v_lshl_add_u64 v[188:189], v[188:189], 0, v[180:181]
	global_store_dwordx2 v[188:189], v[190:191], off nt
	s_and_saveexec_b64 s[0:1], s[28:29]
	s_xor_b64 s[30:31], exec, s[0:1]
	s_cbranch_execz .LBB0_650
	v_cmp_le_u32_e64 s[10:11], v218, v187
	s_and_b64 s[0:1], vcc, s[10:11]
	v_cmp_le_u32_e64 s[12:13], v221, v220
	s_and_b64 s[8:9], s[0:1], s[12:13]
	v_cndmask_b32_e64 v179, 0, v179, s[8:9]
	v_cmp_eq_u32_e64 s[14:15], 0, v218
	v_cmp_lt_u32_e64 s[16:17], v221, v220
	v_cndmask_b32_e64 v178, 0, v178, s[8:9]
	v_cndmask_b32_e64 v180, v179, 0, s[14:15]
	s_and_b64 s[8:9], s[10:11], s[16:17]
	v_lshlrev_b32_e32 v192, 16, v180
	v_and_b32_e32 v193, 0xffff0000, v180
	v_cndmask_b32_e64 v180, 0, v114, s[8:9]
	v_cndmask_b32_e64 v190, 0, v115, s[8:9]
	v_cmp_le_u32_e64 s[8:9], v222, v220
	s_and_b64 s[10:11], s[10:11], s[8:9]
	v_cndmask_b32_e64 v194, v190, 0, s[14:15]
	v_cndmask_b32_e64 v190, 0, v140, s[10:11]
	v_cndmask_b32_e64 v191, 0, v141, s[10:11]
	v_cmp_lt_u32_e64 s[10:11], v218, v187
	s_and_b64 s[0:1], vcc, s[10:11]
	v_cndmask_b32_e64 v179, v178, 0, s[14:15]
	v_cndmask_b32_e64 v180, v180, 0, s[14:15]
	v_cndmask_b32_e64 v195, v191, 0, s[14:15]
	v_cndmask_b32_e64 v190, v190, 0, s[14:15]
	s_and_b64 s[14:15], s[0:1], s[12:13]
	v_cndmask_b32_e64 v196, 0, v177, s[14:15]
	v_cndmask_b32_e64 v191, 0, v176, s[14:15]
	s_and_b64 s[14:15], s[10:11], s[16:17]
	s_and_b64 s[10:11], s[10:11], s[8:9]
	v_cndmask_b32_e64 v199, 0, v133, s[10:11]
	v_cndmask_b32_e64 v223, 0, v132, s[10:11]
	v_cmp_le_u32_e64 s[10:11], v219, v187
	s_and_b64 s[0:1], vcc, s[10:11]
	v_lshlrev_b32_e32 v178, 16, v179
	v_and_b32_e32 v179, 0xffff0000, v179
	s_and_b64 s[12:13], s[0:1], s[12:13]
	v_cndmask_b32_e64 v224, 0, v175, s[12:13]
	v_cndmask_b32_e64 v225, 0, v174, s[12:13]
	v_pk_fma_f32 v[174:175], v[100:101], v[178:179], 0 op_sel_hi:[1,1,0]
	v_lshlrev_b32_e32 v176, 16, v180
	v_and_b32_e32 v177, 0xffff0000, v180
	v_pk_fma_f32 v[174:175], v[88:89], v[176:177], v[174:175]
	v_lshlrev_b32_e32 v176, 16, v190
	v_and_b32_e32 v177, 0xffff0000, v190
	v_cndmask_b32_e64 v198, 0, v118, s[14:15]
	v_pk_fma_f32 v[174:175], v[104:105], v[176:177], v[174:175]
	v_lshlrev_b32_e32 v176, 16, v191
	v_and_b32_e32 v177, 0xffff0000, v191
	v_pk_fma_f32 v[174:175], v[60:61], v[176:177], v[174:175]
	v_lshlrev_b32_e32 v176, 16, v198
	v_and_b32_e32 v177, 0xffff0000, v198
	s_and_b64 s[12:13], s[10:11], s[16:17]
	v_pk_fma_f32 v[174:175], v[48:49], v[176:177], v[174:175]
	v_lshlrev_b32_e32 v176, 16, v223
	v_and_b32_e32 v177, 0xffff0000, v223
	v_cndmask_b32_e64 v227, 0, v124, s[12:13]
	v_pk_fma_f32 v[174:175], v[40:41], v[176:177], v[174:175]
	v_lshlrev_b32_e32 v176, 16, v225
	v_and_b32_e32 v177, 0xffff0000, v225
	v_pk_fma_f32 v[174:175], v[52:53], v[176:177], v[174:175]
	v_lshlrev_b32_e32 v176, 16, v227
	v_and_b32_e32 v177, 0xffff0000, v227
	v_pk_fma_f32 v[190:191], v[12:13], v[176:177], v[174:175]
	v_pk_fma_f32 v[174:175], v[102:103], v[192:193], 0 op_sel_hi:[1,1,0]
	v_lshlrev_b32_e32 v176, 16, v194
	v_and_b32_e32 v177, 0xffff0000, v194
	v_pk_fma_f32 v[174:175], v[90:91], v[176:177], v[174:175]
	v_lshlrev_b32_e32 v176, 16, v195
	v_and_b32_e32 v177, 0xffff0000, v195
	v_cndmask_b32_e64 v197, 0, v119, s[14:15]
	v_pk_fma_f32 v[174:175], v[106:107], v[176:177], v[174:175]
	v_lshlrev_b32_e32 v176, 16, v196
	v_and_b32_e32 v177, 0xffff0000, v196
	v_pk_fma_f32 v[174:175], v[62:63], v[176:177], v[174:175]
	v_lshlrev_b32_e32 v176, 16, v197
	v_and_b32_e32 v177, 0xffff0000, v197
	v_pk_fma_f32 v[174:175], v[50:51], v[176:177], v[174:175]
	v_lshlrev_b32_e32 v176, 16, v199
	v_and_b32_e32 v177, 0xffff0000, v199
	v_cndmask_b32_e64 v226, 0, v125, s[12:13]
	v_pk_fma_f32 v[174:175], v[42:43], v[176:177], v[174:175]
	v_lshlrev_b32_e32 v176, 16, v224
	v_and_b32_e32 v177, 0xffff0000, v224
	v_pk_fma_f32 v[174:175], v[54:55], v[176:177], v[174:175]
	v_lshlrev_b32_e32 v176, 16, v226
	v_and_b32_e32 v177, 0xffff0000, v226
	s_and_b64 s[8:9], s[10:11], s[8:9]
	v_pk_fma_f32 v[194:195], v[14:15], v[176:177], v[174:175]
	v_cndmask_b32_e64 v193, 0, v137, s[8:9]
	v_cndmask_b32_e64 v192, 0, v136, s[8:9]

.LBB0_652:
	s_or_b64 exec, exec, s[8:9]
	v_lshlrev_b32_e32 v174, 16, v193
	v_and_b32_e32 v175, 0xffff0000, v193
	v_pk_fma_f32 v[174:175], v[6:7], v[174:175], v[194:195]
	v_and_b32_e32 v179, 0xffff0000, v192
	v_mul_f32_e32 v176, 0xbfb8aa3b, v175
	v_exp_f32_e32 v176, v176
	v_mul_f32_e32 v177, 0xbfb8aa3b, v174
	v_exp_f32_e32 v178, v177
	v_add_f32_e32 v176, 1.0, v176
	v_rcp_f32_e32 v177, v176
	v_add_f32_e32 v176, 1.0, v178
	v_lshlrev_b32_e32 v178, 16, v192
	v_pk_fma_f32 v[178:179], v[4:5], v[178:179], v[190:191]
	v_rcp_f32_e32 v176, v176
	v_mul_f32_e32 v180, 0xbfb8aa3b, v179
	v_exp_f32_e32 v180, v180
	v_mul_f32_e32 v190, 0xbfb8aa3b, v178
	v_exp_f32_e32 v190, v190
	v_pk_mul_f32 v[174:175], v[174:175], v[176:177]
	v_add_f32_e32 v180, 1.0, v180
	v_rcp_f32_e32 v191, v180
	v_add_f32_e32 v180, 1.0, v190
	v_rcp_f32_e32 v190, v180
	s_nop 0
	v_pk_mul_f32 v[176:177], v[178:179], v[190:191]
	v_mov_b32_e32 v178, v174
	v_mov_b32_e32 v179, v176
	v_pk_mul_f32 v[178:179], v[178:179], v[178:179]
	v_mov_b32_e32 v190, v175
	v_mov_b32_e32 v191, v177
	v_pk_fma_f32 v[178:179], v[190:191], v[190:191], v[178:179]
	s_nop 0
	v_add_f32_e32 v178, v178, v179
	s_nop 1
	v_add_f32_dpp v178, v178, v178 quad_perm:[1,0,3,2] row_mask:0xf bank_mask:0xf bound_ctrl:1
	s_nop 1
	v_add_f32_dpp v178, v178, v178 quad_perm:[2,3,0,1] row_mask:0xf bank_mask:0xf bound_ctrl:1
	s_nop 1
	v_add_f32_dpp v178, v178, v178 row_half_mirror row_mask:0xf bank_mask:0xf bound_ctrl:1
	s_nop 1
	v_add_f32_dpp v178, v178, v178 row_mirror row_mask:0xf bank_mask:0xf bound_ctrl:1
	v_add_f32_e32 v178, 0x358637bd, v178
	v_rsq_f32_e32 v178, v178
	s_nop 0
	v_pk_mul_f32 v[174:175], v[174:175], v[178:179] op_sel_hi:[1,0]
	v_pk_mul_f32 v[176:177], v[176:177], v[178:179] op_sel_hi:[1,0]
	s_nop 0
	v_cvt_pk_bf16_f32 v176, v176, v177
	v_cvt_pk_bf16_f32 v177, v174, v175
	global_store_dwordx2 v[188:189], v[176:177], off offset:512 nt
	s_and_saveexec_b64 s[0:1], s[28:29]
	s_xor_b64 s[28:29], exec, s[0:1]
	s_cbranch_execz .LBB0_654
	v_cmp_le_u32_e64 s[10:11], v218, v187
	s_and_b64 s[0:1], vcc, s[10:11]
	v_cmp_le_u32_e64 s[12:13], v221, v220
	s_and_b64 s[8:9], s[0:1], s[12:13]
	v_cndmask_b32_e64 v155, 0, v155, s[8:9]
	v_cmp_eq_u32_e64 s[14:15], 0, v218
	v_cmp_lt_u32_e64 s[16:17], v221, v220
	v_cndmask_b32_e64 v154, 0, v154, s[8:9]
	v_cndmask_b32_e64 v174, v155, 0, s[14:15]
	s_and_b64 s[8:9], s[10:11], s[16:17]
	v_lshlrev_b32_e32 v176, 16, v174
	v_and_b32_e32 v177, 0xffff0000, v174
	v_cndmask_b32_e64 v174, 0, v116, s[8:9]
	v_cndmask_b32_e64 v175, 0, v117, s[8:9]
	v_cmp_le_u32_e64 s[8:9], v222, v220
	s_and_b64 s[10:11], s[10:11], s[8:9]
	v_cndmask_b32_e64 v178, v175, 0, s[14:15]
	v_cndmask_b32_e64 v175, 0, v138, s[10:11]
	v_cndmask_b32_e64 v179, 0, v139, s[10:11]
	v_cmp_lt_u32_e64 s[10:11], v218, v187
	s_and_b64 s[0:1], vcc, s[10:11]
	v_cndmask_b32_e64 v155, v154, 0, s[14:15]
	v_cndmask_b32_e64 v174, v174, 0, s[14:15]
	v_cndmask_b32_e64 v179, v179, 0, s[14:15]
	v_cndmask_b32_e64 v175, v175, 0, s[14:15]
	s_and_b64 s[14:15], s[0:1], s[12:13]
	v_cndmask_b32_e64 v180, 0, v151, s[14:15]
	v_cndmask_b32_e64 v190, 0, v150, s[14:15]
	s_and_b64 s[14:15], s[10:11], s[16:17]
	s_and_b64 s[10:11], s[10:11], s[8:9]
	v_cndmask_b32_e64 v193, 0, v143, s[10:11]
	v_cndmask_b32_e64 v194, 0, v142, s[10:11]
	v_cmp_le_u32_e64 s[10:11], v219, v187
	s_and_b64 s[0:1], vcc, s[10:11]
	v_lshlrev_b32_e32 v154, 16, v155
	v_and_b32_e32 v155, 0xffff0000, v155
	s_and_b64 vcc, s[0:1], s[12:13]
	v_cndmask_b32_e32 v187, 0, v149, vcc
	v_cndmask_b32_e32 v195, 0, v148, vcc
	v_pk_fma_f32 v[148:149], v[96:97], v[154:155], 0 op_sel_hi:[1,1,0]
	v_lshlrev_b32_e32 v150, 16, v174
	v_and_b32_e32 v151, 0xffff0000, v174
	v_pk_fma_f32 v[148:149], v[80:81], v[150:151], v[148:149]
	v_lshlrev_b32_e32 v150, 16, v175
	v_and_b32_e32 v151, 0xffff0000, v175
	v_cndmask_b32_e64 v192, 0, v122, s[14:15]
	v_pk_fma_f32 v[148:149], v[72:73], v[150:151], v[148:149]
	v_lshlrev_b32_e32 v150, 16, v190
	v_and_b32_e32 v151, 0xffff0000, v190
	v_pk_fma_f32 v[148:149], v[84:85], v[150:151], v[148:149]
	v_lshlrev_b32_e32 v150, 16, v192
	v_and_b32_e32 v151, 0xffff0000, v192
	s_and_b64 vcc, s[10:11], s[16:17]
	v_pk_fma_f32 v[148:149], v[44:45], v[150:151], v[148:149]
	v_lshlrev_b32_e32 v150, 16, v194
	v_and_b32_e32 v151, 0xffff0000, v194
	v_cndmask_b32_e32 v197, 0, v128, vcc
	v_pk_fma_f32 v[148:149], v[32:33], v[150:151], v[148:149]
	v_lshlrev_b32_e32 v150, 16, v195
	v_and_b32_e32 v151, 0xffff0000, v195
	v_pk_fma_f32 v[148:149], v[24:25], v[150:151], v[148:149]
	v_lshlrev_b32_e32 v150, 16, v197
	v_and_b32_e32 v151, 0xffff0000, v197
	v_pk_fma_f32 v[174:175], v[36:37], v[150:151], v[148:149]
	v_pk_fma_f32 v[148:149], v[98:99], v[176:177], 0 op_sel_hi:[1,1,0]
	v_lshlrev_b32_e32 v150, 16, v178
	v_and_b32_e32 v151, 0xffff0000, v178
	v_pk_fma_f32 v[148:149], v[82:83], v[150:151], v[148:149]
	v_lshlrev_b32_e32 v150, 16, v179
	v_and_b32_e32 v151, 0xffff0000, v179
	v_cndmask_b32_e64 v191, 0, v123, s[14:15]
	v_pk_fma_f32 v[148:149], v[74:75], v[150:151], v[148:149]
	v_lshlrev_b32_e32 v150, 16, v180
	v_and_b32_e32 v151, 0xffff0000, v180
	v_pk_fma_f32 v[148:149], v[86:87], v[150:151], v[148:149]
	v_lshlrev_b32_e32 v150, 16, v191
	v_and_b32_e32 v151, 0xffff0000, v191
	v_pk_fma_f32 v[148:149], v[46:47], v[150:151], v[148:149]
	v_lshlrev_b32_e32 v150, 16, v193
	v_and_b32_e32 v151, 0xffff0000, v193
	v_cndmask_b32_e32 v196, 0, v129, vcc
	v_pk_fma_f32 v[148:149], v[34:35], v[150:151], v[148:149]
	v_lshlrev_b32_e32 v150, 16, v187
	v_and_b32_e32 v151, 0xffff0000, v187
	v_pk_fma_f32 v[148:149], v[26:27], v[150:151], v[148:149]
	v_lshlrev_b32_e32 v150, 16, v196
	v_and_b32_e32 v151, 0xffff0000, v196
	s_and_b64 vcc, s[10:11], s[8:9]
	v_pk_fma_f32 v[178:179], v[38:39], v[150:151], v[148:149]
	v_cndmask_b32_e32 v177, 0, v131, vcc
	v_cndmask_b32_e32 v176, 0, v130, vcc

.LBB0_936:
	s_or_b64 exec, exec, s[6:7]
	v_mul_f32_e32 v16, v10, v10
	v_fmamk_f32 v17, v16, 0xb94c1982, v240
	v_fmaak_f32 v17, v16, v17, 0xbe2aaa9d
	v_mul_f32_e32 v17, v16, v17
	v_fmac_f32_e32 v10, v10, v17
	v_fmamk_f32 v17, v16, 0x37d75334, v241
	v_fmaak_f32 v17, v16, v17, 0x3d2aabf7
	v_fmaak_f32 v17, v16, v17, 0xbf000004
	v_fma_f32 v16, v16, v17, 1.0
	v_lshlrev_b32_e32 v17, 30, v11
	v_and_b32_e32 v11, 1, v11
	v_cmp_eq_u32_e32 vcc, 0, v11
	v_xor_b32_e32 v9, v9, v8
	s_brev_b32 s0, 1
	v_cndmask_b32_e32 v11, v16, v10, vcc
	v_xor_b32_e32 v10, 0x80000000, v10
	v_cndmask_b32_e32 v10, v10, v16, vcc
	v_and_b32_e32 v18, 0x80000000, v17
	v_xor_b32_e32 v9, v9, v11
	v_bitop3_b32 v10, v10, v17, s0 bitop3:0x78
	s_movk_i32 s0, 0x1f8
	v_xor_b32_e32 v9, v9, v18
	v_cmp_class_f32_e64 vcc, v8, s0
	v_add_u32_e32 v7, s20, v7
	s_mov_b32 s0, 0x21fff
	v_cndmask_b32_e32 v8, v242, v10, vcc
	v_cndmask_b32_e32 v9, v242, v9, vcc
	v_cmp_lt_i32_e32 vcc, s0, v7
	global_store_dwordx2 v[4:5], v[8:9], off nt
	s_or_b64 s[16:17], vcc, s[16:17]
	v_lshl_add_u64 v[4:5], v[4:5], 0, s[14:15]
	s_andn2_b64 exec, exec, s[16:17]
	s_cbranch_execz .LBB0_941

.LBB0_946:
	s_or_b64 exec, exec, s[6:7]
	s_waitcnt vmcnt(0)
	v_mul_f32_e32 v8, v20, v8
	v_mul_f32_e32 v11, 0x3fb8aa3b, v8
	s_mov_b32 s2, 0x3fb8aa3b
	v_fma_f32 v15, v8, s2, -v11
	v_rndne_f32_e32 v23, v11
	v_fmac_f32_e32 v15, 0x32a5705f, v8
	v_sub_f32_e32 v11, v11, v23
	v_add_f32_e32 v11, v11, v15
	v_exp_f32_e32 v11, v11
	v_cvt_i32_f32_e32 v15, v23
	s_mov_b32 s6, 0xc2ce8ed0
	v_cmp_ngt_f32_e32 vcc, s6, v8
	s_mov_b32 s7, 0x42b17218
	v_ldexp_f32 v11, v11, v15
	v_cndmask_b32_e32 v11, 0, v11, vcc
	v_cmp_nlt_f32_e32 vcc, s7, v8
	v_xor_b32_e32 v7, v7, v6
	s_brev_b32 s1, 1
	v_cndmask_b32_e32 v8, v249, v11, vcc
	v_mul_f32_e32 v11, v9, v9
	v_fmamk_f32 v15, v11, 0xb94c1982, v240
	v_fmaak_f32 v15, v11, v15, 0xbe2aaa9d
	v_mul_f32_e32 v15, v11, v15
	v_fmac_f32_e32 v9, v9, v15
	v_fmamk_f32 v15, v11, 0x37d75334, v241
	v_fmaak_f32 v15, v11, v15, 0x3d2aabf7
	v_fmaak_f32 v15, v11, v15, 0xbf000004
	v_fma_f32 v11, v11, v15, 1.0
	v_lshlrev_b32_e32 v15, 30, v10
	v_and_b32_e32 v10, 1, v10
	v_cmp_eq_u32_e32 vcc, 0, v10
	v_and_b32_e32 v23, 0x80000000, v15
	v_lshl_or_b32 v4, v5, 4, v4
	v_cndmask_b32_e32 v10, v11, v9, vcc
	v_xor_b32_e32 v9, 0x80000000, v9
	v_cndmask_b32_e32 v9, v9, v11, vcc
	v_xor_b32_e32 v7, v7, v10
	v_bitop3_b32 v9, v9, v15, s1 bitop3:0x78
	s_movk_i32 s1, 0x1f8
	v_xor_b32_e32 v7, v7, v23
	v_cmp_class_f32_e64 vcc, v6, s1
	v_ashrrev_i32_e32 v5, 31, v4
	v_lshlrev_b64 v[4:5], 12, v[4:5]
	v_cndmask_b32_e32 v7, v242, v7, vcc
	v_cndmask_b32_e32 v9, v242, v9, vcc
	v_mul_f32_e32 v49, v8, v7
	v_mul_f32_e32 v6, v8, v9
	v_mov_b32_e32 v7, v49
	global_store_dwordx2 v[16:17], v[6:7], off offset:-128 nt
	s_load_dwordx2 s[4:5], s[80:81], 0xa0
	v_fma_f32 v48, v8, v9, -1.0
	v_and_b32_e32 v6, 0x3f0, v22
	v_pk_mul_f32 v[8:9], v[20:21], v[48:49]
	v_lshl_or_b32 v4, v6, 2, v4
	v_add_f32_e32 v15, v8, v9
	v_lshl_add_u64 v[8:9], s[18:19], 0, v[4:5]
	s_waitcnt lgkmcnt(0)
	v_lshl_add_u64 v[44:45], s[4:5], 0, v[4:5]
	global_load_dwordx4 v[4:7], v[8:9], off offset:48
	global_load_dwordx4 v[24:27], v[8:9], off offset:32
	global_load_dwordx4 v[28:31], v[8:9], off offset:16
	global_load_dwordx4 v[32:35], v[8:9], off
	s_nop 0
	global_load_dwordx4 v[8:11], v[44:45], off offset:48
	global_load_dwordx4 v[36:39], v[44:45], off offset:32
	global_load_dwordx4 v[40:43], v[44:45], off offset:16
	s_nop 0
	global_load_dwordx4 v[44:47], v[44:45], off
	v_mov_b32_e32 v50, v21
	v_mov_b32_e32 v52, v48
	v_mov_b32_e32 v53, v21
	v_mov_b32_e32 v48, v49
	v_mov_b32_e32 v49, v20
	v_pk_mul_f32 v[50:51], v[50:51], v[52:53] op_sel_hi:[0,1]
	v_pk_mul_f32 v[20:21], v[20:21], v[48:49] op_sel_hi:[0,1]
	v_add_f32_e32 v21, v21, v51
	v_div_scale_f32 v23, s[4:5], v21, v21, v15
	v_rcp_f32_e32 v48, v23
	v_add_u32_e32 v14, s20, v14
	s_movk_i32 s1, 0xfff
	v_fma_f32 v49, -v23, v48, 1.0
	v_fmac_f32_e32 v48, v49, v48
	v_div_scale_f32 v49, vcc, v15, v21, v15
	v_mul_f32_e32 v51, v49, v48
	v_fma_f32 v52, -v23, v51, v49
	v_fmac_f32_e32 v51, v52, v48
	v_fma_f32 v23, -v23, v51, v49
	v_div_fmas_f32 v23, v23, v48, v51
	v_div_fixup_f32 v52, v23, v21, v15
	v_sub_f32_e32 v15, v20, v50
	v_div_scale_f32 v20, s[4:5], v21, v21, v15
	v_rcp_f32_e32 v23, v20
	v_add_u32_e32 v22, s0, v22
	v_lshl_add_u64 v[18:19], v[18:19], 0, s[26:27]
	v_fma_f32 v48, -v20, v23, 1.0
	v_fmac_f32_e32 v23, v48, v23
	v_div_scale_f32 v48, vcc, v15, v21, v15
	v_mul_f32_e32 v49, v48, v23
	v_fma_f32 v50, -v20, v49, v48
	v_fmac_f32_e32 v49, v50, v23
	v_fma_f32 v20, -v20, v49, v48
	v_div_fmas_f32 v20, v20, v23, v49
	v_div_fixup_f32 v20, v20, v21, v15
	v_cmp_lt_i32_e32 vcc, s1, v14
	s_or_b64 s[28:29], vcc, s[28:29]
	s_waitcnt vmcnt(0)
	v_pk_mul_f32 v[48:49], v[44:45], v[20:21] op_sel_hi:[1,0]
	s_nop 0
	v_pk_fma_f32 v[48:49], v[32:33], v[52:53], v[48:49] op_sel_hi:[1,0,1] neg_lo:[0,0,1] neg_hi:[0,0,1]
	v_pk_mul_f32 v[32:33], v[32:33], v[20:21] op_sel_hi:[1,0]
	s_nop 0
	v_pk_fma_f32 v[32:33], v[44:45], v[52:53], v[32:33] op_sel_hi:[1,0,1]
	v_pk_mul_f32 v[44:45], v[46:47], v[20:21] op_sel_hi:[1,0]
	s_nop 0
	v_pk_fma_f32 v[50:51], v[34:35], v[52:53], v[44:45] op_sel_hi:[1,0,1] neg_lo:[0,0,1] neg_hi:[0,0,1]
	v_pk_mul_f32 v[34:35], v[34:35], v[20:21] op_sel_hi:[1,0]
	global_store_dwordx4 v[16:17], v[48:51], off offset:-120
	v_pk_fma_f32 v[34:35], v[46:47], v[52:53], v[34:35] op_sel_hi:[1,0,1]
	global_store_dwordx4 v[16:17], v[32:35], off offset:-56
	s_nop 1
	v_pk_mul_f32 v[32:33], v[40:41], v[20:21] op_sel_hi:[1,0]
	v_pk_mul_f32 v[34:35], v[42:43], v[20:21] op_sel_hi:[1,0]
	v_pk_fma_f32 v[32:33], v[28:29], v[52:53], v[32:33] op_sel_hi:[1,0,1] neg_lo:[0,0,1] neg_hi:[0,0,1]
	v_pk_mul_f32 v[28:29], v[28:29], v[20:21] op_sel_hi:[1,0]
	v_pk_fma_f32 v[34:35], v[30:31], v[52:53], v[34:35] op_sel_hi:[1,0,1] neg_lo:[0,0,1] neg_hi:[0,0,1]
	v_pk_mul_f32 v[30:31], v[30:31], v[20:21] op_sel_hi:[1,0]
	v_pk_fma_f32 v[28:29], v[40:41], v[52:53], v[28:29] op_sel_hi:[1,0,1]
	v_pk_fma_f32 v[30:31], v[42:43], v[52:53], v[30:31] op_sel_hi:[1,0,1]
	global_store_dwordx4 v[16:17], v[28:31], off offset:-40
	global_store_dwordx4 v[16:17], v[32:35], off offset:-104
	s_nop 0
	v_pk_mul_f32 v[28:29], v[36:37], v[20:21] op_sel_hi:[1,0]
	v_pk_mul_f32 v[30:31], v[38:39], v[20:21] op_sel_hi:[1,0]
	v_pk_fma_f32 v[28:29], v[24:25], v[52:53], v[28:29] op_sel_hi:[1,0,1] neg_lo:[0,0,1] neg_hi:[0,0,1]
	v_pk_mul_f32 v[24:25], v[24:25], v[20:21] op_sel_hi:[1,0]
	v_pk_fma_f32 v[30:31], v[26:27], v[52:53], v[30:31] op_sel_hi:[1,0,1] neg_lo:[0,0,1] neg_hi:[0,0,1]
	v_pk_mul_f32 v[26:27], v[26:27], v[20:21] op_sel_hi:[1,0]
	v_pk_fma_f32 v[24:25], v[36:37], v[52:53], v[24:25] op_sel_hi:[1,0,1]
	v_pk_fma_f32 v[26:27], v[38:39], v[52:53], v[26:27] op_sel_hi:[1,0,1]
	global_store_dwordx4 v[16:17], v[24:27], off offset:-24
	global_store_dwordx4 v[16:17], v[28:31], off offset:-88
	s_nop 0
	v_pk_mul_f32 v[24:25], v[8:9], v[20:21] op_sel_hi:[1,0]
	s_nop 0
	v_pk_fma_f32 v[24:25], v[4:5], v[52:53], v[24:25] op_sel_hi:[1,0,1] neg_lo:[0,0,1] neg_hi:[0,0,1]
	v_pk_mul_f32 v[4:5], v[4:5], v[20:21] op_sel_hi:[1,0]
	s_nop 0
	v_pk_fma_f32 v[4:5], v[8:9], v[52:53], v[4:5] op_sel_hi:[1,0,1]
	v_pk_mul_f32 v[8:9], v[10:11], v[20:21] op_sel_hi:[1,0]
	s_nop 0
	v_pk_fma_f32 v[26:27], v[6:7], v[52:53], v[8:9] op_sel_hi:[1,0,1] neg_lo:[0,0,1] neg_hi:[0,0,1]
	v_pk_mul_f32 v[6:7], v[6:7], v[20:21] op_sel_hi:[1,0]
	global_store_dwordx4 v[16:17], v[24:27], off offset:-72
	v_pk_fma_f32 v[6:7], v[10:11], v[52:53], v[6:7] op_sel_hi:[1,0,1]
	global_store_dwordx4 v[16:17], v[4:7], off offset:-8
	v_lshl_add_u64 v[16:17], v[16:17], 0, s[24:25]
	s_andn2_b64 exec, exec, s[28:29]
	s_cbranch_execz .LBB0_951

.LBB0_978:
	s_or_b64 exec, exec, s[10:11]
	v_pk_mul_f32 v[76:77], v[70:71], v[70:71]
	v_pk_mul_f32 v[78:79], v[68:69], v[68:69]
	v_pk_mul_f32 v[62:63], v[62:63], v[62:63]
	v_pk_mov_b32 v[122:123], v[78:79], v[76:77] op_sel:[1,0]
	v_mov_b32_e32 v79, v77
	v_pk_mul_f32 v[60:61], v[60:61], v[60:61]
	v_pk_add_f32 v[76:77], v[122:123], v[78:79]
	v_pk_mov_b32 v[78:79], v[60:61], v[62:63] op_sel:[1,0]
	v_mov_b32_e32 v61, v63
	v_pk_add_f32 v[60:61], v[78:79], v[60:61]
	v_pk_add_f32 v[76:77], v[76:77], v[76:77] op_sel_hi:[0,1]
	v_pk_add_f32 v[60:61], v[60:61], v[60:61] op_sel_hi:[0,1]
	v_mul_f32_e32 v60, v84, v84
	v_pk_fma_f32 v[62:63], v[84:85], v[84:85], v[60:61] op_sel_hi:[1,1,0]
	v_mul_f32_e32 v60, v86, v86
	v_pk_fma_f32 v[78:79], v[86:87], v[86:87], v[60:61] op_sel_hi:[1,1,0]
	v_mul_f32_e32 v62, v52, v52
	v_mul_f32_e32 v78, v53, v53
	v_mul_f32_e32 v60, v54, v54
	v_mul_f32_e32 v76, v55, v55
	v_pk_add_f32 v[62:63], v[62:63], v[78:79]
	v_pk_add_f32 v[60:61], v[60:61], v[76:77]
	v_lshlrev_b32_e32 v180, 3, v114
	v_pk_add_f32 v[60:61], v[62:63], v[60:61]
	v_lshl_add_u64 v[78:79], s[86:87], 0, v[110:111]
	v_add_f32_e32 v60, v60, v61
	v_mov_b32_e32 v61, v181
	v_mov_b32_e32 v126, v120
	v_add_f32_dpp v60, v60, v60 row_shr:1 row_mask:0xf bank_mask:0xf bound_ctrl:1
	s_nop 1
	v_add_f32_dpp v60, v60, v60 row_shr:2 row_mask:0xf bank_mask:0xf bound_ctrl:1
	s_nop 1
	v_add_f32_dpp v60, v60, v60 row_shr:4 row_mask:0xf bank_mask:0xf bound_ctrl:1
	s_nop 1
	v_add_f32_dpp v60, v60, v60 row_shr:8 row_mask:0xf bank_mask:0xf bound_ctrl:1
	s_nop 1
	v_mov_b32_dpp v61, v60 row_bcast:15 row_mask:0xa bank_mask:0xf
	v_add_f32_e32 v60, v60, v61
	v_mov_b32_e32 v61, v181
	s_nop 1
	v_mov_b32_dpp v61, v60 row_bcast:31 row_mask:0xc bank_mask:0xf
	v_add_f32_e32 v60, v60, v61
	s_nop 0
	v_readlane_b32 s0, v60, 63
	s_nop 1
	v_fma_f32 v60, s0, v247, v237
	v_rsq_f32_e32 v76, v60
	s_nop 0
	v_pk_mul_f32 v[60:61], v[68:69], v[76:77] op_sel_hi:[1,0]
	v_pk_mul_f32 v[62:63], v[70:71], v[76:77] op_sel_hi:[1,0]
	s_waitcnt lgkmcnt(0)
	v_pk_fma_f32 v[60:61], v[72:73], v[60:61], v[80:81]
	v_pk_fma_f32 v[62:63], v[74:75], v[62:63], v[82:83]
	v_cvt_pk_bf16_f32 v60, v60, v61
	v_cvt_pk_bf16_f32 v61, v62, v63
	v_lshl_add_u64 v[62:63], v[78:79], 0, v[180:181]
	global_store_dwordx2 v[62:63], v[60:61], off nt
	v_lshl_add_u32 v60, v112, 4, v124
	v_pk_mul_f32 v[80:81], v[64:65], v[76:77] op_sel_hi:[1,0]
	v_pk_mul_f32 v[82:83], v[66:67], v[76:77] op_sel_hi:[1,0]
	ds_read_b128 v[60:63], v60 offset:40960
	ds_read_b128 v[64:67], v121 offset:46080
	v_lshl_add_u32 v68, v116, 4, v124
	v_lshl_add_u32 v72, v118, 4, v124
	ds_read_b128 v[68:71], v68 offset:40960
	ds_read_b128 v[72:75], v72 offset:40960
	s_waitcnt lgkmcnt(2)
	v_pk_fma_f32 v[62:63], v[62:63], v[82:83], v[66:67]
	v_pk_fma_f32 v[60:61], v[60:61], v[80:81], v[64:65]
	v_cvt_pk_bf16_f32 v65, v62, v63
	v_cvt_pk_bf16_f32 v64, v60, v61
	v_lshl_add_u64 v[66:67], v[112:113], 3, v[78:79]
	ds_read_b128 v[60:63], v121 offset:47104
	global_store_dwordx2 v[66:67], v[64:65], off nt
	v_pk_mul_f32 v[64:65], v[56:57], v[76:77] op_sel_hi:[1,0]
	v_pk_mul_f32 v[66:67], v[58:59], v[76:77] op_sel_hi:[1,0]
	ds_read_b128 v[56:59], v121 offset:48128
	v_pk_mul_f32 v[52:53], v[52:53], v[76:77] op_sel_hi:[1,0]
	v_pk_mul_f32 v[54:55], v[54:55], v[76:77] op_sel_hi:[1,0]
	s_waitcnt lgkmcnt(1)
	v_pk_fma_f32 v[62:63], v[70:71], v[66:67], v[62:63]
	v_pk_fma_f32 v[60:61], v[68:69], v[64:65], v[60:61]
	s_waitcnt lgkmcnt(0)
	v_pk_fma_f32 v[54:55], v[54:55], v[74:75], v[58:59]
	v_pk_fma_f32 v[52:53], v[52:53], v[72:73], v[56:57]
	v_cvt_pk_bf16_f32 v60, v60, v61
	v_cvt_pk_bf16_f32 v61, v62, v63
	v_lshl_add_u64 v[62:63], v[116:117], 3, v[78:79]
	v_cvt_pk_bf16_f32 v52, v52, v53
	v_cvt_pk_bf16_f32 v53, v54, v55
	v_lshl_add_u64 v[54:55], v[118:119], 3, v[78:79]
	global_store_dwordx2 v[62:63], v[60:61], off nt
	global_store_dwordx2 v[54:55], v[52:53], off nt

.LBB0_988:
	s_or_b64 exec, exec, s[12:13]
	v_pk_mul_f32 v[116:117], v[58:59], v[58:59]
	v_pk_mul_f32 v[118:119], v[56:57], v[56:57]
	v_mul_f32_e32 v81, v64, v64
	v_pk_mov_b32 v[120:121], v[118:119], v[116:117] op_sel:[1,0]
	v_mov_b32_e32 v119, v117
	v_pk_add_f32 v[116:117], v[120:121], v[118:119]
	v_pk_mul_f32 v[118:119], v[54:55], v[54:55]
	v_pk_mul_f32 v[120:121], v[52:53], v[52:53]
	v_pk_add_f32 v[116:117], v[116:117], v[116:117] op_sel:[0,1] op_sel_hi:[1,0]
	v_pk_mov_b32 v[122:123], v[120:121], v[118:119] op_sel:[1,0]
	v_mov_b32_e32 v121, v119
	v_pk_add_f32 v[118:119], v[122:123], v[120:121]
	v_mul_f32_e32 v120, v65, v65
	v_pk_add_f32 v[118:119], v[118:119], v[118:119] op_sel:[0,1] op_sel_hi:[1,0]
	v_mov_b32_e32 v117, v81
	v_mov_b32_e32 v119, v120
	v_pk_add_f32 v[116:117], v[116:117], v[118:119]
	v_mul_f32_e32 v118, v61, v61
	v_mul_f32_e32 v121, v66, v66
	v_pk_fma_f32 v[118:119], v[60:61], v[60:61], v[118:119] op_sel_hi:[1,1,0]
	v_mul_f32_e32 v120, v63, v63
	v_mul_f32_e32 v122, v67, v67
	v_mov_b32_e32 v119, v121
	v_pk_fma_f32 v[120:121], v[62:63], v[62:63], v[120:121] op_sel_hi:[1,1,0]
	v_lshlrev_b32_e32 v180, 3, v80
	v_mov_b32_e32 v121, v122
	v_pk_add_f32 v[118:119], v[118:119], v[120:121]
	s_nop 0
	v_pk_add_f32 v[116:117], v[116:117], v[118:119]
	s_nop 0
	v_add_f32_e32 v81, v116, v117
	v_mov_b32_e32 v116, v181
	s_nop 0
	v_add_f32_dpp v81, v81, v81 row_shr:1 row_mask:0xf bank_mask:0xf bound_ctrl:1
	s_nop 1
	v_add_f32_dpp v81, v81, v81 row_shr:2 row_mask:0xf bank_mask:0xf bound_ctrl:1
	s_nop 1
	v_add_f32_dpp v81, v81, v81 row_shr:4 row_mask:0xf bank_mask:0xf bound_ctrl:1
	s_nop 1
	v_add_f32_dpp v81, v81, v81 row_shr:8 row_mask:0xf bank_mask:0xf bound_ctrl:1
	s_nop 1
	v_mov_b32_dpp v116, v81 row_bcast:15 row_mask:0xa bank_mask:0xf
	v_add_f32_e32 v81, v81, v116
	v_mov_b32_e32 v116, v181
	s_nop 1
	v_mov_b32_dpp v116, v81 row_bcast:31 row_mask:0xc bank_mask:0xf
	v_add_f32_e32 v81, v81, v116
	s_nop 0
	v_readlane_b32 s0, v81, 63
	s_nop 1
	v_fma_f32 v81, s0, v247, v237
	v_rsq_f32_e32 v116, v81
	s_nop 0
	v_pk_mul_f32 v[56:57], v[56:57], v[116:117] op_sel_hi:[1,0]
	v_pk_mul_f32 v[58:59], v[58:59], v[116:117] op_sel_hi:[1,0]
	s_waitcnt lgkmcnt(1)
	v_pk_fma_f32 v[56:57], v[68:69], v[56:57], v[72:73]
	v_pk_fma_f32 v[58:59], v[70:71], v[58:59], v[74:75]
	v_lshl_add_u64 v[68:69], s[86:87], 0, v[104:105]
	v_cvt_pk_bf16_f32 v56, v56, v57
	v_cvt_pk_bf16_f32 v57, v58, v59
	v_lshl_add_u64 v[58:59], v[68:69], 0, v[180:181]
	global_store_dwordx2 v[58:59], v[56:57], off nt
	v_lshl_add_u32 v56, v82, 4, v124
	ds_read_b128 v[56:59], v56 offset:40960
	v_pk_mul_f32 v[70:71], v[52:53], v[116:117] op_sel_hi:[1,0]
	v_pk_mul_f32 v[72:73], v[54:55], v[116:117] op_sel_hi:[1,0]
	v_lshl_add_u32 v52, v84, 4, v124
	ds_read_b128 v[52:55], v52 offset:40960
	s_waitcnt lgkmcnt(1)
	v_pk_fma_f32 v[58:59], v[58:59], v[72:73], v[78:79]
	v_pk_fma_f32 v[56:57], v[56:57], v[70:71], v[76:77]
	v_pk_mul_f32 v[70:71], v[60:61], v[116:117] op_sel_hi:[1,0]
	v_cvt_pk_bf16_f32 v56, v56, v57
	v_cvt_pk_bf16_f32 v57, v58, v59
	v_lshl_add_u64 v[58:59], v[82:83], 3, v[68:69]
	global_store_dwordx2 v[58:59], v[56:57], off nt
	ds_read_b128 v[56:59], v114 offset:47104
	v_pk_mul_f32 v[72:73], v[62:63], v[116:117] op_sel_hi:[1,0]
	v_lshl_add_u32 v60, v86, 4, v124
	ds_read_b128 v[60:63], v60 offset:40960
	s_waitcnt lgkmcnt(1)
	v_pk_fma_f32 v[54:55], v[54:55], v[72:73], v[58:59]
	v_pk_fma_f32 v[52:53], v[52:53], v[70:71], v[56:57]
	v_cvt_pk_bf16_f32 v57, v54, v55
	v_cvt_pk_bf16_f32 v56, v52, v53
	ds_read_b128 v[52:55], v114 offset:48128
	v_lshl_add_u64 v[58:59], v[84:85], 3, v[68:69]
	global_store_dwordx2 v[58:59], v[56:57], off nt
	v_pk_mul_f32 v[56:57], v[64:65], v[116:117] op_sel_hi:[1,0]
	v_pk_mul_f32 v[58:59], v[66:67], v[116:117] op_sel_hi:[1,0]
	s_waitcnt lgkmcnt(0)
	v_pk_fma_f32 v[52:53], v[56:57], v[60:61], v[52:53]
	v_pk_fma_f32 v[54:55], v[58:59], v[62:63], v[54:55]
	v_cvt_pk_bf16_f32 v52, v52, v53
	v_cvt_pk_bf16_f32 v53, v54, v55
	v_lshl_add_u64 v[54:55], v[86:87], 3, v[68:69]
	global_store_dwordx2 v[54:55], v[52:53], off nt
	v_add_u32_e32 v52, 3, v112
	v_cmp_lt_i32_e32 vcc, v52, v89
	s_and_saveexec_b64 s[12:13], vcc
	s_cbranch_execz .LBB0_990
	v_mov_b32_e32 v4, v186
	s_movk_i32 s0, 0x7fd
	v_and_b32_e32 v8, 63, v4
	v_add_u32_e32 v6, 0xfffff803, v112
	v_lshl_add_u64 v[4:5], v[102:103], 0, s[88:89]
	v_cmp_gt_i32_e32 vcc, s0, v112
	v_mov_b32_e32 v7, s31
	v_mov_b32_e32 v9, s30
	v_cndmask_b32_e32 v4, v6, v4, vcc
	v_mov_b32_e32 v6, s37
	v_cndmask_b32_e32 v5, 0, v5, vcc
	v_cndmask_b32_e32 v7, v6, v7, vcc
	v_mov_b32_e32 v6, s36
	v_lshlrev_b64 v[4:5], 12, v[4:5]
	v_cndmask_b32_e32 v6, v6, v9, vcc
	v_lshl_add_u64 v[4:5], v[6:7], 0, v[4:5]
	v_lshlrev_b32_e32 v180, 4, v8
	v_lshl_add_u64 v[16:17], v[4:5], 0, v[180:181]
	global_load_dwordx4 v[4:7], v[16:17], off
	global_load_dwordx4 v[8:11], v[16:17], off offset:1024
	global_load_dwordx4 v[12:15], v[16:17], off offset:2048
	s_nop 0
	global_load_dwordx4 v[16:19], v[16:17], off offset:3072

.LBB0_997:
	s_or_b64 exec, exec, s[12:13]
	v_pk_mul_f32 v[76:77], v[70:71], v[70:71]
	v_pk_mul_f32 v[78:79], v[68:69], v[68:69]
	v_pk_mul_f32 v[62:63], v[62:63], v[62:63]
	v_pk_mov_b32 v[130:131], v[78:79], v[76:77] op_sel:[1,0]
	v_mov_b32_e32 v79, v77
	v_pk_mul_f32 v[60:61], v[60:61], v[60:61]
	v_pk_add_f32 v[76:77], v[130:131], v[78:79]
	v_pk_mov_b32 v[78:79], v[60:61], v[62:63] op_sel:[1,0]
	v_mov_b32_e32 v61, v63
	v_pk_add_f32 v[60:61], v[78:79], v[60:61]
	v_pk_add_f32 v[76:77], v[76:77], v[76:77] op_sel_hi:[0,1]
	v_pk_add_f32 v[60:61], v[60:61], v[60:61] op_sel_hi:[0,1]
	v_mul_f32_e32 v60, v84, v84
	v_pk_fma_f32 v[62:63], v[84:85], v[84:85], v[60:61] op_sel_hi:[1,1,0]
	v_mul_f32_e32 v60, v86, v86
	v_pk_fma_f32 v[78:79], v[86:87], v[86:87], v[60:61] op_sel_hi:[1,1,0]
	v_mul_f32_e32 v62, v52, v52
	v_mul_f32_e32 v78, v53, v53
	v_mul_f32_e32 v60, v54, v54
	v_mul_f32_e32 v76, v55, v55
	v_pk_add_f32 v[62:63], v[62:63], v[78:79]
	v_pk_add_f32 v[60:61], v[60:61], v[76:77]
	v_lshlrev_b32_e32 v180, 3, v114
	v_pk_add_f32 v[60:61], v[62:63], v[60:61]
	v_mov_b32_e32 v126, v127
	v_add_f32_e32 v60, v60, v61
	v_mov_b32_e32 v61, v181
	s_nop 0
	v_add_f32_dpp v60, v60, v60 row_shr:1 row_mask:0xf bank_mask:0xf bound_ctrl:1
	s_nop 1
	v_add_f32_dpp v60, v60, v60 row_shr:2 row_mask:0xf bank_mask:0xf bound_ctrl:1
	s_nop 1
	v_add_f32_dpp v60, v60, v60 row_shr:4 row_mask:0xf bank_mask:0xf bound_ctrl:1
	s_nop 1
	v_add_f32_dpp v60, v60, v60 row_shr:8 row_mask:0xf bank_mask:0xf bound_ctrl:1
	s_nop 1
	v_mov_b32_dpp v61, v60 row_bcast:15 row_mask:0xa bank_mask:0xf
	v_add_f32_e32 v60, v60, v61
	v_mov_b32_e32 v61, v181
	s_nop 1
	v_mov_b32_dpp v61, v60 row_bcast:31 row_mask:0xc bank_mask:0xf
	v_add_f32_e32 v60, v60, v61
	s_nop 0
	v_readlane_b32 s0, v60, 63
	s_nop 1
	v_fma_f32 v60, s0, v247, v237
	v_rsq_f32_e32 v76, v60
	v_lshlrev_b64 v[60:61], 11, v[116:117]
	v_lshl_add_u64 v[78:79], s[26:27], 0, v[60:61]
	v_lshl_add_u64 v[60:61], v[78:79], 0, v[180:181]
	v_pk_mul_f32 v[62:63], v[68:69], v[76:77] op_sel_hi:[1,0]
	v_pk_mul_f32 v[68:69], v[70:71], v[76:77] op_sel_hi:[1,0]
	s_waitcnt lgkmcnt(0)
	v_pk_fma_f32 v[62:63], v[72:73], v[62:63], v[80:81]
	v_pk_fma_f32 v[68:69], v[74:75], v[68:69], v[82:83]
	v_cvt_pk_bf16_f32 v62, v62, v63
	v_cvt_pk_bf16_f32 v63, v68, v69
	global_store_dwordx2 v[60:61], v[62:63], off nt
	v_lshl_add_u32 v60, v118, 4, v124
	v_pk_mul_f32 v[80:81], v[64:65], v[76:77] op_sel_hi:[1,0]
	v_pk_mul_f32 v[82:83], v[66:67], v[76:77] op_sel_hi:[1,0]
	ds_read_b128 v[60:63], v60 offset:40960
	ds_read_b128 v[64:67], v128 offset:46080
	v_lshl_add_u32 v68, v120, 4, v124
	v_lshl_add_u32 v72, v122, 4, v124
	ds_read_b128 v[68:71], v68 offset:40960
	ds_read_b128 v[72:75], v72 offset:40960
	s_waitcnt lgkmcnt(2)
	v_pk_fma_f32 v[62:63], v[62:63], v[82:83], v[66:67]
	v_pk_fma_f32 v[60:61], v[60:61], v[80:81], v[64:65]
	v_cvt_pk_bf16_f32 v65, v62, v63
	v_cvt_pk_bf16_f32 v64, v60, v61
	v_lshl_add_u64 v[66:67], v[118:119], 3, v[78:79]
	ds_read_b128 v[60:63], v128 offset:47104
	global_store_dwordx2 v[66:67], v[64:65], off nt
	v_pk_mul_f32 v[64:65], v[56:57], v[76:77] op_sel_hi:[1,0]
	v_pk_mul_f32 v[66:67], v[58:59], v[76:77] op_sel_hi:[1,0]
	ds_read_b128 v[56:59], v128 offset:48128
	v_pk_mul_f32 v[52:53], v[52:53], v[76:77] op_sel_hi:[1,0]
	v_pk_mul_f32 v[54:55], v[54:55], v[76:77] op_sel_hi:[1,0]
	s_waitcnt lgkmcnt(1)
	v_pk_fma_f32 v[62:63], v[70:71], v[66:67], v[62:63]
	v_pk_fma_f32 v[60:61], v[68:69], v[64:65], v[60:61]
	s_waitcnt lgkmcnt(0)
	v_pk_fma_f32 v[54:55], v[54:55], v[74:75], v[58:59]
	v_pk_fma_f32 v[52:53], v[52:53], v[72:73], v[56:57]
	v_cvt_pk_bf16_f32 v60, v60, v61
	v_cvt_pk_bf16_f32 v61, v62, v63
	v_lshl_add_u64 v[62:63], v[120:121], 3, v[78:79]
	v_cvt_pk_bf16_f32 v52, v52, v53
	v_cvt_pk_bf16_f32 v53, v54, v55
	v_lshl_add_u64 v[54:55], v[122:123], 3, v[78:79]
	global_store_dwordx2 v[62:63], v[60:61], off nt
	global_store_dwordx2 v[54:55], v[52:53], off nt

.LBB0_1015:
	s_or_b64 exec, exec, s[12:13]
	v_pk_mul_f32 v[62:63], v[52:53], v[52:53]
	v_pk_mul_f32 v[64:65], v[50:51], v[50:51]
	v_lshlrev_b32_e32 v180, 3, v54
	v_pk_mov_b32 v[68:69], v[64:65], v[62:63] op_sel:[1,0]
	v_mov_b32_e32 v65, v63
	v_pk_add_f32 v[62:63], v[68:69], v[64:65]
	v_pk_mul_f32 v[64:65], v[46:47], v[46:47]
	v_pk_add_f32 v[62:63], v[62:63], v[62:63] op_sel_hi:[0,1]
	v_pk_mul_f32 v[68:69], v[48:49], v[48:49]
	v_mul_f32_e32 v62, v42, v42
	v_pk_mov_b32 v[70:71], v[68:69], v[64:65] op_sel:[1,0]
	v_mov_b32_e32 v69, v65
	v_pk_add_f32 v[64:65], v[70:71], v[68:69]
	v_pk_fma_f32 v[68:69], v[42:43], v[42:43], v[62:63] op_sel_hi:[1,1,0]
	v_mul_f32_e32 v62, v44, v44
	v_pk_add_f32 v[64:65], v[64:65], v[64:65] op_sel_hi:[0,1]
	v_pk_fma_f32 v[70:71], v[44:45], v[44:45], v[62:63] op_sel_hi:[1,1,0]
	v_mul_f32_e32 v68, v38, v38
	v_mul_f32_e32 v70, v39, v39
	v_mul_f32_e32 v62, v40, v40
	v_mul_f32_e32 v64, v41, v41
	v_pk_add_f32 v[68:69], v[68:69], v[70:71]
	v_pk_add_f32 v[62:63], v[62:63], v[64:65]
	v_lshl_add_u64 v[64:65], s[40:41], 0, v[96:97]
	v_pk_add_f32 v[62:63], v[68:69], v[62:63]
	v_mov_b32_e32 v67, v55
	v_add_f32_e32 v62, v62, v63
	v_mov_b32_e32 v63, v181
	s_nop 0
	v_add_f32_dpp v62, v62, v62 row_shr:1 row_mask:0xf bank_mask:0xf bound_ctrl:1
	s_nop 1
	v_add_f32_dpp v62, v62, v62 row_shr:2 row_mask:0xf bank_mask:0xf bound_ctrl:1
	s_nop 1
	v_add_f32_dpp v62, v62, v62 row_shr:4 row_mask:0xf bank_mask:0xf bound_ctrl:1
	s_nop 1
	v_add_f32_dpp v62, v62, v62 row_shr:8 row_mask:0xf bank_mask:0xf bound_ctrl:1
	s_nop 1
	v_mov_b32_dpp v63, v62 row_bcast:15 row_mask:0xa bank_mask:0xf
	v_add_f32_e32 v62, v62, v63
	v_mov_b32_e32 v63, v181
	s_nop 1
	v_mov_b32_dpp v63, v62 row_bcast:31 row_mask:0xc bank_mask:0xf
	v_add_f32_e32 v62, v62, v63
	s_nop 0
	v_readlane_b32 s0, v62, 63
	s_nop 1
	v_fma_f32 v62, s0, v247, v237
	v_rsq_f32_e32 v62, v62
	s_nop 0
	v_pk_mul_f32 v[50:51], v[62:63], v[50:51] op_sel_hi:[0,1]
	v_pk_mul_f32 v[52:53], v[62:63], v[52:53] op_sel_hi:[0,1]
	s_waitcnt lgkmcnt(0)
	v_pk_fma_f32 v[6:7], v[6:7], v[52:53], v[10:11]
	v_pk_fma_f32 v[4:5], v[4:5], v[50:51], v[8:9]
	v_pk_mul_f32 v[68:69], v[48:49], v[62:63] op_sel_hi:[1,0]
	v_cvt_pk_bf16_f32 v4, v4, v5
	v_cvt_pk_bf16_f32 v5, v6, v7
	v_lshl_add_u64 v[6:7], v[64:65], 0, v[180:181]
	global_store_dwordx2 v[6:7], v[4:5], off nt
	v_lshl_add_u32 v4, v56, 4, v124
	ds_read_b128 v[4:7], v4 offset:40960
	ds_read_b128 v[8:11], v57 offset:46080
	v_pk_mul_f32 v[70:71], v[46:47], v[62:63] op_sel_hi:[1,0]
	v_lshl_add_u32 v46, v36, 4, v124
	ds_read_b128 v[46:49], v46 offset:40960
	v_lshl_add_u32 v50, v58, 4, v124
	s_waitcnt lgkmcnt(1)
	v_pk_fma_f32 v[6:7], v[6:7], v[70:71], v[10:11]
	v_pk_fma_f32 v[4:5], v[4:5], v[68:69], v[8:9]
	v_cvt_pk_bf16_f32 v9, v6, v7
	v_cvt_pk_bf16_f32 v8, v4, v5
	ds_read_b128 v[4:7], v57 offset:47104
	v_lshl_add_u64 v[10:11], v[60:61], 3, v[64:65]
	ds_read_b128 v[50:53], v50 offset:40960
	global_store_dwordx2 v[10:11], v[8:9], off nt
	ds_read_b128 v[8:11], v57 offset:48128
	v_pk_mul_f32 v[42:43], v[42:43], v[62:63] op_sel_hi:[1,0]
	v_pk_mul_f32 v[44:45], v[44:45], v[62:63] op_sel_hi:[1,0]
	s_waitcnt lgkmcnt(2)
	v_pk_fma_f32 v[4:5], v[46:47], v[42:43], v[4:5]
	v_pk_fma_f32 v[6:7], v[48:49], v[44:45], v[6:7]
	v_cvt_pk_bf16_f32 v4, v4, v5
	v_cvt_pk_bf16_f32 v5, v6, v7
	v_lshl_add_u64 v[6:7], v[36:37], 3, v[64:65]
	global_store_dwordx2 v[6:7], v[4:5], off nt
	v_pk_mul_f32 v[4:5], v[38:39], v[62:63] op_sel_hi:[1,0]
	v_pk_mul_f32 v[6:7], v[40:41], v[62:63] op_sel_hi:[1,0]
	s_waitcnt lgkmcnt(0)
	v_pk_fma_f32 v[4:5], v[4:5], v[50:51], v[8:9]
	v_pk_fma_f32 v[6:7], v[6:7], v[52:53], v[10:11]
	v_cvt_pk_bf16_f32 v4, v4, v5
	v_cvt_pk_bf16_f32 v5, v6, v7
	v_lshl_add_u64 v[6:7], v[58:59], 3, v[64:65]
	global_store_dwordx2 v[6:7], v[4:5], off nt

.LBB0_1023:
	s_or_b64 exec, exec, s[10:11]
	s_waitcnt vmcnt(1)
	v_and_b32_e32 v51, 0xffff0000, v13
	v_and_b32_e32 v50, 0xffff0000, v12
	v_and_b32_e32 v55, 0xffff0000, v15
	v_and_b32_e32 v54, 0xffff0000, v14
	v_lshlrev_b32_e32 v49, 16, v13
	v_lshlrev_b32_e32 v48, 16, v12
	v_lshlrev_b32_e32 v53, 16, v15
	v_lshlrev_b32_e32 v52, 16, v14
	s_waitcnt vmcnt(0)
	v_lshlrev_b32_e32 v58, 16, v16
	v_and_b32_e32 v59, 0xffff0000, v16
	v_lshlrev_b32_e32 v60, 16, v17
	v_lshlrev_b32_e32 v62, 16, v18
	v_pk_mul_f32 v[68:69], v[50:51], v[50:51]
	v_pk_mul_f32 v[70:71], v[54:55], v[54:55]
	v_and_b32_e32 v61, 0xffff0000, v17
	v_pk_fma_f32 v[68:69], v[48:49], v[48:49], v[68:69]
	v_pk_fma_f32 v[70:71], v[52:53], v[52:53], v[70:71]
	v_mul_f32_e32 v63, v58, v58
	v_mul_f32_e32 v73, v59, v59
	v_mul_f32_e32 v56, v60, v60
	v_mov_b32_e32 v72, v62
	v_and_b32_e32 v66, 0xffff0000, v18
	v_lshlrev_b32_e32 v64, 16, v19
	v_and_b32_e32 v65, 0xffff0000, v19
	v_pk_add_f32 v[68:69], v[68:69], v[68:69] op_sel_hi:[0,1]
	v_pk_add_f32 v[70:71], v[70:71], v[70:71] op_sel_hi:[0,1]
	v_pk_fma_f32 v[74:75], v[60:61], v[60:61], v[56:57] op_sel_hi:[1,1,0]
	v_pk_add_f32 v[72:73], v[62:63], v[72:73]
	v_mul_f32_e32 v74, v66, v66
	v_mul_f32_e32 v70, v64, v64
	v_mul_f32_e32 v68, v65, v65
	v_mul_f32_e32 v76, v62, v62
	v_mov_b32_e32 v77, v73
	v_pk_add_f32 v[72:73], v[76:77], v[74:75]
	v_pk_add_f32 v[68:69], v[70:71], v[68:69]
	v_mov_b32_e32 v43, 0
	v_pk_add_f32 v[68:69], v[72:73], v[68:69]
	v_lshlrev_b32_e32 v180, 3, v38
	v_add_f32_e32 v39, v68, v69
	v_mov_b32_e32 v68, v48
	v_mov_b32_e32 v69, v50
	v_add_f32_dpp v39, v39, v39 row_shr:1 row_mask:0xf bank_mask:0xf bound_ctrl:1
	v_mov_b32_e32 v50, v49
	v_mov_b32_e32 v63, v66
	v_add_f32_dpp v39, v39, v39 row_shr:2 row_mask:0xf bank_mask:0xf bound_ctrl:1
	v_add_u32_e32 v66, 3, v57
	v_cmp_lt_i32_e64 s[12:13], v66, v125
	v_add_f32_dpp v39, v39, v39 row_shr:4 row_mask:0xf bank_mask:0xf bound_ctrl:1
	v_cmp_ge_i32_e64 s[10:11], v66, v125
	s_nop 0
	v_add_f32_dpp v39, v39, v39 row_shr:8 row_mask:0xf bank_mask:0xf bound_ctrl:1
	s_nop 1
	v_mov_b32_dpp v43, v39 row_bcast:15 row_mask:0xa bank_mask:0xf
	v_add_f32_e32 v39, v39, v43
	v_mov_b32_e32 v43, 0
	s_nop 1
	v_mov_b32_dpp v43, v39 row_bcast:31 row_mask:0xc bank_mask:0xf
	v_add_f32_e32 v39, v39, v43
	s_nop 0
	v_readlane_b32 s0, v39, 63
	s_nop 1
	v_fma_f32 v39, s0, v247, v237
	v_rsq_f32_e32 v56, v39
	v_lshl_add_u64 v[38:39], s[40:41], 0, v[94:95]
	v_pk_mul_f32 v[68:69], v[56:57], v[68:69] op_sel_hi:[0,1]
	v_pk_mul_f32 v[48:49], v[56:57], v[50:51] op_sel_hi:[0,1]
	s_waitcnt lgkmcnt(0)
	v_pk_fma_f32 v[6:7], v[6:7], v[48:49], v[10:11]
	v_pk_fma_f32 v[4:5], v[4:5], v[68:69], v[8:9]
	s_nop 0
	v_cvt_pk_bf16_f32 v4, v4, v5
	v_cvt_pk_bf16_f32 v5, v6, v7
	v_lshl_add_u64 v[6:7], v[38:39], 0, v[180:181]
	global_store_dwordx2 v[6:7], v[4:5], off nt
	v_mov_b32_e32 v4, v52
	v_mov_b32_e32 v5, v54
	v_pk_mul_f32 v[68:69], v[56:57], v[4:5] op_sel_hi:[0,1]
	v_lshl_add_u32 v4, v42, 4, v124
	ds_read_b128 v[4:7], v4 offset:40960
	ds_read_b128 v[8:11], v37 offset:46080
	v_mov_b32_e32 v54, v53
	v_pk_mul_f32 v[70:71], v[56:57], v[54:55] op_sel_hi:[0,1]
	v_lshl_add_u32 v42, v40, 4, v124
	ds_read_b128 v[48:51], v42 offset:40960
	s_waitcnt lgkmcnt(1)
	v_pk_fma_f32 v[6:7], v[6:7], v[70:71], v[10:11]
	v_pk_fma_f32 v[4:5], v[4:5], v[68:69], v[8:9]
	v_cvt_pk_bf16_f32 v9, v6, v7
	v_cvt_pk_bf16_f32 v8, v4, v5
	ds_read_b128 v[4:7], v37 offset:47104
	v_lshl_add_u32 v42, v44, 4, v124
	v_lshl_add_u64 v[10:11], v[46:47], 3, v[38:39]
	ds_read_b128 v[52:55], v42 offset:40960
	global_store_dwordx2 v[10:11], v[8:9], off nt
	ds_read_b128 v[8:11], v37 offset:48128
	v_pk_mul_f32 v[42:43], v[56:57], v[58:59] op_sel_hi:[0,1]
	v_pk_mul_f32 v[46:47], v[56:57], v[60:61] op_sel_hi:[0,1]
	s_waitcnt lgkmcnt(2)
	v_pk_fma_f32 v[6:7], v[50:51], v[46:47], v[6:7]
	v_pk_fma_f32 v[4:5], v[48:49], v[42:43], v[4:5]
	s_nop 0
	v_cvt_pk_bf16_f32 v4, v4, v5
	v_cvt_pk_bf16_f32 v5, v6, v7
	v_lshl_add_u64 v[6:7], v[40:41], 3, v[38:39]
	global_store_dwordx2 v[6:7], v[4:5], off nt
	v_pk_mul_f32 v[4:5], v[56:57], v[62:63] op_sel_hi:[0,1]
	v_pk_mul_f32 v[6:7], v[56:57], v[64:65] op_sel_hi:[0,1]
	s_waitcnt lgkmcnt(0)
	v_pk_fma_f32 v[6:7], v[6:7], v[54:55], v[10:11]
	v_pk_fma_f32 v[4:5], v[4:5], v[52:53], v[8:9]
	s_nop 0
	v_cvt_pk_bf16_f32 v4, v4, v5
	v_cvt_pk_bf16_f32 v5, v6, v7
	v_lshl_add_u64 v[6:7], v[44:45], 3, v[38:39]
	global_store_dwordx2 v[6:7], v[4:5], off nt
	s_and_saveexec_b64 s[4:5], s[12:13]
	s_cbranch_execz .LBB0_1025
	v_mov_b32_e32 v4, v186
	s_nop 0
	v_and_b32_e32 v6, 63, v4
	v_add_u32_e32 v4, 0xfffff803, v57
	v_ashrrev_i32_e32 v5, 31, v4
	v_lshlrev_b64 v[4:5], 12, v[4:5]
	v_lshl_add_u64 v[4:5], s[30:31], 0, v[4:5]
	v_lshlrev_b32_e32 v180, 3, v6
	v_lshl_add_u64 v[4:5], v[4:5], 0, v[180:181]
	global_load_dwordx2 v[12:13], v[4:5], off
	global_load_dwordx2 v[14:15], v[4:5], off offset:512
	global_load_dwordx2 v[16:17], v[4:5], off offset:1024
	global_load_dwordx2 v[18:19], v[4:5], off offset:1536

.LBB0_1030:
	s_or_b64 exec, exec, s[12:13]
	v_pk_mul_f32 v[68:69], v[54:55], v[54:55]
	v_pk_mul_f32 v[70:71], v[52:53], v[52:53]
	v_mov_b32_e32 v67, v181
	v_pk_mov_b32 v[72:73], v[70:71], v[68:69] op_sel:[1,0]
	v_mov_b32_e32 v71, v69
	v_pk_add_f32 v[68:69], v[72:73], v[70:71]
	v_pk_mul_f32 v[70:71], v[46:47], v[46:47]
	v_pk_add_f32 v[68:69], v[68:69], v[68:69] op_sel_hi:[0,1]
	v_pk_mul_f32 v[72:73], v[48:49], v[48:49]
	v_mul_f32_e32 v68, v42, v42
	v_pk_mov_b32 v[74:75], v[72:73], v[70:71] op_sel:[1,0]
	v_mov_b32_e32 v73, v71
	v_pk_add_f32 v[70:71], v[74:75], v[72:73]
	v_pk_fma_f32 v[72:73], v[42:43], v[42:43], v[68:69] op_sel_hi:[1,1,0]
	v_mul_f32_e32 v68, v44, v44
	v_pk_add_f32 v[70:71], v[70:71], v[70:71] op_sel_hi:[0,1]
	v_pk_fma_f32 v[74:75], v[44:45], v[44:45], v[68:69] op_sel_hi:[1,1,0]
	v_mul_f32_e32 v72, v38, v38
	v_mul_f32_e32 v74, v39, v39
	v_mul_f32_e32 v68, v40, v40
	v_mul_f32_e32 v70, v41, v41
	v_pk_add_f32 v[72:73], v[72:73], v[74:75]
	v_pk_add_f32 v[68:69], v[68:69], v[70:71]
	v_lshlrev_b32_e32 v180, 3, v56
	v_pk_add_f32 v[68:69], v[72:73], v[68:69]
	s_nop 0
	v_add_f32_e32 v51, v68, v69
	s_nop 1
	v_add_f32_dpp v51, v51, v51 row_shr:1 row_mask:0xf bank_mask:0xf bound_ctrl:1
	s_nop 1
	v_add_f32_dpp v51, v51, v51 row_shr:2 row_mask:0xf bank_mask:0xf bound_ctrl:1
	s_nop 1
	v_add_f32_dpp v51, v51, v51 row_shr:4 row_mask:0xf bank_mask:0xf bound_ctrl:1
	s_nop 1
	v_add_f32_dpp v51, v51, v51 row_shr:8 row_mask:0xf bank_mask:0xf bound_ctrl:1
	s_nop 1
	v_mov_b32_dpp v67, v51 row_bcast:15 row_mask:0xa bank_mask:0xf
	v_add_f32_e32 v51, v51, v67
	v_mov_b32_e32 v67, v181
	s_nop 1
	v_mov_b32_dpp v67, v51 row_bcast:31 row_mask:0xc bank_mask:0xf
	v_add_f32_e32 v51, v51, v67
	v_mov_b32_e32 v67, v37
	v_readlane_b32 s0, v51, 63
	s_nop 1
	v_fma_f32 v51, s0, v247, v237
	v_rsq_f32_e32 v68, v51
	v_ashrrev_i32_e32 v51, 31, v50
	v_lshlrev_b64 v[50:51], 11, v[50:51]
	v_pk_mul_f32 v[52:53], v[68:69], v[52:53] op_sel_hi:[0,1]
	v_pk_mul_f32 v[54:55], v[68:69], v[54:55] op_sel_hi:[0,1]
	s_waitcnt lgkmcnt(0)
	v_pk_fma_f32 v[6:7], v[6:7], v[54:55], v[10:11]
	v_pk_fma_f32 v[4:5], v[4:5], v[52:53], v[8:9]
	v_lshl_add_u64 v[54:55], s[26:27], 0, v[50:51]
	v_cvt_pk_bf16_f32 v4, v4, v5
	v_cvt_pk_bf16_f32 v5, v6, v7
	v_lshl_add_u64 v[6:7], v[54:55], 0, v[180:181]
	global_store_dwordx2 v[6:7], v[4:5], off nt
	v_lshl_add_u32 v4, v60, 4, v124
	ds_read_b128 v[4:7], v4 offset:40960
	ds_read_b128 v[8:11], v61 offset:46080
	v_pk_mul_f32 v[70:71], v[48:49], v[68:69] op_sel_hi:[1,0]
	v_pk_mul_f32 v[72:73], v[46:47], v[68:69] op_sel_hi:[1,0]
	v_lshl_add_u32 v46, v58, 4, v124
	ds_read_b128 v[46:49], v46 offset:40960
	s_waitcnt lgkmcnt(1)
	v_pk_fma_f32 v[6:7], v[6:7], v[72:73], v[10:11]
	v_pk_fma_f32 v[4:5], v[4:5], v[70:71], v[8:9]
	v_cvt_pk_bf16_f32 v9, v6, v7
	v_cvt_pk_bf16_f32 v8, v4, v5
	ds_read_b128 v[4:7], v61 offset:47104
	v_lshl_add_u32 v50, v62, 4, v124
	v_lshl_add_u64 v[10:11], v[64:65], 3, v[54:55]
	ds_read_b128 v[50:53], v50 offset:40960
	global_store_dwordx2 v[10:11], v[8:9], off nt
	ds_read_b128 v[8:11], v61 offset:48128
	v_pk_mul_f32 v[42:43], v[42:43], v[68:69] op_sel_hi:[1,0]
	v_pk_mul_f32 v[44:45], v[44:45], v[68:69] op_sel_hi:[1,0]
	s_waitcnt lgkmcnt(2)
	v_pk_fma_f32 v[4:5], v[46:47], v[42:43], v[4:5]
	v_pk_fma_f32 v[6:7], v[48:49], v[44:45], v[6:7]
	v_cvt_pk_bf16_f32 v4, v4, v5
	v_cvt_pk_bf16_f32 v5, v6, v7
	v_lshl_add_u64 v[6:7], v[58:59], 3, v[54:55]
	global_store_dwordx2 v[6:7], v[4:5], off nt
	v_pk_mul_f32 v[4:5], v[38:39], v[68:69] op_sel_hi:[1,0]
	v_pk_mul_f32 v[6:7], v[40:41], v[68:69] op_sel_hi:[1,0]
	s_waitcnt lgkmcnt(0)
	v_pk_fma_f32 v[4:5], v[4:5], v[50:51], v[8:9]
	v_pk_fma_f32 v[6:7], v[6:7], v[52:53], v[10:11]
	v_cvt_pk_bf16_f32 v4, v4, v5
	v_cvt_pk_bf16_f32 v5, v6, v7
	v_lshl_add_u64 v[6:7], v[62:63], 3, v[54:55]
	global_store_dwordx2 v[6:7], v[4:5], off nt
